# rstd via v_rsq_f32 also in P0 x-norm, K finalize and final norm loops (serial IEEE sqrt+div chains removed), result placed in a chain temp
# baseline (speedup 1.0000x reference)
; __device__ __forceinline__ float sq4(f32x4 a) { return (a.x * a.x + a.y * a.y) + (a.z * a.z + a.w * a.w); }
; __device__ __forceinline__ u32x4 pack8(f32x4 a, f32x4 b) { u32x4 o; o.x = cvt_pk(a.x, a.y); o.y = cvt_pk(a.z, a.w); o.z = cvt_pk(b.x, b.y); o.w = cvt_pk(b.z, b.w); return o; }
; __device__ __forceinline__ void p0_prologue(const Params& p, LAS unsigned char* lds, int G) {
;     ...
;     for (int m = gw; m < M; m += 4 * NGW) {
;         f32x4 a0[4], a1[4], b0[4], b1[4];
; #pragma unroll
;         for (int k = 0; k < 4; ++k) { const int mm = (m + k * NGW < M) ? m + k * NGW : m; const f32x4* s4 = (const f32x4*)(p.in[0] + (size_t)mm * D);
;             a0[k] = s4[2 * lane]; a1[k] = s4[2 * lane + 1]; b0[k] = s4[128 + 2 * lane]; b1[k] = s4[129 + 2 * lane]; }
; #pragma unroll
;         for (int k = 0; k < 4; ++k) { const int mm = m + k * NGW; if (mm < M) {
;             const float ss = wave_sum((sq4(a0[k]) + sq4(a1[k])) + (sq4(b0[k]) + sq4(b1[k])));
;             const float r = 1.0f / sqrtf(ss * (1.f / 1024.f) + EPS);
;             bf16_t* dst = (bf16_t*)(ws + WS_XN) + (size_t)mm * D;
;             *(u32x4*)(dst + 8 * lane) = pack8(a0[k] * r, a1[k] * r); *(u32x4*)(dst + 512 + 8 * lane) = pack8(b0[k] * r, b1[k] * r); } }
;     }
.LBB0_21:
	v_ashrrev_i32_e32 v59, 31, v58
	s_waitcnt vmcnt(3)
	v_lshlrev_b64 v[0:1], 12, v[58:59]
	v_lshl_add_u64 v[0:1], v[48:49], 0, v[0:1]
	global_load_dwordx4 v[72:75], v[0:1], off offset:2048
	global_load_dwordx4 v[76:79], v[0:1], off
	global_load_dwordx4 v[84:87], v[0:1], off offset:2064
	global_load_dwordx4 v[88:91], v[0:1], off offset:16
	v_add_u32_e32 v52, s33, v58
	v_cmp_gt_i32_e64 s[6:7], s34, v52
	v_add_u32_e32 v56, s35, v58
	v_add_u32_e32 v54, s38, v58
	v_cndmask_b32_e64 v0, v58, v52, s[6:7]
	v_ashrrev_i32_e32 v1, 31, v0
	v_lshlrev_b64 v[0:1], 12, v[0:1]
	v_lshl_add_u64 v[0:1], v[48:49], 0, v[0:1]
	global_load_dwordx4 v[36:39], v[0:1], off offset:16
	global_load_dwordx4 v[44:47], v[0:1], off
	global_load_dwordx4 v[32:35], v[0:1], off offset:2064
	global_load_dwordx4 v[40:43], v[0:1], off offset:2048
	v_cmp_gt_i32_e64 s[4:5], s34, v56
	v_cmp_gt_i32_e64 s[0:1], s34, v54
	s_waitcnt vmcnt(7)
	v_mov_b32_e32 v6, v73
	s_waitcnt vmcnt(6)
	v_mov_b32_e32 v7, v77
	v_mov_b32_e32 v10, v75
	v_mov_b32_e32 v11, v79
	s_waitcnt vmcnt(5)
	v_mov_b32_e32 v14, v85
	s_waitcnt vmcnt(4)
	v_mov_b32_e32 v15, v89
	v_mov_b32_e32 v18, v87
	v_mov_b32_e32 v19, v91
	v_mov_b32_e32 v0, v72
	v_mov_b32_e32 v1, v76
	v_mov_b32_e32 v8, v74
	v_mov_b32_e32 v9, v78
	v_mov_b32_e32 v12, v84
	v_mov_b32_e32 v13, v88
	v_mov_b32_e32 v16, v86
	v_mov_b32_e32 v17, v90
	v_pk_mul_f32 v[6:7], v[6:7], v[6:7]
	v_pk_mul_f32 v[10:11], v[10:11], v[10:11]
	v_pk_mul_f32 v[14:15], v[14:15], v[14:15]
	v_pk_mul_f32 v[18:19], v[18:19], v[18:19]
	v_pk_fma_f32 v[0:1], v[0:1], v[0:1], v[6:7]
	v_pk_fma_f32 v[6:7], v[8:9], v[8:9], v[10:11]
	v_pk_fma_f32 v[8:9], v[12:13], v[12:13], v[14:15]
	v_pk_fma_f32 v[10:11], v[16:17], v[16:17], v[18:19]
	v_pk_add_f32 v[0:1], v[0:1], v[6:7]
	v_pk_add_f32 v[6:7], v[8:9], v[10:11]
	v_cndmask_b32_e64 v2, v58, v56, s[4:5]
	v_pk_add_f32 v[0:1], v[6:7], v[0:1]
	v_cndmask_b32_e64 v4, v58, v54, s[0:1]
	v_add_f32_e32 v0, v0, v1
	ds_bpermute_b32 v1, v63, v0
	v_ashrrev_i32_e32 v3, 31, v2
	v_ashrrev_i32_e32 v5, 31, v4
	v_lshlrev_b64 v[2:3], 12, v[2:3]
	v_lshlrev_b64 v[4:5], 12, v[4:5]
	v_lshl_add_u64 v[2:3], v[48:49], 0, v[2:3]
	v_lshl_add_u64 v[4:5], v[48:49], 0, v[4:5]
	global_load_dwordx4 v[16:19], v[2:3], off offset:16
	global_load_dwordx4 v[20:23], v[2:3], off
	global_load_dwordx4 v[24:27], v[2:3], off offset:2064
	global_load_dwordx4 v[28:31], v[2:3], off offset:2048
	s_waitcnt lgkmcnt(0)
	v_add_f32_e32 v53, v0, v1
	global_load_dwordx4 v[8:11], v[4:5], off offset:16
	global_load_dwordx4 v[12:15], v[4:5], off
	global_load_dwordx4 v[0:3], v[4:5], off offset:2064
	s_nop 0
	global_load_dwordx4 v[4:7], v[4:5], off offset:2048
	ds_bpermute_b32 v55, v64, v53
	v_lshlrev_b64 v[58:59], 11, v[58:59]
	v_lshl_add_u64 v[58:59], v[50:51], 0, v[58:59]
	s_waitcnt lgkmcnt(0)
	v_add_f32_e32 v53, v53, v55
	ds_bpermute_b32 v55, v65, v53
	s_waitcnt lgkmcnt(0)
	v_add_f32_e32 v53, v53, v55
	ds_bpermute_b32 v55, v66, v53
	s_waitcnt lgkmcnt(0)
	v_add_f32_e32 v53, v53, v55
	ds_bpermute_b32 v55, v67, v53
	s_waitcnt lgkmcnt(0)
	v_add_f32_e32 v53, v53, v55
	ds_bpermute_b32 v55, v68, v53
	s_waitcnt lgkmcnt(0)
	v_add_f32_e32 v53, v53, v55
	v_fmamk_f32 v53, v53, 0x3a800000, v69
	v_rsq_f32_e32 v55, v53
	s_nop 0
	v_mov_b32_e32 v80, v55
	v_pk_mul_f32 v[78:79], v[78:79], v[80:81] op_sel_hi:[1,0]
	v_pk_mul_f32 v[76:77], v[76:77], v[80:81] op_sel_hi:[1,0]
	v_pk_mul_f32 v[90:91], v[90:91], v[80:81] op_sel_hi:[1,0]
	v_pk_mul_f32 v[88:89], v[88:89], v[80:81] op_sel_hi:[1,0]
	v_pk_mul_f32 v[92:93], v[74:75], v[80:81] op_sel_hi:[1,0]
	v_pk_mul_f32 v[94:95], v[72:73], v[80:81] op_sel_hi:[1,0]
	v_cvt_pk_bf16_f32 v72, v76, v77
	v_cvt_pk_bf16_f32 v73, v78, v79
	v_cvt_pk_bf16_f32 v74, v88, v89
	v_cvt_pk_bf16_f32 v75, v90, v91
	v_pk_mul_f32 v[86:87], v[86:87], v[80:81] op_sel_hi:[1,0]
	v_pk_mul_f32 v[80:81], v[84:85], v[80:81] op_sel_hi:[1,0]
	global_store_dwordx4 v[58:59], v[72:75], off
	s_nop 1
	v_cvt_pk_bf16_f32 v72, v94, v95
	v_cvt_pk_bf16_f32 v73, v92, v93
	v_cvt_pk_bf16_f32 v74, v80, v81
	v_cvt_pk_bf16_f32 v75, v86, v87
	global_store_dwordx4 v[58:59], v[72:75], off offset:1024
	s_and_saveexec_b64 s[8:9], s[6:7]
	s_cbranch_execz .LBB0_24
	s_waitcnt vmcnt(12)
	v_mov_b32_e32 v72, v45
	s_waitcnt vmcnt(10)
	v_mov_b32_e32 v73, v41
	v_mov_b32_e32 v58, v44
	v_mov_b32_e32 v59, v40
	v_pk_mul_f32 v[72:73], v[72:73], v[72:73]
	v_mov_b32_e32 v74, v47
	v_mov_b32_e32 v75, v43
	v_pk_fma_f32 v[58:59], v[58:59], v[58:59], v[72:73]
	v_mov_b32_e32 v72, v46
	v_mov_b32_e32 v73, v42
	v_pk_mul_f32 v[74:75], v[74:75], v[74:75]
	v_mov_b32_e32 v76, v39
	v_pk_fma_f32 v[72:73], v[72:73], v[72:73], v[74:75]
	v_mov_b32_e32 v74, v37
	v_mov_b32_e32 v75, v33
	v_pk_add_f32 v[58:59], v[58:59], v[72:73]
	v_mov_b32_e32 v72, v36
	v_mov_b32_e32 v73, v32
	v_pk_mul_f32 v[74:75], v[74:75], v[74:75]
	v_mov_b32_e32 v77, v35
	v_pk_fma_f32 v[72:73], v[72:73], v[72:73], v[74:75]
	v_mov_b32_e32 v74, v38
	v_mov_b32_e32 v75, v34
	v_pk_mul_f32 v[76:77], v[76:77], v[76:77]
	s_nop 0
	v_pk_fma_f32 v[74:75], v[74:75], v[74:75], v[76:77]
	s_nop 0
	v_pk_add_f32 v[72:73], v[72:73], v[74:75]
	s_nop 0
	v_pk_add_f32 v[58:59], v[58:59], v[72:73]
	s_nop 0
	v_add_f32_e32 v53, v58, v59
	ds_bpermute_b32 v55, v63, v53
	s_waitcnt lgkmcnt(0)
	v_add_f32_e32 v53, v53, v55
	ds_bpermute_b32 v55, v64, v53
	s_waitcnt lgkmcnt(0)
	v_add_f32_e32 v53, v53, v55
	ds_bpermute_b32 v55, v65, v53
	s_waitcnt lgkmcnt(0)
	v_add_f32_e32 v53, v53, v55
	ds_bpermute_b32 v55, v66, v53
	s_waitcnt lgkmcnt(0)
	v_add_f32_e32 v53, v53, v55
	ds_bpermute_b32 v55, v67, v53
	s_waitcnt lgkmcnt(0)
	v_add_f32_e32 v53, v53, v55
	ds_bpermute_b32 v55, v68, v53
	s_waitcnt lgkmcnt(0)
	v_add_f32_e32 v53, v53, v55
	v_fmamk_f32 v53, v53, 0x3a800000, v69
	v_rsq_f32_e32 v55, v53
	s_nop 0
	v_mov_b32_e32 v58, v55
	v_ashrrev_i32_e32 v53, 31, v52
	v_lshlrev_b64 v[72:73], 11, v[52:53]
	v_pk_mul_f32 v[44:45], v[44:45], v[58:59] op_sel_hi:[1,0]
	v_pk_mul_f32 v[74:75], v[38:39], v[58:59] op_sel_hi:[1,0]
	v_pk_mul_f32 v[38:39], v[36:37], v[58:59] op_sel_hi:[1,0]
	v_pk_mul_f32 v[46:47], v[46:47], v[58:59] op_sel_hi:[1,0]
	v_cvt_pk_bf16_f32 v36, v44, v45
	v_lshl_add_u64 v[44:45], v[50:51], 0, v[72:73]
	v_cvt_pk_bf16_f32 v37, v46, v47
	v_cvt_pk_bf16_f32 v38, v38, v39
	v_cvt_pk_bf16_f32 v39, v74, v75
	global_store_dwordx4 v[44:45], v[36:39], off
	s_nop 1
	v_pk_mul_f32 v[38:39], v[40:41], v[58:59] op_sel_hi:[1,0]
	v_pk_mul_f32 v[40:41], v[34:35], v[58:59] op_sel_hi:[1,0]
	v_pk_mul_f32 v[34:35], v[32:33], v[58:59] op_sel_hi:[1,0]
	v_pk_mul_f32 v[36:37], v[42:43], v[58:59] op_sel_hi:[1,0]
	v_cvt_pk_bf16_f32 v32, v38, v39
	s_nop 0
	v_cvt_pk_bf16_f32 v33, v36, v37
	v_cvt_pk_bf16_f32 v34, v34, v35
	v_cvt_pk_bf16_f32 v35, v40, v41
	global_store_dwordx4 v[44:45], v[32:35], off offset:1024
	s_or_b64 exec, exec, s[8:9]
	s_and_saveexec_b64 s[6:7], s[4:5]
	s_cbranch_execnz .LBB0_25

; __device__ __forceinline__ float sq4(f32x4 a) { return (a.x * a.x + a.y * a.y) + (a.z * a.z + a.w * a.w); }
; __device__ __forceinline__ u32x4 pack8(f32x4 a, f32x4 b) { u32x4 o; o.x = cvt_pk(a.x, a.y); o.y = cvt_pk(a.z, a.w); o.z = cvt_pk(b.x, b.y); o.w = cvt_pk(b.z, b.w); return o; }
; __device__ __forceinline__ void p0_prologue(const Params& p, LAS unsigned char* lds, int G) {
;     ...
;     for (int m = gw; m < M; m += 4 * NGW) {
;         f32x4 a0[4], a1[4], b0[4], b1[4];
; #pragma unroll
;         for (int k = 0; k < 4; ++k) { const int mm = (m + k * NGW < M) ? m + k * NGW : m; const f32x4* s4 = (const f32x4*)(p.in[0] + (size_t)mm * D);
;             a0[k] = s4[2 * lane]; a1[k] = s4[2 * lane + 1]; b0[k] = s4[128 + 2 * lane]; b1[k] = s4[129 + 2 * lane]; }
; #pragma unroll
;         for (int k = 0; k < 4; ++k) { const int mm = m + k * NGW; if (mm < M) {
;             const float ss = wave_sum((sq4(a0[k]) + sq4(a1[k])) + (sq4(b0[k]) + sq4(b1[k])));
;             const float r = 1.0f / sqrtf(ss * (1.f / 1024.f) + EPS);
;             bf16_t* dst = (bf16_t*)(ws + WS_XN) + (size_t)mm * D;
;             *(u32x4*)(dst + 8 * lane) = pack8(a0[k] * r, a1[k] * r); *(u32x4*)(dst + 512 + 8 * lane) = pack8(b0[k] * r, b1[k] * r); } }
;     }
.LBB0_25:
	s_waitcnt vmcnt(8)
	v_mov_b32_e32 v34, v21
	s_waitcnt vmcnt(6)
	v_mov_b32_e32 v35, v29
	v_mov_b32_e32 v32, v20
	v_mov_b32_e32 v33, v28
	v_pk_mul_f32 v[34:35], v[34:35], v[34:35]
	v_mov_b32_e32 v36, v23
	v_mov_b32_e32 v37, v31
	v_pk_fma_f32 v[32:33], v[32:33], v[32:33], v[34:35]
	v_mov_b32_e32 v34, v22
	v_mov_b32_e32 v35, v30
	v_pk_mul_f32 v[36:37], v[36:37], v[36:37]
	v_mov_b32_e32 v38, v19
	v_pk_fma_f32 v[34:35], v[34:35], v[34:35], v[36:37]
	v_mov_b32_e32 v36, v17
	v_mov_b32_e32 v37, v25
	v_pk_add_f32 v[32:33], v[32:33], v[34:35]
	v_mov_b32_e32 v34, v16
	v_mov_b32_e32 v35, v24
	v_pk_mul_f32 v[36:37], v[36:37], v[36:37]
	v_mov_b32_e32 v39, v27
	v_pk_fma_f32 v[34:35], v[34:35], v[34:35], v[36:37]
	v_mov_b32_e32 v36, v18
	v_mov_b32_e32 v37, v26
	v_pk_mul_f32 v[38:39], v[38:39], v[38:39]
	v_ashrrev_i32_e32 v57, 31, v56
	v_pk_fma_f32 v[36:37], v[36:37], v[36:37], v[38:39]
	s_nop 0
	v_pk_add_f32 v[34:35], v[34:35], v[36:37]
	s_nop 0
	v_pk_add_f32 v[32:33], v[32:33], v[34:35]
	s_nop 0
	v_add_f32_e32 v32, v32, v33
	ds_bpermute_b32 v33, v63, v32
	s_waitcnt lgkmcnt(0)
	v_add_f32_e32 v32, v32, v33
	ds_bpermute_b32 v33, v64, v32
	s_waitcnt lgkmcnt(0)
	v_add_f32_e32 v32, v32, v33
	ds_bpermute_b32 v33, v65, v32
	s_waitcnt lgkmcnt(0)
	v_add_f32_e32 v32, v32, v33
	ds_bpermute_b32 v33, v66, v32
	s_waitcnt lgkmcnt(0)
	v_add_f32_e32 v32, v32, v33
	ds_bpermute_b32 v33, v67, v32
	s_waitcnt lgkmcnt(0)
	v_add_f32_e32 v32, v32, v33
	ds_bpermute_b32 v33, v68, v32
	s_waitcnt lgkmcnt(0)
	v_add_f32_e32 v32, v32, v33
	v_fmamk_f32 v32, v32, 0x3a800000, v69
	v_rsq_f32_e32 v33, v32
	s_nop 0
	v_mov_b32_e32 v32, v33
	v_lshlrev_b64 v[34:35], 11, v[56:57]
	v_pk_mul_f32 v[20:21], v[20:21], v[32:33] op_sel_hi:[1,0]
	v_pk_mul_f32 v[36:37], v[18:19], v[32:33] op_sel_hi:[1,0]
	v_pk_mul_f32 v[18:19], v[16:17], v[32:33] op_sel_hi:[1,0]
	v_pk_mul_f32 v[22:23], v[22:23], v[32:33] op_sel_hi:[1,0]
	v_cvt_pk_bf16_f32 v16, v20, v21
	v_lshl_add_u64 v[20:21], v[50:51], 0, v[34:35]
	v_cvt_pk_bf16_f32 v17, v22, v23
	v_cvt_pk_bf16_f32 v18, v18, v19
	v_cvt_pk_bf16_f32 v19, v36, v37
	global_store_dwordx4 v[20:21], v[16:19], off
	v_pk_mul_f32 v[22:23], v[26:27], v[32:33] op_sel_hi:[1,0]
	v_pk_mul_f32 v[24:25], v[24:25], v[32:33] op_sel_hi:[1,0]
	v_pk_mul_f32 v[18:19], v[30:31], v[32:33] op_sel_hi:[1,0]
	v_pk_mul_f32 v[16:17], v[28:29], v[32:33] op_sel_hi:[1,0]
	s_nop 0
	v_cvt_pk_bf16_f32 v16, v16, v17
	v_cvt_pk_bf16_f32 v17, v18, v19
	v_cvt_pk_bf16_f32 v18, v24, v25
	v_cvt_pk_bf16_f32 v19, v22, v23
	global_store_dwordx4 v[20:21], v[16:19], off offset:1024
	s_or_b64 exec, exec, s[6:7]
	s_and_saveexec_b64 s[4:5], s[0:1]
	s_cbranch_execz .LBB0_20
.LBB0_26:
	s_waitcnt vmcnt(4)
	v_mov_b32_e32 v18, v13
	s_waitcnt vmcnt(2)
	v_mov_b32_e32 v19, v5
	v_mov_b32_e32 v16, v12
	v_mov_b32_e32 v17, v4
	v_pk_mul_f32 v[18:19], v[18:19], v[18:19]
	v_mov_b32_e32 v20, v15
	v_mov_b32_e32 v21, v7
	v_pk_fma_f32 v[16:17], v[16:17], v[16:17], v[18:19]
	v_mov_b32_e32 v18, v14
	v_mov_b32_e32 v19, v6
	v_pk_mul_f32 v[20:21], v[20:21], v[20:21]
	v_mov_b32_e32 v22, v11
	v_pk_fma_f32 v[18:19], v[18:19], v[18:19], v[20:21]
	v_mov_b32_e32 v20, v9
	v_mov_b32_e32 v21, v1
	v_pk_add_f32 v[16:17], v[16:17], v[18:19]
	v_mov_b32_e32 v18, v8
	v_mov_b32_e32 v19, v0
	v_pk_mul_f32 v[20:21], v[20:21], v[20:21]
	v_mov_b32_e32 v23, v3
	v_pk_fma_f32 v[18:19], v[18:19], v[18:19], v[20:21]
	v_mov_b32_e32 v20, v10
	v_mov_b32_e32 v21, v2
	v_pk_mul_f32 v[22:23], v[22:23], v[22:23]
	v_ashrrev_i32_e32 v55, 31, v54
	v_pk_fma_f32 v[20:21], v[20:21], v[20:21], v[22:23]
	s_nop 0
	v_pk_add_f32 v[18:19], v[18:19], v[20:21]
	s_nop 0
	v_pk_add_f32 v[16:17], v[16:17], v[18:19]
	s_nop 0
	v_add_f32_e32 v16, v16, v17
	ds_bpermute_b32 v17, v63, v16
	s_waitcnt lgkmcnt(0)
	v_add_f32_e32 v16, v16, v17
	ds_bpermute_b32 v17, v64, v16
	s_waitcnt lgkmcnt(0)
	v_add_f32_e32 v16, v16, v17
	ds_bpermute_b32 v17, v65, v16
	s_waitcnt lgkmcnt(0)
	v_add_f32_e32 v16, v16, v17
	ds_bpermute_b32 v17, v66, v16
	s_waitcnt lgkmcnt(0)
	v_add_f32_e32 v16, v16, v17
	ds_bpermute_b32 v17, v67, v16
	s_waitcnt lgkmcnt(0)
	v_add_f32_e32 v16, v16, v17
	ds_bpermute_b32 v17, v68, v16
	s_waitcnt lgkmcnt(0)
	v_add_f32_e32 v16, v16, v17
	v_fmamk_f32 v16, v16, 0x3a800000, v69
	v_rsq_f32_e32 v17, v16
	s_nop 0
	v_mov_b32_e32 v16, v17
	v_lshlrev_b64 v[18:19], 11, v[54:55]
	v_pk_mul_f32 v[12:13], v[12:13], v[16:17] op_sel_hi:[1,0]
	v_pk_mul_f32 v[14:15], v[14:15], v[16:17] op_sel_hi:[1,0]
	v_pk_mul_f32 v[20:21], v[10:11], v[16:17] op_sel_hi:[1,0]
	v_pk_mul_f32 v[10:11], v[8:9], v[16:17] op_sel_hi:[1,0]
	v_cvt_pk_bf16_f32 v8, v12, v13
	v_cvt_pk_bf16_f32 v9, v14, v15
	v_lshl_add_u64 v[12:13], v[50:51], 0, v[18:19]
	v_cvt_pk_bf16_f32 v10, v10, v11
	v_cvt_pk_bf16_f32 v11, v20, v21
	global_store_dwordx4 v[12:13], v[8:11], off
	v_pk_mul_f32 v[6:7], v[6:7], v[16:17] op_sel_hi:[1,0]
	v_pk_mul_f32 v[4:5], v[4:5], v[16:17] op_sel_hi:[1,0]
	v_pk_mul_f32 v[8:9], v[2:3], v[16:17] op_sel_hi:[1,0]
	v_pk_mul_f32 v[2:3], v[0:1], v[16:17] op_sel_hi:[1,0]
	v_cvt_pk_bf16_f32 v0, v4, v5
	v_cvt_pk_bf16_f32 v1, v6, v7
	s_nop 0
	v_cvt_pk_bf16_f32 v2, v2, v3
	v_cvt_pk_bf16_f32 v3, v8, v9
	global_store_dwordx4 v[12:13], v[0:3], off offset:1024
	s_branch .LBB0_20

; __device__ __forceinline__ float sq4(f32x4 a) { return (a.x * a.x + a.y * a.y) + (a.z * a.z + a.w * a.w); }
; __device__ __forceinline__ u32x4 pack8(f32x4 a, f32x4 b) { u32x4 o; o.x = cvt_pk(a.x, a.y); o.y = cvt_pk(a.z, a.w); o.z = cvt_pk(b.x, b.y); o.w = cvt_pk(b.z, b.w); return o; }
; __device__ __forceinline__ float rstd_of(const float* SS, int row, float invw) { return 1.0f / sqrtf(SS[row] * invw + EPS); }
;     __device__ __forceinline__ void operator()(const f32x4 (&acc)[2][2][4][2], const pg8::Unit& u, int wr, int wc, int fr, int fq) const {
;     ...
;         } else {
; #pragma unroll
;             for (int ai = 0; ai < 2; ++ai)
; #pragma unroll
;                 for (int m = 0; m < 4; ++m) {
;                     const int row = row0 + ai * 128 + m * 16; const float r = rstd_of(SS1, row, 1.f / 1024.f);
;                     const f32x4 a = acc[ai][0][m][0] * r, b = acc[ai][0][m][1] * r;
;                     *(u32x4*)(CKV + (size_t)row * 128 + colw) = pack8(a, b);
;                     row_stat_add(SSKV, row, sq4(a) + sq4(b), fq);
;                     if (wc == 0) { float* d = KR + (size_t)row * 32 + 8 * fq; *(f32x4*)d = acc[ai][1][m][0] * r; *(f32x4*)(d + 4) = acc[ai][1][m][1] * r; }
;                 }
.LBB0_348:
	v_lshl_add_u32 v152, s0, 8, v167
	s_mov_b64 s[0:1], -1
	s_cmp_gt_i32 s58, 3
	v_ashrrev_i32_e32 v153, 31, v152
	s_cbranch_scc0 .LBB0_403
	v_lshl_add_u64 v[154:155], v[152:153], 2, s[48:49]
	global_load_dword v156, v[154:155], off
	global_load_dword v200, v[154:155], off offset:64
	global_load_dword v201, v[154:155], off offset:128
	global_load_dword v202, v[154:155], off offset:192
	global_load_dword v203, v[154:155], off offset:512
	global_load_dword v204, v[154:155], off offset:576
	global_load_dword v205, v[154:155], off offset:640
	global_load_dword v206, v[154:155], off offset:704
	s_cmp_eq_u32 s58, 4
	s_waitcnt vmcnt(0)
	v_fmamk_f32 v156, v156, 0x3a800000, v172
	v_rsq_f32_e32 v157, v156
	s_nop 0
	s_mov_b64 s[0:1], -1
	v_mov_b32_e32 v156, v157
	v_mov_b32_e32 v157, v156
	v_pk_mul_f32 v[160:161], v[124:125], v[156:157]
	v_pk_mul_f32 v[158:159], v[120:121], v[156:157]
	s_cbranch_scc1 .LBB0_383
	v_mov_b32_e32 v162, v156
	v_mov_b32_e32 v163, v156
	v_pk_mul_f32 v[164:165], v[126:127], v[162:163]
	v_pk_mul_f32 v[182:183], v[122:123], v[162:163]
	v_mul_f32_e32 v162, v161, v161
	v_mul_f32_e32 v163, v165, v165
	v_fmac_f32_e32 v162, v160, v160
	v_fmac_f32_e32 v163, v164, v164
	v_add_f32_e32 v162, v162, v163
	v_mul_f32_e32 v163, v159, v159
	v_mul_f32_e32 v175, v183, v183
	v_fmac_f32_e32 v163, v158, v158
	v_fmac_f32_e32 v175, v182, v182
	v_add_f32_e32 v163, v163, v175
	v_and_b32_e32 v175, 64, v174
	v_add_f32_e32 v162, v162, v163
	v_xor_b32_e32 v163, 16, v174
	v_add_u32_e32 v176, 64, v175
	v_cmp_lt_i32_e32 vcc, v163, v176
	v_cvt_pk_bf16_f32 v178, v160, v161
	v_cvt_pk_bf16_f32 v179, v164, v165
	v_lshlrev_b64 v[164:165], 8, v[152:153]
	v_lshl_add_u64 v[164:165], v[138:139], 0, v[164:165]
	v_cndmask_b32_e32 v163, v174, v163, vcc
	v_lshlrev_b32_e32 v175, 2, v163
	ds_bpermute_b32 v163, v175, v162
	v_cvt_pk_bf16_f32 v180, v158, v159
	v_cvt_pk_bf16_f32 v181, v182, v183
	global_store_dwordx4 v[164:165], v[178:181], off
	s_waitcnt lgkmcnt(0)
	v_add_f32_e32 v162, v162, v163
	v_xor_b32_e32 v163, 32, v174
	v_cmp_lt_i32_e32 vcc, v163, v176
	s_nop 1
	v_cndmask_b32_e32 v163, v174, v163, vcc
	v_lshlrev_b32_e32 v176, 2, v163
	ds_bpermute_b32 v163, v176, v162
	s_and_saveexec_b64 s[0:1], s[38:39]
	s_cbranch_execz .LBB0_352
	v_lshl_add_u64 v[164:165], v[152:153], 2, s[44:45]
	s_waitcnt lgkmcnt(0)
	v_add_f32_e32 v162, v162, v163
	global_atomic_add_f32 v[164:165], v162, off

; __device__ __forceinline__ float sq4(f32x4 a) { return (a.x * a.x + a.y * a.y) + (a.z * a.z + a.w * a.w); }
; __device__ __forceinline__ u32x4 pack8(f32x4 a, f32x4 b) { u32x4 o; o.x = cvt_pk(a.x, a.y); o.y = cvt_pk(a.z, a.w); o.z = cvt_pk(b.x, b.y); o.w = cvt_pk(b.z, b.w); return o; }
; __device__ __forceinline__ float rstd_of(const float* SS, int row, float invw) { return 1.0f / sqrtf(SS[row] * invw + EPS); }
;     __device__ __forceinline__ void operator()(const f32x4 (&acc)[2][2][4][2], const pg8::Unit& u, int wr, int wc, int fr, int fq) const {
;     ...
;         } else {
; #pragma unroll
;             for (int ai = 0; ai < 2; ++ai)
; #pragma unroll
;                 for (int m = 0; m < 4; ++m) {
;                     const int row = row0 + ai * 128 + m * 16; const float r = rstd_of(SS1, row, 1.f / 1024.f);
;                     const f32x4 a = acc[ai][0][m][0] * r, b = acc[ai][0][m][1] * r;
;                     *(u32x4*)(CKV + (size_t)row * 128 + colw) = pack8(a, b);
;                     row_stat_add(SSKV, row, sq4(a) + sq4(b), fq);
;                     if (wc == 0) { float* d = KR + (size_t)row * 32 + 8 * fq; *(f32x4*)d = acc[ai][1][m][0] * r; *(f32x4*)(d + 4) = acc[ai][1][m][1] * r; }
;                 }
.LBB0_354:
	s_nop 1
	v_or_b32_e32 v162, 16, v152
	s_waitcnt lgkmcnt(0)
	v_ashrrev_i32_e32 v163, 31, v162
	v_lshl_add_u64 v[164:165], v[162:163], 2, s[48:49]
	s_nop 1
	v_mov_b32_e32 v164, v200
	v_fmamk_f32 v164, v164, 0x3a800000, v172
	v_rsq_f32_e32 v165, v164
	s_nop 0
	v_mov_b32_e32 v164, v165
	v_pk_mul_f32 v[180:181], v[110:111], v[164:165] op_sel_hi:[1,0]
	v_pk_mul_f32 v[178:179], v[108:109], v[164:165] op_sel_hi:[1,0]
	v_pk_mul_f32 v[182:183], v[106:107], v[164:165] op_sel_hi:[1,0]
	v_pk_mul_f32 v[184:185], v[104:105], v[164:165] op_sel_hi:[1,0]
	v_mul_f32_e32 v165, v179, v179
	v_mul_f32_e32 v177, v181, v181
	v_mul_f32_e32 v186, v185, v185
	v_mul_f32_e32 v187, v183, v183
	v_fmac_f32_e32 v165, v178, v178
	v_fmac_f32_e32 v177, v180, v180
	v_fmac_f32_e32 v186, v184, v184
	v_fmac_f32_e32 v187, v182, v182
	v_add_f32_e32 v165, v165, v177
	v_add_f32_e32 v177, v186, v187
	v_add_f32_e32 v165, v165, v177
	ds_bpermute_b32 v177, v175, v165
	v_cvt_pk_bf16_f32 v178, v178, v179
	v_cvt_pk_bf16_f32 v179, v180, v181
	v_cvt_pk_bf16_f32 v180, v184, v185
	v_cvt_pk_bf16_f32 v181, v182, v183
	s_waitcnt lgkmcnt(0)
	v_add_f32_e32 v165, v165, v177
	ds_bpermute_b32 v177, v176, v165
	v_lshlrev_b64 v[182:183], 8, v[162:163]
	v_lshl_add_u64 v[182:183], v[138:139], 0, v[182:183]
	global_store_dwordx4 v[182:183], v[178:181], off
	s_and_saveexec_b64 s[0:1], s[38:39]
	s_cbranch_execz .LBB0_356
	v_lshl_add_u64 v[178:179], v[162:163], 2, s[44:45]
	s_waitcnt lgkmcnt(0)
	v_add_f32_e32 v165, v165, v177
	global_atomic_add_f32 v[178:179], v165, off

; __device__ __forceinline__ float sq4(f32x4 a) { return (a.x * a.x + a.y * a.y) + (a.z * a.z + a.w * a.w); }
; __device__ __forceinline__ u32x4 pack8(f32x4 a, f32x4 b) { u32x4 o; o.x = cvt_pk(a.x, a.y); o.y = cvt_pk(a.z, a.w); o.z = cvt_pk(b.x, b.y); o.w = cvt_pk(b.z, b.w); return o; }
; __device__ __forceinline__ float rstd_of(const float* SS, int row, float invw) { return 1.0f / sqrtf(SS[row] * invw + EPS); }
;     __device__ __forceinline__ void operator()(const f32x4 (&acc)[2][2][4][2], const pg8::Unit& u, int wr, int wc, int fr, int fq) const {
;     ...
;         } else {
; #pragma unroll
;             for (int ai = 0; ai < 2; ++ai)
; #pragma unroll
;                 for (int m = 0; m < 4; ++m) {
;                     const int row = row0 + ai * 128 + m * 16; const float r = rstd_of(SS1, row, 1.f / 1024.f);
;                     const f32x4 a = acc[ai][0][m][0] * r, b = acc[ai][0][m][1] * r;
;                     *(u32x4*)(CKV + (size_t)row * 128 + colw) = pack8(a, b);
;                     row_stat_add(SSKV, row, sq4(a) + sq4(b), fq);
;                     if (wc == 0) { float* d = KR + (size_t)row * 32 + 8 * fq; *(f32x4*)d = acc[ai][1][m][0] * r; *(f32x4*)(d + 4) = acc[ai][1][m][1] * r; }
;                 }
.LBB0_358:
	v_or_b32_e32 v162, 32, v152
	v_ashrrev_i32_e32 v163, 31, v162
	v_lshl_add_u64 v[164:165], v[162:163], 2, s[48:49]
	s_nop 1
	v_mov_b32_e32 v164, v201
	v_fmamk_f32 v164, v164, 0x3a800000, v172
	v_rsq_f32_e32 v165, v164
	s_nop 0
	s_waitcnt lgkmcnt(0)
	v_mov_b32_e32 v164, v165
	v_pk_mul_f32 v[180:181], v[94:95], v[164:165] op_sel_hi:[1,0]
	v_pk_mul_f32 v[178:179], v[92:93], v[164:165] op_sel_hi:[1,0]
	v_pk_mul_f32 v[182:183], v[90:91], v[164:165] op_sel_hi:[1,0]
	v_pk_mul_f32 v[184:185], v[88:89], v[164:165] op_sel_hi:[1,0]
	v_mul_f32_e32 v165, v179, v179
	v_mul_f32_e32 v177, v181, v181
	v_mul_f32_e32 v186, v185, v185
	v_mul_f32_e32 v187, v183, v183
	v_fmac_f32_e32 v165, v178, v178
	v_fmac_f32_e32 v177, v180, v180
	v_fmac_f32_e32 v186, v184, v184
	v_fmac_f32_e32 v187, v182, v182
	v_add_f32_e32 v165, v165, v177
	v_add_f32_e32 v177, v186, v187
	v_add_f32_e32 v165, v165, v177
	ds_bpermute_b32 v177, v175, v165
	v_cvt_pk_bf16_f32 v178, v178, v179
	v_cvt_pk_bf16_f32 v179, v180, v181
	v_cvt_pk_bf16_f32 v180, v184, v185
	v_cvt_pk_bf16_f32 v181, v182, v183
	s_waitcnt lgkmcnt(0)
	v_add_f32_e32 v165, v165, v177
	ds_bpermute_b32 v177, v176, v165
	v_lshlrev_b64 v[182:183], 8, v[162:163]
	v_lshl_add_u64 v[182:183], v[138:139], 0, v[182:183]
	global_store_dwordx4 v[182:183], v[178:181], off
	s_and_saveexec_b64 s[0:1], s[38:39]
	s_cbranch_execz .LBB0_360
	v_lshl_add_u64 v[178:179], v[162:163], 2, s[44:45]
	s_waitcnt lgkmcnt(0)
	v_add_f32_e32 v165, v165, v177
	global_atomic_add_f32 v[178:179], v165, off

; __device__ __forceinline__ float sq4(f32x4 a) { return (a.x * a.x + a.y * a.y) + (a.z * a.z + a.w * a.w); }
; __device__ __forceinline__ u32x4 pack8(f32x4 a, f32x4 b) { u32x4 o; o.x = cvt_pk(a.x, a.y); o.y = cvt_pk(a.z, a.w); o.z = cvt_pk(b.x, b.y); o.w = cvt_pk(b.z, b.w); return o; }
; __device__ __forceinline__ float rstd_of(const float* SS, int row, float invw) { return 1.0f / sqrtf(SS[row] * invw + EPS); }
;     __device__ __forceinline__ void operator()(const f32x4 (&acc)[2][2][4][2], const pg8::Unit& u, int wr, int wc, int fr, int fq) const {
;     ...
;         } else {
; #pragma unroll
;             for (int ai = 0; ai < 2; ++ai)
; #pragma unroll
;                 for (int m = 0; m < 4; ++m) {
;                     const int row = row0 + ai * 128 + m * 16; const float r = rstd_of(SS1, row, 1.f / 1024.f);
;                     const f32x4 a = acc[ai][0][m][0] * r, b = acc[ai][0][m][1] * r;
;                     *(u32x4*)(CKV + (size_t)row * 128 + colw) = pack8(a, b);
;                     row_stat_add(SSKV, row, sq4(a) + sq4(b), fq);
;                     if (wc == 0) { float* d = KR + (size_t)row * 32 + 8 * fq; *(f32x4*)d = acc[ai][1][m][0] * r; *(f32x4*)(d + 4) = acc[ai][1][m][1] * r; }
;                 }
.LBB0_362:
	v_or_b32_e32 v162, 48, v152
	v_ashrrev_i32_e32 v163, 31, v162
	v_lshl_add_u64 v[164:165], v[162:163], 2, s[48:49]
	s_nop 1
	v_mov_b32_e32 v164, v202
	v_fmamk_f32 v164, v164, 0x3a800000, v172
	v_rsq_f32_e32 v165, v164
	s_nop 0
	s_waitcnt lgkmcnt(0)
	v_mov_b32_e32 v164, v165
	v_pk_mul_f32 v[180:181], v[78:79], v[164:165] op_sel_hi:[1,0]
	v_pk_mul_f32 v[178:179], v[76:77], v[164:165] op_sel_hi:[1,0]
	v_pk_mul_f32 v[182:183], v[74:75], v[164:165] op_sel_hi:[1,0]
	v_pk_mul_f32 v[184:185], v[72:73], v[164:165] op_sel_hi:[1,0]
	v_mul_f32_e32 v165, v179, v179
	v_mul_f32_e32 v177, v181, v181
	v_mul_f32_e32 v186, v185, v185
	v_mul_f32_e32 v187, v183, v183
	v_fmac_f32_e32 v165, v178, v178
	v_fmac_f32_e32 v177, v180, v180
	v_fmac_f32_e32 v186, v184, v184
	v_fmac_f32_e32 v187, v182, v182
	v_add_f32_e32 v165, v165, v177
	v_add_f32_e32 v177, v186, v187
	v_add_f32_e32 v165, v165, v177
	ds_bpermute_b32 v177, v175, v165
	v_cvt_pk_bf16_f32 v178, v178, v179
	v_cvt_pk_bf16_f32 v179, v180, v181
	v_cvt_pk_bf16_f32 v180, v184, v185
	v_cvt_pk_bf16_f32 v181, v182, v183
	s_waitcnt lgkmcnt(0)
	v_add_f32_e32 v165, v165, v177
	ds_bpermute_b32 v177, v176, v165
	v_lshlrev_b64 v[182:183], 8, v[162:163]
	v_lshl_add_u64 v[182:183], v[138:139], 0, v[182:183]
	global_store_dwordx4 v[182:183], v[178:181], off
	s_and_saveexec_b64 s[0:1], s[38:39]
	s_cbranch_execz .LBB0_364
	v_lshl_add_u64 v[178:179], v[162:163], 2, s[44:45]
	s_waitcnt lgkmcnt(0)
	v_add_f32_e32 v165, v165, v177
	global_atomic_add_f32 v[178:179], v165, off

; __device__ __forceinline__ float sq4(f32x4 a) { return (a.x * a.x + a.y * a.y) + (a.z * a.z + a.w * a.w); }
; __device__ __forceinline__ u32x4 pack8(f32x4 a, f32x4 b) { u32x4 o; o.x = cvt_pk(a.x, a.y); o.y = cvt_pk(a.z, a.w); o.z = cvt_pk(b.x, b.y); o.w = cvt_pk(b.z, b.w); return o; }
; __device__ __forceinline__ float rstd_of(const float* SS, int row, float invw) { return 1.0f / sqrtf(SS[row] * invw + EPS); }
;     __device__ __forceinline__ void operator()(const f32x4 (&acc)[2][2][4][2], const pg8::Unit& u, int wr, int wc, int fr, int fq) const {
;     ...
;         } else {
; #pragma unroll
;             for (int ai = 0; ai < 2; ++ai)
; #pragma unroll
;                 for (int m = 0; m < 4; ++m) {
;                     const int row = row0 + ai * 128 + m * 16; const float r = rstd_of(SS1, row, 1.f / 1024.f);
;                     const f32x4 a = acc[ai][0][m][0] * r, b = acc[ai][0][m][1] * r;
;                     *(u32x4*)(CKV + (size_t)row * 128 + colw) = pack8(a, b);
;                     row_stat_add(SSKV, row, sq4(a) + sq4(b), fq);
;                     if (wc == 0) { float* d = KR + (size_t)row * 32 + 8 * fq; *(f32x4*)d = acc[ai][1][m][0] * r; *(f32x4*)(d + 4) = acc[ai][1][m][1] * r; }
;                 }
.LBB0_366:
	s_nop 1
	v_mov_b32_e32 v162, v203
	v_fmamk_f32 v162, v162, 0x3a800000, v172
	v_rsq_f32_e32 v163, v162
	s_nop 0
	s_waitcnt lgkmcnt(0)
	v_add_u32_e32 v162, 0x80, v152
	v_mov_b32_e32 v164, v163
	v_pk_mul_f32 v[180:181], v[62:63], v[164:165] op_sel_hi:[1,0]
	v_pk_mul_f32 v[178:179], v[60:61], v[164:165] op_sel_hi:[1,0]
	v_pk_mul_f32 v[182:183], v[58:59], v[164:165] op_sel_hi:[1,0]
	v_pk_mul_f32 v[184:185], v[56:57], v[164:165] op_sel_hi:[1,0]
	v_mul_f32_e32 v163, v179, v179
	v_mul_f32_e32 v165, v181, v181
	v_mul_f32_e32 v177, v185, v185
	v_mul_f32_e32 v186, v183, v183
	v_fmac_f32_e32 v163, v178, v178
	v_fmac_f32_e32 v165, v180, v180
	v_fmac_f32_e32 v177, v184, v184
	v_fmac_f32_e32 v186, v182, v182
	v_add_f32_e32 v163, v163, v165
	v_add_f32_e32 v165, v177, v186
	v_add_f32_e32 v165, v163, v165
	ds_bpermute_b32 v177, v175, v165
	v_ashrrev_i32_e32 v163, 31, v162
	v_cvt_pk_bf16_f32 v178, v178, v179
	v_cvt_pk_bf16_f32 v179, v180, v181
	v_cvt_pk_bf16_f32 v180, v184, v185
	s_waitcnt lgkmcnt(0)
	v_add_f32_e32 v165, v165, v177
	ds_bpermute_b32 v177, v176, v165
	v_cvt_pk_bf16_f32 v181, v182, v183
	v_lshlrev_b64 v[182:183], 8, v[162:163]
	v_lshl_add_u64 v[182:183], v[138:139], 0, v[182:183]
	global_store_dwordx4 v[182:183], v[178:181], off
	s_and_saveexec_b64 s[0:1], s[38:39]
	s_cbranch_execz .LBB0_368
	v_lshl_add_u64 v[178:179], v[162:163], 2, s[44:45]
	s_waitcnt lgkmcnt(0)
	v_add_f32_e32 v165, v165, v177
	global_atomic_add_f32 v[178:179], v165, off

; __device__ __forceinline__ float sq4(f32x4 a) { return (a.x * a.x + a.y * a.y) + (a.z * a.z + a.w * a.w); }
; __device__ __forceinline__ u32x4 pack8(f32x4 a, f32x4 b) { u32x4 o; o.x = cvt_pk(a.x, a.y); o.y = cvt_pk(a.z, a.w); o.z = cvt_pk(b.x, b.y); o.w = cvt_pk(b.z, b.w); return o; }
; __device__ __forceinline__ float rstd_of(const float* SS, int row, float invw) { return 1.0f / sqrtf(SS[row] * invw + EPS); }
;     __device__ __forceinline__ void operator()(const f32x4 (&acc)[2][2][4][2], const pg8::Unit& u, int wr, int wc, int fr, int fq) const {
;     ...
;         } else {
; #pragma unroll
;             for (int ai = 0; ai < 2; ++ai)
; #pragma unroll
;                 for (int m = 0; m < 4; ++m) {
;                     const int row = row0 + ai * 128 + m * 16; const float r = rstd_of(SS1, row, 1.f / 1024.f);
;                     const f32x4 a = acc[ai][0][m][0] * r, b = acc[ai][0][m][1] * r;
;                     *(u32x4*)(CKV + (size_t)row * 128 + colw) = pack8(a, b);
;                     row_stat_add(SSKV, row, sq4(a) + sq4(b), fq);
;                     if (wc == 0) { float* d = KR + (size_t)row * 32 + 8 * fq; *(f32x4*)d = acc[ai][1][m][0] * r; *(f32x4*)(d + 4) = acc[ai][1][m][1] * r; }
;                 }
.LBB0_370:
	s_nop 1
	v_mov_b32_e32 v162, v204
	v_fmamk_f32 v162, v162, 0x3a800000, v172
	v_rsq_f32_e32 v163, v162
	s_nop 0
	s_waitcnt lgkmcnt(0)
	v_add_u32_e32 v162, 0x90, v152
	v_mov_b32_e32 v164, v163
	v_pk_mul_f32 v[180:181], v[46:47], v[164:165] op_sel_hi:[1,0]
	v_pk_mul_f32 v[178:179], v[44:45], v[164:165] op_sel_hi:[1,0]
	v_pk_mul_f32 v[182:183], v[42:43], v[164:165] op_sel_hi:[1,0]
	v_pk_mul_f32 v[184:185], v[40:41], v[164:165] op_sel_hi:[1,0]
	v_mul_f32_e32 v163, v179, v179
	v_mul_f32_e32 v165, v181, v181
	v_mul_f32_e32 v177, v185, v185
	v_mul_f32_e32 v186, v183, v183
	v_fmac_f32_e32 v163, v178, v178
	v_fmac_f32_e32 v165, v180, v180
	v_fmac_f32_e32 v177, v184, v184
	v_fmac_f32_e32 v186, v182, v182
	v_add_f32_e32 v163, v163, v165
	v_add_f32_e32 v165, v177, v186
	v_add_f32_e32 v165, v163, v165
	ds_bpermute_b32 v177, v175, v165
	v_ashrrev_i32_e32 v163, 31, v162
	v_cvt_pk_bf16_f32 v178, v178, v179
	v_cvt_pk_bf16_f32 v179, v180, v181
	v_cvt_pk_bf16_f32 v180, v184, v185
	s_waitcnt lgkmcnt(0)
	v_add_f32_e32 v165, v165, v177
	ds_bpermute_b32 v177, v176, v165
	v_cvt_pk_bf16_f32 v181, v182, v183
	v_lshlrev_b64 v[182:183], 8, v[162:163]
	v_lshl_add_u64 v[182:183], v[138:139], 0, v[182:183]
	global_store_dwordx4 v[182:183], v[178:181], off
	s_and_saveexec_b64 s[0:1], s[38:39]
	s_cbranch_execz .LBB0_372
	v_lshl_add_u64 v[178:179], v[162:163], 2, s[44:45]
	s_waitcnt lgkmcnt(0)
	v_add_f32_e32 v165, v165, v177
	global_atomic_add_f32 v[178:179], v165, off

; __device__ __forceinline__ float sq4(f32x4 a) { return (a.x * a.x + a.y * a.y) + (a.z * a.z + a.w * a.w); }
; __device__ __forceinline__ u32x4 pack8(f32x4 a, f32x4 b) { u32x4 o; o.x = cvt_pk(a.x, a.y); o.y = cvt_pk(a.z, a.w); o.z = cvt_pk(b.x, b.y); o.w = cvt_pk(b.z, b.w); return o; }
; __device__ __forceinline__ float rstd_of(const float* SS, int row, float invw) { return 1.0f / sqrtf(SS[row] * invw + EPS); }
;     __device__ __forceinline__ void operator()(const f32x4 (&acc)[2][2][4][2], const pg8::Unit& u, int wr, int wc, int fr, int fq) const {
;     ...
;         } else {
; #pragma unroll
;             for (int ai = 0; ai < 2; ++ai)
; #pragma unroll
;                 for (int m = 0; m < 4; ++m) {
;                     const int row = row0 + ai * 128 + m * 16; const float r = rstd_of(SS1, row, 1.f / 1024.f);
;                     const f32x4 a = acc[ai][0][m][0] * r, b = acc[ai][0][m][1] * r;
;                     *(u32x4*)(CKV + (size_t)row * 128 + colw) = pack8(a, b);
;                     row_stat_add(SSKV, row, sq4(a) + sq4(b), fq);
;                     if (wc == 0) { float* d = KR + (size_t)row * 32 + 8 * fq; *(f32x4*)d = acc[ai][1][m][0] * r; *(f32x4*)(d + 4) = acc[ai][1][m][1] * r; }
;                 }
.LBB0_374:
	s_nop 1
	v_mov_b32_e32 v162, v205
	v_fmamk_f32 v162, v162, 0x3a800000, v172
	v_rsq_f32_e32 v163, v162
	s_nop 0
	s_waitcnt lgkmcnt(0)
	v_add_u32_e32 v162, 0xa0, v152
	v_mov_b32_e32 v164, v163
	v_pk_mul_f32 v[180:181], v[30:31], v[164:165] op_sel_hi:[1,0]
	v_pk_mul_f32 v[178:179], v[28:29], v[164:165] op_sel_hi:[1,0]
	v_pk_mul_f32 v[182:183], v[26:27], v[164:165] op_sel_hi:[1,0]
	v_pk_mul_f32 v[184:185], v[24:25], v[164:165] op_sel_hi:[1,0]
	v_mul_f32_e32 v163, v179, v179
	v_mul_f32_e32 v165, v181, v181
	v_mul_f32_e32 v177, v185, v185
	v_mul_f32_e32 v186, v183, v183
	v_fmac_f32_e32 v163, v178, v178
	v_fmac_f32_e32 v165, v180, v180
	v_fmac_f32_e32 v177, v184, v184
	v_fmac_f32_e32 v186, v182, v182
	v_add_f32_e32 v163, v163, v165
	v_add_f32_e32 v165, v177, v186
	v_add_f32_e32 v165, v163, v165
	ds_bpermute_b32 v177, v175, v165
	v_ashrrev_i32_e32 v163, 31, v162
	v_cvt_pk_bf16_f32 v178, v178, v179
	v_cvt_pk_bf16_f32 v179, v180, v181
	v_cvt_pk_bf16_f32 v180, v184, v185
	s_waitcnt lgkmcnt(0)
	v_add_f32_e32 v165, v165, v177
	ds_bpermute_b32 v177, v176, v165
	v_cvt_pk_bf16_f32 v181, v182, v183
	v_lshlrev_b64 v[182:183], 8, v[162:163]
	v_lshl_add_u64 v[182:183], v[138:139], 0, v[182:183]
	global_store_dwordx4 v[182:183], v[178:181], off
	s_and_saveexec_b64 s[0:1], s[38:39]
	s_cbranch_execz .LBB0_376
	v_lshl_add_u64 v[178:179], v[162:163], 2, s[44:45]
	s_waitcnt lgkmcnt(0)
	v_add_f32_e32 v165, v165, v177
	global_atomic_add_f32 v[178:179], v165, off

; __device__ __forceinline__ float sq4(f32x4 a) { return (a.x * a.x + a.y * a.y) + (a.z * a.z + a.w * a.w); }
; __device__ __forceinline__ u32x4 pack8(f32x4 a, f32x4 b) { u32x4 o; o.x = cvt_pk(a.x, a.y); o.y = cvt_pk(a.z, a.w); o.z = cvt_pk(b.x, b.y); o.w = cvt_pk(b.z, b.w); return o; }
; __device__ __forceinline__ float rstd_of(const float* SS, int row, float invw) { return 1.0f / sqrtf(SS[row] * invw + EPS); }
;     __device__ __forceinline__ void operator()(const f32x4 (&acc)[2][2][4][2], const pg8::Unit& u, int wr, int wc, int fr, int fq) const {
;     ...
;         } else {
; #pragma unroll
;             for (int ai = 0; ai < 2; ++ai)
; #pragma unroll
;                 for (int m = 0; m < 4; ++m) {
;                     const int row = row0 + ai * 128 + m * 16; const float r = rstd_of(SS1, row, 1.f / 1024.f);
;                     const f32x4 a = acc[ai][0][m][0] * r, b = acc[ai][0][m][1] * r;
;                     *(u32x4*)(CKV + (size_t)row * 128 + colw) = pack8(a, b);
;                     row_stat_add(SSKV, row, sq4(a) + sq4(b), fq);
;                     if (wc == 0) { float* d = KR + (size_t)row * 32 + 8 * fq; *(f32x4*)d = acc[ai][1][m][0] * r; *(f32x4*)(d + 4) = acc[ai][1][m][1] * r; }
;                 }
.LBB0_378:
	s_nop 1
	v_mov_b32_e32 v162, v206
	v_fmamk_f32 v162, v162, 0x3a800000, v172
	v_rsq_f32_e32 v163, v162
	s_nop 0
	s_waitcnt lgkmcnt(0)
	v_add_u32_e32 v162, 0xb0, v152
	v_mov_b32_e32 v164, v163
	v_pk_mul_f32 v[180:181], v[14:15], v[164:165] op_sel_hi:[1,0]
	v_pk_mul_f32 v[178:179], v[12:13], v[164:165] op_sel_hi:[1,0]
	v_pk_mul_f32 v[182:183], v[10:11], v[164:165] op_sel_hi:[1,0]
	v_pk_mul_f32 v[184:185], v[8:9], v[164:165] op_sel_hi:[1,0]
	v_mul_f32_e32 v163, v179, v179
	v_mul_f32_e32 v165, v181, v181
	v_mul_f32_e32 v177, v185, v185
	v_mul_f32_e32 v186, v183, v183
	v_fmac_f32_e32 v163, v178, v178
	v_fmac_f32_e32 v165, v180, v180
	v_fmac_f32_e32 v177, v184, v184
	v_fmac_f32_e32 v186, v182, v182
	v_add_f32_e32 v163, v163, v165
	v_add_f32_e32 v165, v177, v186
	v_add_f32_e32 v165, v163, v165
	ds_bpermute_b32 v175, v175, v165
	v_ashrrev_i32_e32 v163, 31, v162
	v_cvt_pk_bf16_f32 v178, v178, v179
	v_cvt_pk_bf16_f32 v179, v180, v181
	v_cvt_pk_bf16_f32 v180, v184, v185
	s_waitcnt lgkmcnt(0)
	v_add_f32_e32 v165, v165, v175
	ds_bpermute_b32 v175, v176, v165
	v_lshlrev_b64 v[176:177], 8, v[162:163]
	v_lshl_add_u64 v[176:177], v[138:139], 0, v[176:177]
	v_cvt_pk_bf16_f32 v181, v182, v183
	global_store_dwordx4 v[176:177], v[178:181], off
	s_and_saveexec_b64 s[0:1], s[38:39]
	s_cbranch_execz .LBB0_380
	v_lshl_add_u64 v[176:177], v[162:163], 2, s[44:45]
	s_waitcnt lgkmcnt(0)
	v_add_f32_e32 v165, v165, v175
	global_atomic_add_f32 v[176:177], v165, off

; __device__ __forceinline__ float sq4(f32x4 a) { return (a.x * a.x + a.y * a.y) + (a.z * a.z + a.w * a.w); }
; __device__ __forceinline__ u32x4 pack8(f32x4 a, f32x4 b) { u32x4 o; o.x = cvt_pk(a.x, a.y); o.y = cvt_pk(a.z, a.w); o.z = cvt_pk(b.x, b.y); o.w = cvt_pk(b.z, b.w); return o; }
; __device__ __forceinline__ float rstd_of(const float* SS, int row, float invw) { return 1.0f / sqrtf(SS[row] * invw + EPS); }
;     __device__ __forceinline__ void operator()(const f32x4 (&acc)[2][2][4][2], const pg8::Unit& u, int wr, int wc, int fr, int fq) const {
;     ...
;         } else if (u.pn == 4) {
; #pragma unroll
;             for (int ai = 0; ai < 2; ++ai)
; #pragma unroll
;                 for (int m = 0; m < 4; ++m) {
;                     const int row = row0 + ai * 128 + m * 16; const float r = rstd_of(SS1, row, 1.f / 1024.f); float ssq = 0.f;
; #pragma unroll
;                     for (int bj = 0; bj < 2; ++bj) {
;                         const f32x4 a = acc[ai][bj][m][0] * r, b = acc[ai][bj][m][1] * r; ssq += sq4(a) + sq4(b);
;                         *(u32x4*)(CQ + (size_t)row * 256 + bj * 128 + colw) = pack8(a, b);
;                     }
;                     row_stat_add(SSQ, row, ssq, fq);
;                 }
.LBB0_386:
	s_or_b64 exec, exec, s[0:1]
	v_or_b32_e32 v156, 16, v152
	s_waitcnt lgkmcnt(0)
	v_ashrrev_i32_e32 v157, 31, v156
	v_lshl_add_u64 v[160:161], v[156:157], 2, s[48:49]
	s_nop 1
	v_mov_b32_e32 v160, v200
	v_lshlrev_b64 v[176:177], 9, v[156:157]
	v_lshl_add_u64 v[176:177], v[142:143], 0, v[176:177]
	v_fmamk_f32 v160, v160, 0x3a800000, v172
	v_rsq_f32_e32 v161, v160
	s_nop 0
	v_mov_b32_e32 v164, v161
	v_pk_mul_f32 v[162:163], v[110:111], v[164:165] op_sel_hi:[1,0]
	v_pk_mul_f32 v[160:161], v[108:109], v[164:165] op_sel_hi:[1,0]
	v_pk_mul_f32 v[178:179], v[106:107], v[164:165] op_sel_hi:[1,0]
	v_pk_mul_f32 v[180:181], v[104:105], v[164:165] op_sel_hi:[1,0]
	v_mul_f32_e32 v165, v161, v161
	v_mul_f32_e32 v175, v163, v163
	v_fmac_f32_e32 v165, v160, v160
	v_fmac_f32_e32 v175, v162, v162
	v_add_f32_e32 v165, v165, v175
	v_mul_f32_e32 v175, v181, v181
	v_mul_f32_e32 v182, v179, v179
	v_cvt_pk_bf16_f32 v160, v160, v161
	v_cvt_pk_bf16_f32 v161, v162, v163
	v_cvt_pk_bf16_f32 v162, v180, v181
	v_cvt_pk_bf16_f32 v163, v178, v179
	v_fmac_f32_e32 v175, v180, v180
	v_fmac_f32_e32 v182, v178, v178
	global_store_dwordx4 v[176:177], v[160:163], off
	v_add_f32_e32 v175, v175, v182
	v_add_f32_e32 v175, v165, v175
	v_pk_mul_f32 v[162:163], v[102:103], v[164:165] op_sel_hi:[1,0]
	v_pk_mul_f32 v[160:161], v[100:101], v[164:165] op_sel_hi:[1,0]
	v_mul_f32_e32 v181, v163, v163
	v_mul_f32_e32 v180, v161, v161
	v_pk_mul_f32 v[178:179], v[98:99], v[164:165] op_sel_hi:[1,0]
	v_pk_mul_f32 v[164:165], v[96:97], v[164:165] op_sel_hi:[1,0]
	v_fmac_f32_e32 v180, v160, v160
	v_fmac_f32_e32 v181, v162, v162
	v_add_f32_e32 v180, v180, v181
	v_mul_f32_e32 v181, v165, v165
	v_mul_f32_e32 v182, v179, v179
	v_fmac_f32_e32 v181, v164, v164
	v_fmac_f32_e32 v182, v178, v178
	v_add_f32_e32 v181, v181, v182
	v_add_f32_e32 v180, v180, v181
	v_add_f32_e32 v175, v175, v180
	v_cvt_pk_bf16_f32 v160, v160, v161
	v_cvt_pk_bf16_f32 v161, v162, v163
	v_cvt_pk_bf16_f32 v162, v164, v165
	v_cvt_pk_bf16_f32 v163, v178, v179
	global_store_dwordx4 v[176:177], v[160:163], off offset:256
	ds_bpermute_b32 v160, v158, v175
	s_waitcnt lgkmcnt(0)
	v_add_f32_e32 v160, v175, v160
	ds_bpermute_b32 v161, v159, v160
	s_and_saveexec_b64 s[0:1], s[38:39]
	s_cbranch_execz .LBB0_388
	v_lshl_add_u64 v[156:157], v[156:157], 2, s[46:47]
	s_waitcnt lgkmcnt(0)
	v_add_f32_e32 v160, v160, v161
	global_atomic_add_f32 v[156:157], v160, off
.LBB0_388:
	s_or_b64 exec, exec, s[0:1]
	v_or_b32_e32 v156, 32, v152
	v_ashrrev_i32_e32 v157, 31, v156
	s_waitcnt lgkmcnt(0)
	v_lshl_add_u64 v[160:161], v[156:157], 2, s[48:49]
	s_nop 1
	v_mov_b32_e32 v160, v201
	v_lshlrev_b64 v[176:177], 9, v[156:157]
	v_lshl_add_u64 v[176:177], v[142:143], 0, v[176:177]
	v_fmamk_f32 v160, v160, 0x3a800000, v172
	v_rsq_f32_e32 v161, v160
	s_nop 0
	v_mov_b32_e32 v164, v161
	v_pk_mul_f32 v[162:163], v[94:95], v[164:165] op_sel_hi:[1,0]
	v_pk_mul_f32 v[160:161], v[92:93], v[164:165] op_sel_hi:[1,0]
	v_pk_mul_f32 v[178:179], v[90:91], v[164:165] op_sel_hi:[1,0]
	v_pk_mul_f32 v[180:181], v[88:89], v[164:165] op_sel_hi:[1,0]
	v_mul_f32_e32 v165, v161, v161
	v_mul_f32_e32 v175, v163, v163
	v_fmac_f32_e32 v165, v160, v160
	v_fmac_f32_e32 v175, v162, v162
	v_add_f32_e32 v165, v165, v175
	v_mul_f32_e32 v175, v181, v181
	v_mul_f32_e32 v182, v179, v179
	v_cvt_pk_bf16_f32 v160, v160, v161
	v_cvt_pk_bf16_f32 v161, v162, v163
	v_cvt_pk_bf16_f32 v162, v180, v181
	v_cvt_pk_bf16_f32 v163, v178, v179
	v_fmac_f32_e32 v175, v180, v180
	v_fmac_f32_e32 v182, v178, v178
	global_store_dwordx4 v[176:177], v[160:163], off
	v_add_f32_e32 v175, v175, v182
	v_add_f32_e32 v175, v165, v175
	v_pk_mul_f32 v[162:163], v[86:87], v[164:165] op_sel_hi:[1,0]
	v_pk_mul_f32 v[160:161], v[84:85], v[164:165] op_sel_hi:[1,0]
	v_mul_f32_e32 v181, v163, v163
	v_mul_f32_e32 v180, v161, v161
	v_pk_mul_f32 v[178:179], v[82:83], v[164:165] op_sel_hi:[1,0]
	v_pk_mul_f32 v[164:165], v[80:81], v[164:165] op_sel_hi:[1,0]
	v_fmac_f32_e32 v180, v160, v160
	v_fmac_f32_e32 v181, v162, v162
	v_add_f32_e32 v180, v180, v181
	v_mul_f32_e32 v181, v165, v165
	v_mul_f32_e32 v182, v179, v179
	v_fmac_f32_e32 v181, v164, v164
	v_fmac_f32_e32 v182, v178, v178
	v_add_f32_e32 v181, v181, v182
	v_add_f32_e32 v180, v180, v181
	v_add_f32_e32 v175, v175, v180
	v_cvt_pk_bf16_f32 v160, v160, v161
	v_cvt_pk_bf16_f32 v161, v162, v163
	v_cvt_pk_bf16_f32 v162, v164, v165
	v_cvt_pk_bf16_f32 v163, v178, v179
	global_store_dwordx4 v[176:177], v[160:163], off offset:256
	ds_bpermute_b32 v160, v158, v175
	s_waitcnt lgkmcnt(0)
	v_add_f32_e32 v160, v175, v160
	ds_bpermute_b32 v161, v159, v160
	s_and_saveexec_b64 s[0:1], s[38:39]
	s_cbranch_execz .LBB0_390
	v_lshl_add_u64 v[156:157], v[156:157], 2, s[46:47]
	s_waitcnt lgkmcnt(0)
	v_add_f32_e32 v160, v160, v161
	global_atomic_add_f32 v[156:157], v160, off
; __device__ __forceinline__ float sq4(f32x4 a) { return (a.x * a.x + a.y * a.y) + (a.z * a.z + a.w * a.w); }
; __device__ __forceinline__ u32x4 pack8(f32x4 a, f32x4 b) { u32x4 o; o.x = cvt_pk(a.x, a.y); o.y = cvt_pk(a.z, a.w); o.z = cvt_pk(b.x, b.y); o.w = cvt_pk(b.z, b.w); return o; }
; __device__ __forceinline__ float rstd_of(const float* SS, int row, float invw) { return 1.0f / sqrtf(SS[row] * invw + EPS); }
;     __device__ __forceinline__ void operator()(const f32x4 (&acc)[2][2][4][2], const pg8::Unit& u, int wr, int wc, int fr, int fq) const {
;     ...
;         } else if (u.pn == 4) {
; #pragma unroll
;             for (int ai = 0; ai < 2; ++ai)
; #pragma unroll
;                 for (int m = 0; m < 4; ++m) {
;                     const int row = row0 + ai * 128 + m * 16; const float r = rstd_of(SS1, row, 1.f / 1024.f); float ssq = 0.f;
; #pragma unroll
;                     for (int bj = 0; bj < 2; ++bj) {
;                         const f32x4 a = acc[ai][bj][m][0] * r, b = acc[ai][bj][m][1] * r; ssq += sq4(a) + sq4(b);
;                         *(u32x4*)(CQ + (size_t)row * 256 + bj * 128 + colw) = pack8(a, b);
;                     }
;                     row_stat_add(SSQ, row, ssq, fq);
;                 }
.LBB0_390:
	s_or_b64 exec, exec, s[0:1]
	v_or_b32_e32 v156, 48, v152
	v_ashrrev_i32_e32 v157, 31, v156
	s_waitcnt lgkmcnt(0)
	v_lshl_add_u64 v[160:161], v[156:157], 2, s[48:49]
	s_nop 1
	v_mov_b32_e32 v160, v202
	v_lshlrev_b64 v[176:177], 9, v[156:157]
	v_lshl_add_u64 v[176:177], v[142:143], 0, v[176:177]
	v_fmamk_f32 v160, v160, 0x3a800000, v172
	v_rsq_f32_e32 v161, v160
	s_nop 0
	v_mov_b32_e32 v164, v161
	v_pk_mul_f32 v[162:163], v[78:79], v[164:165] op_sel_hi:[1,0]
	v_pk_mul_f32 v[160:161], v[76:77], v[164:165] op_sel_hi:[1,0]
	v_pk_mul_f32 v[178:179], v[74:75], v[164:165] op_sel_hi:[1,0]
	v_pk_mul_f32 v[180:181], v[72:73], v[164:165] op_sel_hi:[1,0]
	v_mul_f32_e32 v165, v161, v161
	v_mul_f32_e32 v175, v163, v163
	v_fmac_f32_e32 v165, v160, v160
	v_fmac_f32_e32 v175, v162, v162
	v_add_f32_e32 v165, v165, v175
	v_mul_f32_e32 v175, v181, v181
	v_mul_f32_e32 v182, v179, v179
	v_cvt_pk_bf16_f32 v160, v160, v161
	v_cvt_pk_bf16_f32 v161, v162, v163
	v_cvt_pk_bf16_f32 v162, v180, v181
	v_cvt_pk_bf16_f32 v163, v178, v179
	v_fmac_f32_e32 v175, v180, v180
	v_fmac_f32_e32 v182, v178, v178
	global_store_dwordx4 v[176:177], v[160:163], off
	v_add_f32_e32 v175, v175, v182
	v_add_f32_e32 v175, v165, v175
	v_pk_mul_f32 v[162:163], v[70:71], v[164:165] op_sel_hi:[1,0]
	v_pk_mul_f32 v[160:161], v[68:69], v[164:165] op_sel_hi:[1,0]
	v_mul_f32_e32 v181, v163, v163
	v_mul_f32_e32 v180, v161, v161
	v_pk_mul_f32 v[178:179], v[66:67], v[164:165] op_sel_hi:[1,0]
	v_pk_mul_f32 v[164:165], v[64:65], v[164:165] op_sel_hi:[1,0]
	v_fmac_f32_e32 v180, v160, v160
	v_fmac_f32_e32 v181, v162, v162
	v_add_f32_e32 v180, v180, v181
	v_mul_f32_e32 v181, v165, v165
	v_mul_f32_e32 v182, v179, v179
	v_fmac_f32_e32 v181, v164, v164
	v_fmac_f32_e32 v182, v178, v178
	v_add_f32_e32 v181, v181, v182
	v_add_f32_e32 v180, v180, v181
	v_add_f32_e32 v175, v175, v180
	v_cvt_pk_bf16_f32 v160, v160, v161
	v_cvt_pk_bf16_f32 v161, v162, v163
	v_cvt_pk_bf16_f32 v162, v164, v165
	v_cvt_pk_bf16_f32 v163, v178, v179
	global_store_dwordx4 v[176:177], v[160:163], off offset:256
	ds_bpermute_b32 v160, v158, v175
	s_waitcnt lgkmcnt(0)
	v_add_f32_e32 v160, v175, v160
	ds_bpermute_b32 v161, v159, v160
	s_and_saveexec_b64 s[0:1], s[38:39]
	s_cbranch_execz .LBB0_392
	v_lshl_add_u64 v[156:157], v[156:157], 2, s[46:47]
	s_waitcnt lgkmcnt(0)
	v_add_f32_e32 v160, v160, v161
	global_atomic_add_f32 v[156:157], v160, off
.LBB0_392:
	s_or_b64 exec, exec, s[0:1]
	s_nop 1
	v_mov_b32_e32 v160, v203
	v_add_u32_e32 v156, 0x80, v152
	v_ashrrev_i32_e32 v157, 31, v156
	v_lshlrev_b64 v[176:177], 9, v[156:157]
	v_lshl_add_u64 v[176:177], v[142:143], 0, v[176:177]
	v_fmamk_f32 v160, v160, 0x3a800000, v172
	v_rsq_f32_e32 v161, v160
	s_nop 0
	s_waitcnt lgkmcnt(0)
	v_mov_b32_e32 v164, v161
	v_pk_mul_f32 v[162:163], v[62:63], v[164:165] op_sel_hi:[1,0]
	v_pk_mul_f32 v[160:161], v[60:61], v[164:165] op_sel_hi:[1,0]
	v_pk_mul_f32 v[178:179], v[58:59], v[164:165] op_sel_hi:[1,0]
	v_pk_mul_f32 v[180:181], v[56:57], v[164:165] op_sel_hi:[1,0]
	v_mul_f32_e32 v165, v161, v161
	v_mul_f32_e32 v175, v163, v163
	v_fmac_f32_e32 v165, v160, v160
	v_fmac_f32_e32 v175, v162, v162
	v_add_f32_e32 v165, v165, v175
	v_mul_f32_e32 v175, v181, v181
	v_mul_f32_e32 v182, v179, v179
	v_cvt_pk_bf16_f32 v160, v160, v161
	v_cvt_pk_bf16_f32 v161, v162, v163
	v_cvt_pk_bf16_f32 v162, v180, v181
	v_cvt_pk_bf16_f32 v163, v178, v179
	v_fmac_f32_e32 v175, v180, v180
	v_fmac_f32_e32 v182, v178, v178
	global_store_dwordx4 v[176:177], v[160:163], off
	v_add_f32_e32 v175, v175, v182
	v_add_f32_e32 v175, v165, v175
	v_pk_mul_f32 v[162:163], v[54:55], v[164:165] op_sel_hi:[1,0]
	v_pk_mul_f32 v[160:161], v[52:53], v[164:165] op_sel_hi:[1,0]
	v_mul_f32_e32 v181, v163, v163
	v_mul_f32_e32 v180, v161, v161
	v_pk_mul_f32 v[178:179], v[50:51], v[164:165] op_sel_hi:[1,0]
	v_pk_mul_f32 v[164:165], v[48:49], v[164:165] op_sel_hi:[1,0]
	v_fmac_f32_e32 v180, v160, v160
	v_fmac_f32_e32 v181, v162, v162
	v_add_f32_e32 v180, v180, v181
	v_mul_f32_e32 v181, v165, v165
	v_mul_f32_e32 v182, v179, v179
	v_fmac_f32_e32 v181, v164, v164
	v_fmac_f32_e32 v182, v178, v178
	v_add_f32_e32 v181, v181, v182
	v_add_f32_e32 v180, v180, v181
	v_add_f32_e32 v175, v175, v180
	v_cvt_pk_bf16_f32 v160, v160, v161
	v_cvt_pk_bf16_f32 v161, v162, v163
	v_cvt_pk_bf16_f32 v162, v164, v165
	v_cvt_pk_bf16_f32 v163, v178, v179
	global_store_dwordx4 v[176:177], v[160:163], off offset:256
	ds_bpermute_b32 v160, v158, v175
	s_waitcnt lgkmcnt(0)
	v_add_f32_e32 v160, v175, v160
	ds_bpermute_b32 v161, v159, v160
	s_and_saveexec_b64 s[0:1], s[38:39]
	s_cbranch_execz .LBB0_394
	v_lshl_add_u64 v[156:157], v[156:157], 2, s[46:47]
	s_waitcnt lgkmcnt(0)
	v_add_f32_e32 v160, v160, v161
	global_atomic_add_f32 v[156:157], v160, off
; __device__ __forceinline__ float sq4(f32x4 a) { return (a.x * a.x + a.y * a.y) + (a.z * a.z + a.w * a.w); }
; __device__ __forceinline__ u32x4 pack8(f32x4 a, f32x4 b) { u32x4 o; o.x = cvt_pk(a.x, a.y); o.y = cvt_pk(a.z, a.w); o.z = cvt_pk(b.x, b.y); o.w = cvt_pk(b.z, b.w); return o; }
; __device__ __forceinline__ float rstd_of(const float* SS, int row, float invw) { return 1.0f / sqrtf(SS[row] * invw + EPS); }
;     __device__ __forceinline__ void operator()(const f32x4 (&acc)[2][2][4][2], const pg8::Unit& u, int wr, int wc, int fr, int fq) const {
;     ...
;         } else if (u.pn == 4) {
; #pragma unroll
;             for (int ai = 0; ai < 2; ++ai)
; #pragma unroll
;                 for (int m = 0; m < 4; ++m) {
;                     const int row = row0 + ai * 128 + m * 16; const float r = rstd_of(SS1, row, 1.f / 1024.f); float ssq = 0.f;
; #pragma unroll
;                     for (int bj = 0; bj < 2; ++bj) {
;                         const f32x4 a = acc[ai][bj][m][0] * r, b = acc[ai][bj][m][1] * r; ssq += sq4(a) + sq4(b);
;                         *(u32x4*)(CQ + (size_t)row * 256 + bj * 128 + colw) = pack8(a, b);
;                     }
;                     row_stat_add(SSQ, row, ssq, fq);
;                 }
.LBB0_394:
	s_or_b64 exec, exec, s[0:1]
	s_nop 1
	v_mov_b32_e32 v160, v204
	v_add_u32_e32 v156, 0x90, v152
	v_ashrrev_i32_e32 v157, 31, v156
	v_lshlrev_b64 v[176:177], 9, v[156:157]
	v_lshl_add_u64 v[176:177], v[142:143], 0, v[176:177]
	v_fmamk_f32 v160, v160, 0x3a800000, v172
	v_rsq_f32_e32 v161, v160
	s_nop 0
	s_waitcnt lgkmcnt(0)
	v_mov_b32_e32 v164, v161
	v_pk_mul_f32 v[162:163], v[46:47], v[164:165] op_sel_hi:[1,0]
	v_pk_mul_f32 v[160:161], v[44:45], v[164:165] op_sel_hi:[1,0]
	v_pk_mul_f32 v[178:179], v[42:43], v[164:165] op_sel_hi:[1,0]
	v_pk_mul_f32 v[180:181], v[40:41], v[164:165] op_sel_hi:[1,0]
	v_mul_f32_e32 v165, v161, v161
	v_mul_f32_e32 v175, v163, v163
	v_fmac_f32_e32 v165, v160, v160
	v_fmac_f32_e32 v175, v162, v162
	v_add_f32_e32 v165, v165, v175
	v_mul_f32_e32 v175, v181, v181
	v_mul_f32_e32 v182, v179, v179
	v_cvt_pk_bf16_f32 v160, v160, v161
	v_cvt_pk_bf16_f32 v161, v162, v163
	v_cvt_pk_bf16_f32 v162, v180, v181
	v_cvt_pk_bf16_f32 v163, v178, v179
	v_fmac_f32_e32 v175, v180, v180
	v_fmac_f32_e32 v182, v178, v178
	global_store_dwordx4 v[176:177], v[160:163], off
	v_add_f32_e32 v175, v175, v182
	v_add_f32_e32 v175, v165, v175
	v_pk_mul_f32 v[162:163], v[38:39], v[164:165] op_sel_hi:[1,0]
	v_pk_mul_f32 v[160:161], v[36:37], v[164:165] op_sel_hi:[1,0]
	v_mul_f32_e32 v181, v163, v163
	v_mul_f32_e32 v180, v161, v161
	v_pk_mul_f32 v[178:179], v[34:35], v[164:165] op_sel_hi:[1,0]
	v_pk_mul_f32 v[164:165], v[32:33], v[164:165] op_sel_hi:[1,0]
	v_fmac_f32_e32 v180, v160, v160
	v_fmac_f32_e32 v181, v162, v162
	v_add_f32_e32 v180, v180, v181
	v_mul_f32_e32 v181, v165, v165
	v_mul_f32_e32 v182, v179, v179
	v_fmac_f32_e32 v181, v164, v164
	v_fmac_f32_e32 v182, v178, v178
	v_add_f32_e32 v181, v181, v182
	v_add_f32_e32 v180, v180, v181
	v_add_f32_e32 v175, v175, v180
	v_cvt_pk_bf16_f32 v160, v160, v161
	v_cvt_pk_bf16_f32 v161, v162, v163
	v_cvt_pk_bf16_f32 v162, v164, v165
	v_cvt_pk_bf16_f32 v163, v178, v179
	global_store_dwordx4 v[176:177], v[160:163], off offset:256
	ds_bpermute_b32 v160, v158, v175
	s_waitcnt lgkmcnt(0)
	v_add_f32_e32 v160, v175, v160
	ds_bpermute_b32 v161, v159, v160
	s_and_saveexec_b64 s[0:1], s[38:39]
	s_cbranch_execz .LBB0_396
	v_lshl_add_u64 v[156:157], v[156:157], 2, s[46:47]
	s_waitcnt lgkmcnt(0)
	v_add_f32_e32 v160, v160, v161
	global_atomic_add_f32 v[156:157], v160, off
.LBB0_396:
	s_or_b64 exec, exec, s[0:1]
	s_nop 1
	v_mov_b32_e32 v160, v205
	v_add_u32_e32 v156, 0xa0, v152
	v_ashrrev_i32_e32 v157, 31, v156
	v_lshlrev_b64 v[176:177], 9, v[156:157]
	v_lshl_add_u64 v[176:177], v[142:143], 0, v[176:177]
	v_fmamk_f32 v160, v160, 0x3a800000, v172
	v_rsq_f32_e32 v161, v160
	s_nop 0
	s_waitcnt lgkmcnt(0)
	v_mov_b32_e32 v164, v161
	v_pk_mul_f32 v[162:163], v[30:31], v[164:165] op_sel_hi:[1,0]
	v_pk_mul_f32 v[160:161], v[28:29], v[164:165] op_sel_hi:[1,0]
	v_pk_mul_f32 v[178:179], v[26:27], v[164:165] op_sel_hi:[1,0]
	v_pk_mul_f32 v[180:181], v[24:25], v[164:165] op_sel_hi:[1,0]
	v_mul_f32_e32 v165, v161, v161
	v_mul_f32_e32 v175, v163, v163
	v_fmac_f32_e32 v165, v160, v160
	v_fmac_f32_e32 v175, v162, v162
	v_add_f32_e32 v165, v165, v175
	v_mul_f32_e32 v175, v181, v181
	v_mul_f32_e32 v182, v179, v179
	v_cvt_pk_bf16_f32 v160, v160, v161
	v_cvt_pk_bf16_f32 v161, v162, v163
	v_cvt_pk_bf16_f32 v162, v180, v181
	v_cvt_pk_bf16_f32 v163, v178, v179
	v_fmac_f32_e32 v175, v180, v180
	v_fmac_f32_e32 v182, v178, v178
	global_store_dwordx4 v[176:177], v[160:163], off
	v_add_f32_e32 v175, v175, v182
	v_add_f32_e32 v175, v165, v175
	v_pk_mul_f32 v[162:163], v[22:23], v[164:165] op_sel_hi:[1,0]
	v_pk_mul_f32 v[160:161], v[20:21], v[164:165] op_sel_hi:[1,0]
	v_mul_f32_e32 v181, v163, v163
	v_mul_f32_e32 v180, v161, v161
	v_pk_mul_f32 v[178:179], v[18:19], v[164:165] op_sel_hi:[1,0]
	v_pk_mul_f32 v[164:165], v[16:17], v[164:165] op_sel_hi:[1,0]
	v_fmac_f32_e32 v180, v160, v160
	v_fmac_f32_e32 v181, v162, v162
	v_add_f32_e32 v180, v180, v181
	v_mul_f32_e32 v181, v165, v165
	v_mul_f32_e32 v182, v179, v179
	v_fmac_f32_e32 v181, v164, v164
	v_fmac_f32_e32 v182, v178, v178
	v_add_f32_e32 v181, v181, v182
	v_add_f32_e32 v180, v180, v181
	v_add_f32_e32 v175, v175, v180
	v_cvt_pk_bf16_f32 v160, v160, v161
	v_cvt_pk_bf16_f32 v161, v162, v163
	v_cvt_pk_bf16_f32 v162, v164, v165
	v_cvt_pk_bf16_f32 v163, v178, v179
	global_store_dwordx4 v[176:177], v[160:163], off offset:256
	ds_bpermute_b32 v160, v158, v175
	s_waitcnt lgkmcnt(0)
	v_add_f32_e32 v160, v175, v160
	ds_bpermute_b32 v161, v159, v160
	s_and_saveexec_b64 s[0:1], s[38:39]
	s_cbranch_execz .LBB0_398
	v_lshl_add_u64 v[156:157], v[156:157], 2, s[46:47]
	s_waitcnt lgkmcnt(0)
	v_add_f32_e32 v160, v160, v161
	global_atomic_add_f32 v[156:157], v160, off
.LBB0_398:
	s_or_b64 exec, exec, s[0:1]
	s_nop 1
	v_mov_b32_e32 v154, v206
	v_add_u32_e32 v156, 0xb0, v152
	v_ashrrev_i32_e32 v157, 31, v156
	v_lshlrev_b64 v[164:165], 9, v[156:157]
	v_lshl_add_u64 v[164:165], v[142:143], 0, v[164:165]
	v_fmamk_f32 v154, v154, 0x3a800000, v172
	v_rsq_f32_e32 v155, v154
	s_nop 0
	s_waitcnt lgkmcnt(0)
	v_mov_b32_e32 v154, v155
	v_pk_mul_f32 v[162:163], v[14:15], v[154:155] op_sel_hi:[1,0]
	v_pk_mul_f32 v[160:161], v[12:13], v[154:155] op_sel_hi:[1,0]
	v_pk_mul_f32 v[176:177], v[10:11], v[154:155] op_sel_hi:[1,0]
	v_pk_mul_f32 v[178:179], v[8:9], v[154:155] op_sel_hi:[1,0]
	v_mul_f32_e32 v155, v161, v161
	v_mul_f32_e32 v175, v163, v163
	v_fmac_f32_e32 v155, v160, v160
	v_fmac_f32_e32 v175, v162, v162
	v_add_f32_e32 v155, v155, v175
	v_mul_f32_e32 v175, v179, v179
	v_mul_f32_e32 v180, v177, v177
	v_cvt_pk_bf16_f32 v160, v160, v161
	v_cvt_pk_bf16_f32 v161, v162, v163
	v_cvt_pk_bf16_f32 v162, v178, v179
	v_cvt_pk_bf16_f32 v163, v176, v177
	v_fmac_f32_e32 v175, v178, v178
	v_fmac_f32_e32 v180, v176, v176
	global_store_dwordx4 v[164:165], v[160:163], off
	v_add_f32_e32 v175, v175, v180
	v_add_f32_e32 v175, v155, v175
	v_pk_mul_f32 v[162:163], v[6:7], v[154:155] op_sel_hi:[1,0]
	v_pk_mul_f32 v[160:161], v[4:5], v[154:155] op_sel_hi:[1,0]
	v_mul_f32_e32 v179, v163, v163
	v_mul_f32_e32 v178, v161, v161
	v_pk_mul_f32 v[176:177], v[2:3], v[154:155] op_sel_hi:[1,0]
	v_pk_mul_f32 v[154:155], v[0:1], v[154:155] op_sel_hi:[1,0]
	v_fmac_f32_e32 v178, v160, v160
	v_fmac_f32_e32 v179, v162, v162
	v_add_f32_e32 v178, v178, v179
	v_mul_f32_e32 v179, v155, v155
	v_mul_f32_e32 v180, v177, v177
	v_fmac_f32_e32 v179, v154, v154
	v_fmac_f32_e32 v180, v176, v176
	v_add_f32_e32 v179, v179, v180
	v_add_f32_e32 v178, v178, v179
	v_add_f32_e32 v175, v175, v178
	v_cvt_pk_bf16_f32 v160, v160, v161
	v_cvt_pk_bf16_f32 v161, v162, v163
	v_cvt_pk_bf16_f32 v162, v154, v155
	ds_bpermute_b32 v154, v158, v175
	v_cvt_pk_bf16_f32 v163, v176, v177
	global_store_dwordx4 v[164:165], v[160:163], off offset:256
	s_waitcnt lgkmcnt(0)
	v_add_f32_e32 v154, v175, v154
	ds_bpermute_b32 v155, v159, v154
	s_and_saveexec_b64 s[0:1], s[38:39]
	s_cbranch_execz .LBB0_400
	v_lshl_add_u64 v[156:157], v[156:157], 2, s[46:47]
	s_waitcnt lgkmcnt(0)
	v_add_f32_e32 v154, v154, v155
	global_atomic_add_f32 v[156:157], v154, off

; __device__ __forceinline__ u32x4 pack8(f32x4 a, f32x4 b) { u32x4 o; o.x = cvt_pk(a.x, a.y); o.y = cvt_pk(a.z, a.w); o.z = cvt_pk(b.x, b.y); o.w = cvt_pk(b.z, b.w); return o; }
; __device__ __forceinline__ float rstd_of(const float* SS, int row, float invw) { return 1.0f / sqrtf(SS[row] * invw + EPS); }
;     __device__ __forceinline__ void operator()(const f32x4 (&acc)[2][2][4][2], const pg8::Unit& u, int wr, int wc, int fr, int fq) const {
;         const int row0 = u.pm * 256 + wr * 64 + fr, col0 = u.pn * 256 + wc * 32 + 8 * fq;
; #pragma unroll
;         for (int ai = 0; ai < 2; ++ai)
; #pragma unroll
;             for (int m = 0; m < 4; ++m) {
;                 const int row = row0 + ai * 128 + m * 16; const float r = rstd_of(SS, row, invw);
; #pragma unroll
;                 for (int bj = 0; bj < 2; ++bj)
;                     *(u32x4*)(O + (size_t)row * ldc + col0 + bj * 128) = pack8(acc[ai][bj][m][0] * r, acc[ai][bj][m][1] * r);
;             }
;     }
.LBB0_475:
	v_lshl_add_u32 v140, s0, 8, v144
	v_ashrrev_i32_e32 v141, 31, v140
	v_lshl_add_u64 v[142:143], v[140:141], 2, s[46:47]
	global_load_dword v200, v[142:143], off
	global_load_dword v201, v[142:143], off offset:64
	global_load_dword v202, v[142:143], off offset:128
	global_load_dword v203, v[142:143], off offset:192
	global_load_dword v204, v[142:143], off offset:512
	global_load_dword v205, v[142:143], off offset:576
	global_load_dword v206, v[142:143], off offset:640
	global_load_dword v207, v[142:143], off offset:704
	v_lshl_or_b32 v152, s1, 8, v146
	v_ashrrev_i32_e32 v153, 31, v152
	s_waitcnt vmcnt(0)
	v_mov_b32_e32 v141, v200
	v_fmamk_f32 v141, v141, 0x3b800000, v150
	v_rsq_f32_e32 v155, v141
	s_nop 0
	v_mov_b32_e32 v154, v155
	v_pk_mul_f32 v[126:127], v[126:127], v[154:155] op_sel_hi:[1,0]
	v_pk_mul_f32 v[124:125], v[124:125], v[154:155] op_sel_hi:[1,0]
	v_pk_mul_f32 v[120:121], v[120:121], v[154:155] op_sel_hi:[1,0]
	v_pk_mul_f32 v[122:123], v[122:123], v[154:155] op_sel_hi:[1,0]
	v_cvt_pk_bf16_f32 v124, v124, v125
	v_cvt_pk_bf16_f32 v125, v126, v127
	v_cvt_pk_bf16_f32 v126, v120, v121
	v_mov_b64_e32 v[120:121], s[34:35]
	v_cvt_pk_bf16_f32 v127, v122, v123
	v_mad_i64_i32 v[156:157], s[0:1], v140, s10, v[120:121]
	v_lshlrev_b64 v[122:123], 1, v[152:153]
	v_lshl_add_u64 v[152:153], v[156:157], 0, v[122:123]
	global_store_dwordx4 v[152:153], v[124:127], off
	v_pk_mul_f32 v[116:117], v[116:117], v[154:155] op_sel_hi:[1,0]
	v_pk_mul_f32 v[118:119], v[118:119], v[154:155] op_sel_hi:[1,0]
	v_pk_mul_f32 v[124:125], v[114:115], v[154:155] op_sel_hi:[1,0]
	v_pk_mul_f32 v[114:115], v[112:113], v[154:155] op_sel_hi:[1,0]
	v_cvt_pk_bf16_f32 v112, v116, v117
	v_cvt_pk_bf16_f32 v113, v118, v119
	s_nop 0
	v_cvt_pk_bf16_f32 v114, v114, v115
	v_cvt_pk_bf16_f32 v115, v124, v125
	global_store_dwordx4 v[152:153], v[112:115], off offset:256
	s_nop 1
	v_or_b32_e32 v112, 16, v140
	v_ashrrev_i32_e32 v113, 31, v112
	v_lshl_add_u64 v[114:115], v[112:113], 2, s[46:47]
	s_nop 1
	v_mov_b32_e32 v113, v201
	v_fmamk_f32 v113, v113, 0x3b800000, v150
	v_rsq_f32_e32 v115, v113
	s_nop 0
	v_mov_b32_e32 v114, v115
	v_pk_mul_f32 v[108:109], v[108:109], v[114:115] op_sel_hi:[1,0]
	v_pk_mul_f32 v[116:117], v[106:107], v[114:115] op_sel_hi:[1,0]
	v_pk_mul_f32 v[106:107], v[104:105], v[114:115] op_sel_hi:[1,0]
	v_cvt_pk_bf16_f32 v104, v108, v109
	v_mad_i64_i32 v[108:109], s[0:1], v112, s10, v[120:121]
	v_pk_mul_f32 v[110:111], v[110:111], v[114:115] op_sel_hi:[1,0]
	v_lshl_add_u64 v[108:109], v[108:109], 0, v[122:123]
	v_cvt_pk_bf16_f32 v105, v110, v111
	v_cvt_pk_bf16_f32 v106, v106, v107
	v_cvt_pk_bf16_f32 v107, v116, v117
	global_store_dwordx4 v[108:109], v[104:107], off
	v_pk_mul_f32 v[100:101], v[100:101], v[114:115] op_sel_hi:[1,0]
	v_pk_mul_f32 v[102:103], v[102:103], v[114:115] op_sel_hi:[1,0]
	v_pk_mul_f32 v[104:105], v[98:99], v[114:115] op_sel_hi:[1,0]
	v_pk_mul_f32 v[98:99], v[96:97], v[114:115] op_sel_hi:[1,0]
	v_cvt_pk_bf16_f32 v96, v100, v101
	v_cvt_pk_bf16_f32 v97, v102, v103
	s_nop 0
	v_cvt_pk_bf16_f32 v98, v98, v99
	v_cvt_pk_bf16_f32 v99, v104, v105
	global_store_dwordx4 v[108:109], v[96:99], off offset:256
	s_nop 1
	v_or_b32_e32 v96, 32, v140
	v_ashrrev_i32_e32 v97, 31, v96
	v_lshl_add_u64 v[98:99], v[96:97], 2, s[46:47]
	s_nop 1
	v_mov_b32_e32 v97, v202
	v_fmamk_f32 v97, v97, 0x3b800000, v150
	v_rsq_f32_e32 v99, v97
	s_nop 0
	v_mov_b32_e32 v98, v99
	v_pk_mul_f32 v[92:93], v[92:93], v[98:99] op_sel_hi:[1,0]
	v_pk_mul_f32 v[100:101], v[90:91], v[98:99] op_sel_hi:[1,0]
	v_pk_mul_f32 v[90:91], v[88:89], v[98:99] op_sel_hi:[1,0]
	v_cvt_pk_bf16_f32 v88, v92, v93
	v_mad_i64_i32 v[92:93], s[0:1], v96, s10, v[120:121]
	v_pk_mul_f32 v[94:95], v[94:95], v[98:99] op_sel_hi:[1,0]
	v_lshl_add_u64 v[92:93], v[92:93], 0, v[122:123]
	v_cvt_pk_bf16_f32 v89, v94, v95
	v_cvt_pk_bf16_f32 v90, v90, v91
	v_cvt_pk_bf16_f32 v91, v100, v101
	global_store_dwordx4 v[92:93], v[88:91], off
	v_pk_mul_f32 v[84:85], v[84:85], v[98:99] op_sel_hi:[1,0]
	v_pk_mul_f32 v[86:87], v[86:87], v[98:99] op_sel_hi:[1,0]
	v_pk_mul_f32 v[88:89], v[82:83], v[98:99] op_sel_hi:[1,0]
	v_pk_mul_f32 v[82:83], v[80:81], v[98:99] op_sel_hi:[1,0]
	v_cvt_pk_bf16_f32 v80, v84, v85
	v_cvt_pk_bf16_f32 v81, v86, v87
	s_nop 0
	v_cvt_pk_bf16_f32 v82, v82, v83
	v_cvt_pk_bf16_f32 v83, v88, v89
	global_store_dwordx4 v[92:93], v[80:83], off offset:256
	s_nop 1
	v_or_b32_e32 v80, 48, v140
	v_ashrrev_i32_e32 v81, 31, v80
	v_lshl_add_u64 v[82:83], v[80:81], 2, s[46:47]
	s_nop 1
	v_mov_b32_e32 v81, v203
	v_fmamk_f32 v81, v81, 0x3b800000, v150
	v_rsq_f32_e32 v83, v81
	s_nop 0
	v_mov_b32_e32 v82, v83
	v_pk_mul_f32 v[76:77], v[76:77], v[82:83] op_sel_hi:[1,0]
	v_pk_mul_f32 v[84:85], v[74:75], v[82:83] op_sel_hi:[1,0]
	v_pk_mul_f32 v[74:75], v[72:73], v[82:83] op_sel_hi:[1,0]
	v_cvt_pk_bf16_f32 v72, v76, v77
	v_mad_i64_i32 v[76:77], s[0:1], v80, s10, v[120:121]
	v_pk_mul_f32 v[78:79], v[78:79], v[82:83] op_sel_hi:[1,0]
	v_lshl_add_u64 v[76:77], v[76:77], 0, v[122:123]
	v_cvt_pk_bf16_f32 v73, v78, v79
	v_cvt_pk_bf16_f32 v74, v74, v75
	v_cvt_pk_bf16_f32 v75, v84, v85
; __device__ __forceinline__ u32x4 pack8(f32x4 a, f32x4 b) { u32x4 o; o.x = cvt_pk(a.x, a.y); o.y = cvt_pk(a.z, a.w); o.z = cvt_pk(b.x, b.y); o.w = cvt_pk(b.z, b.w); return o; }
; __device__ __forceinline__ float rstd_of(const float* SS, int row, float invw) { return 1.0f / sqrtf(SS[row] * invw + EPS); }
;     __device__ __forceinline__ void operator()(const f32x4 (&acc)[2][2][4][2], const pg8::Unit& u, int wr, int wc, int fr, int fq) const {
;         const int row0 = u.pm * 256 + wr * 64 + fr, col0 = u.pn * 256 + wc * 32 + 8 * fq;
; #pragma unroll
;         for (int ai = 0; ai < 2; ++ai)
; #pragma unroll
;             for (int m = 0; m < 4; ++m) {
;                 const int row = row0 + ai * 128 + m * 16; const float r = rstd_of(SS, row, invw);
; #pragma unroll
;                 for (int bj = 0; bj < 2; ++bj)
;                     *(u32x4*)(O + (size_t)row * ldc + col0 + bj * 128) = pack8(acc[ai][bj][m][0] * r, acc[ai][bj][m][1] * r);
;             }
;     }
	global_store_dwordx4 v[76:77], v[72:75], off
	v_pk_mul_f32 v[70:71], v[70:71], v[82:83] op_sel_hi:[1,0]
	v_pk_mul_f32 v[68:69], v[68:69], v[82:83] op_sel_hi:[1,0]
	v_pk_mul_f32 v[72:73], v[66:67], v[82:83] op_sel_hi:[1,0]
	v_pk_mul_f32 v[66:67], v[64:65], v[82:83] op_sel_hi:[1,0]
	v_cvt_pk_bf16_f32 v64, v68, v69
	v_cvt_pk_bf16_f32 v65, v70, v71
	s_nop 0
	v_cvt_pk_bf16_f32 v66, v66, v67
	v_cvt_pk_bf16_f32 v67, v72, v73
	global_store_dwordx4 v[76:77], v[64:67], off offset:256
	s_nop 1
	s_nop 0
	v_add_u32_e32 v65, 0x80, v140
	v_mov_b32_e32 v64, v204
	v_fmamk_f32 v64, v64, 0x3b800000, v150
	v_rsq_f32_e32 v66, v64
	s_nop 0
	v_mov_b32_e32 v64, v66
	v_pk_mul_f32 v[60:61], v[60:61], v[64:65] op_sel_hi:[1,0]
	v_pk_mul_f32 v[66:67], v[58:59], v[64:65] op_sel_hi:[1,0]
	v_pk_mul_f32 v[58:59], v[56:57], v[64:65] op_sel_hi:[1,0]
	v_cvt_pk_bf16_f32 v56, v60, v61
	v_mad_i64_i32 v[60:61], s[0:1], v65, s10, v[120:121]
	v_pk_mul_f32 v[62:63], v[62:63], v[64:65] op_sel_hi:[1,0]
	v_lshl_add_u64 v[60:61], v[60:61], 0, v[122:123]
	v_cvt_pk_bf16_f32 v57, v62, v63
	v_cvt_pk_bf16_f32 v58, v58, v59
	v_cvt_pk_bf16_f32 v59, v66, v67
	global_store_dwordx4 v[60:61], v[56:59], off
	v_pk_mul_f32 v[54:55], v[54:55], v[64:65] op_sel_hi:[1,0]
	v_pk_mul_f32 v[52:53], v[52:53], v[64:65] op_sel_hi:[1,0]
	v_pk_mul_f32 v[56:57], v[50:51], v[64:65] op_sel_hi:[1,0]
	v_pk_mul_f32 v[50:51], v[48:49], v[64:65] op_sel_hi:[1,0]
	v_cvt_pk_bf16_f32 v48, v52, v53
	v_cvt_pk_bf16_f32 v49, v54, v55
	s_nop 0
	v_cvt_pk_bf16_f32 v50, v50, v51
	v_cvt_pk_bf16_f32 v51, v56, v57
	global_store_dwordx4 v[60:61], v[48:51], off offset:256
	s_nop 1
	s_nop 0
	v_add_u32_e32 v49, 0x90, v140
	v_mov_b32_e32 v48, v205
	v_fmamk_f32 v48, v48, 0x3b800000, v150
	v_rsq_f32_e32 v50, v48
	s_nop 0
	v_mov_b32_e32 v48, v50
	v_pk_mul_f32 v[44:45], v[44:45], v[48:49] op_sel_hi:[1,0]
	v_pk_mul_f32 v[50:51], v[42:43], v[48:49] op_sel_hi:[1,0]
	v_pk_mul_f32 v[42:43], v[40:41], v[48:49] op_sel_hi:[1,0]
	v_cvt_pk_bf16_f32 v40, v44, v45
	v_mad_i64_i32 v[44:45], s[0:1], v49, s10, v[120:121]
	v_pk_mul_f32 v[46:47], v[46:47], v[48:49] op_sel_hi:[1,0]
	v_lshl_add_u64 v[44:45], v[44:45], 0, v[122:123]
	v_cvt_pk_bf16_f32 v41, v46, v47
	v_cvt_pk_bf16_f32 v42, v42, v43
	v_cvt_pk_bf16_f32 v43, v50, v51
	global_store_dwordx4 v[44:45], v[40:43], off
	v_pk_mul_f32 v[38:39], v[38:39], v[48:49] op_sel_hi:[1,0]
	v_pk_mul_f32 v[36:37], v[36:37], v[48:49] op_sel_hi:[1,0]
	v_pk_mul_f32 v[40:41], v[34:35], v[48:49] op_sel_hi:[1,0]
	v_pk_mul_f32 v[34:35], v[32:33], v[48:49] op_sel_hi:[1,0]
	v_cvt_pk_bf16_f32 v32, v36, v37
	v_cvt_pk_bf16_f32 v33, v38, v39
	s_nop 0
	v_cvt_pk_bf16_f32 v34, v34, v35
	v_cvt_pk_bf16_f32 v35, v40, v41
	global_store_dwordx4 v[44:45], v[32:35], off offset:256
	s_nop 1
	s_nop 0
	v_add_u32_e32 v33, 0xa0, v140
	v_mov_b32_e32 v32, v206
	v_fmamk_f32 v32, v32, 0x3b800000, v150
	v_rsq_f32_e32 v34, v32
	s_nop 0
	v_mov_b32_e32 v32, v34
	v_pk_mul_f32 v[28:29], v[28:29], v[32:33] op_sel_hi:[1,0]
	v_pk_mul_f32 v[34:35], v[26:27], v[32:33] op_sel_hi:[1,0]
	v_pk_mul_f32 v[26:27], v[24:25], v[32:33] op_sel_hi:[1,0]
	v_cvt_pk_bf16_f32 v24, v28, v29
	v_mad_i64_i32 v[28:29], s[0:1], v33, s10, v[120:121]
	v_pk_mul_f32 v[30:31], v[30:31], v[32:33] op_sel_hi:[1,0]
	v_lshl_add_u64 v[28:29], v[28:29], 0, v[122:123]
	v_cvt_pk_bf16_f32 v25, v30, v31
	v_cvt_pk_bf16_f32 v26, v26, v27
	v_cvt_pk_bf16_f32 v27, v34, v35
	global_store_dwordx4 v[28:29], v[24:27], off
	v_pk_mul_f32 v[22:23], v[22:23], v[32:33] op_sel_hi:[1,0]
	v_pk_mul_f32 v[20:21], v[20:21], v[32:33] op_sel_hi:[1,0]
	v_pk_mul_f32 v[24:25], v[18:19], v[32:33] op_sel_hi:[1,0]
	v_pk_mul_f32 v[18:19], v[16:17], v[32:33] op_sel_hi:[1,0]
	v_cvt_pk_bf16_f32 v16, v20, v21
	v_cvt_pk_bf16_f32 v17, v22, v23
	s_nop 0
	v_cvt_pk_bf16_f32 v18, v18, v19
	v_cvt_pk_bf16_f32 v19, v24, v25
	global_store_dwordx4 v[28:29], v[16:19], off offset:256
	s_nop 1
	s_nop 0
	v_add_u32_e32 v17, 0xb0, v140
	v_mov_b32_e32 v16, v207
	v_fmamk_f32 v16, v16, 0x3b800000, v150
	v_rsq_f32_e32 v18, v16
	s_nop 0
	v_mov_b32_e32 v16, v18
	v_pk_mul_f32 v[12:13], v[12:13], v[16:17] op_sel_hi:[1,0]
	v_pk_mul_f32 v[18:19], v[10:11], v[16:17] op_sel_hi:[1,0]
	v_pk_mul_f32 v[10:11], v[8:9], v[16:17] op_sel_hi:[1,0]
	v_cvt_pk_bf16_f32 v8, v12, v13
	v_mad_i64_i32 v[12:13], s[0:1], v17, s10, v[120:121]
	v_pk_mul_f32 v[14:15], v[14:15], v[16:17] op_sel_hi:[1,0]
	v_lshl_add_u64 v[12:13], v[12:13], 0, v[122:123]
	v_cvt_pk_bf16_f32 v9, v14, v15
	v_cvt_pk_bf16_f32 v10, v10, v11
	v_cvt_pk_bf16_f32 v11, v18, v19
	global_store_dwordx4 v[12:13], v[8:11], off
	s_mov_b64 s[0:1], -1
	s_andn2_b64 vcc, exec, s[38:39]
	v_pk_mul_f32 v[8:9], v[2:3], v[16:17] op_sel_hi:[1,0]
	v_pk_mul_f32 v[2:3], v[0:1], v[16:17] op_sel_hi:[1,0]
	v_pk_mul_f32 v[6:7], v[6:7], v[16:17] op_sel_hi:[1,0]
	v_pk_mul_f32 v[4:5], v[4:5], v[16:17] op_sel_hi:[1,0]
	s_nop 0
	v_cvt_pk_bf16_f32 v0, v4, v5
	v_cvt_pk_bf16_f32 v1, v6, v7
	v_cvt_pk_bf16_f32 v2, v2, v3
	v_cvt_pk_bf16_f32 v3, v8, v9
	global_store_dwordx4 v[12:13], v[0:3], off offset:256
	s_cbranch_vccnz .LBB0_468
	s_andn2_b64 vcc, exec, s[30:31]
	s_cbranch_vccnz .LBB0_467
	s_barrier
	s_branch .LBB0_467

; __device__ __forceinline__ u32x4 pack8(f32x4 a, f32x4 b) { u32x4 o; o.x = cvt_pk(a.x, a.y); o.y = cvt_pk(a.z, a.w); o.z = cvt_pk(b.x, b.y); o.w = cvt_pk(b.z, b.w); return o; }
; __device__ __forceinline__ float rstd_of(const float* SS, int row, float invw) { return 1.0f / sqrtf(SS[row] * invw + EPS); }
;     __device__ __forceinline__ void operator()(const f32x4 (&acc)[2][2][4][2], const pg8::Unit& u, int wr, int wc, int fr, int fq) const {
;         const int row0 = u.pm * 256 + wr * 64 + fr, col0 = u.pn * 256 + wc * 32 + 8 * fq;
; #pragma unroll
;         for (int ai = 0; ai < 2; ++ai)
; #pragma unroll
;             for (int m = 0; m < 4; ++m) {
;                 const int row = row0 + ai * 128 + m * 16; const float r = rstd_of(SS, row, invw);
; #pragma unroll
;                 for (int bj = 0; bj < 2; ++bj)
;                     *(u32x4*)(O + (size_t)row * ldc + col0 + bj * 128) = pack8(acc[ai][bj][m][0] * r, acc[ai][bj][m][1] * r);
;             }
;     }
.LBB0_493:
	v_lshl_add_u32 v142, s0, 8, v144
	v_ashrrev_i32_e32 v143, 31, v142
	v_lshl_add_u64 v[140:141], v[142:143], 2, s[44:45]
	global_load_dword v200, v[140:141], off
	global_load_dword v201, v[140:141], off offset:64
	global_load_dword v202, v[140:141], off offset:128
	global_load_dword v203, v[140:141], off offset:192
	global_load_dword v204, v[140:141], off offset:512
	global_load_dword v205, v[140:141], off offset:576
	global_load_dword v206, v[140:141], off offset:640
	global_load_dword v207, v[140:141], off offset:704
	v_lshl_or_b32 v152, s1, 8, v146
	v_ashrrev_i32_e32 v153, 31, v152
	s_waitcnt vmcnt(0)
	v_mov_b32_e32 v154, v200
	v_fmamk_f32 v154, v154, 0x3c000000, v150
	v_rsq_f32_e32 v155, v154
	s_nop 0
	v_mov_b32_e32 v154, v155
	v_pk_mul_f32 v[112:113], v[112:113], v[154:155] op_sel_hi:[1,0]
	v_pk_mul_f32 v[114:115], v[114:115], v[154:155] op_sel_hi:[1,0]
	v_pk_mul_f32 v[156:157], v[118:119], v[154:155] op_sel_hi:[1,0]
	v_pk_mul_f32 v[118:119], v[116:117], v[154:155] op_sel_hi:[1,0]
	v_cvt_pk_bf16_f32 v116, v112, v113
	v_lshlrev_b64 v[112:113], 11, v[142:143]
	v_cvt_pk_bf16_f32 v117, v114, v115
	v_lshl_add_u64 v[112:113], s[12:13], 0, v[112:113]
	v_lshlrev_b64 v[114:115], 1, v[152:153]
	v_lshl_add_u64 v[112:113], v[112:113], 0, v[114:115]
	v_cvt_pk_bf16_f32 v118, v118, v119
	v_cvt_pk_bf16_f32 v119, v156, v157
	global_store_dwordx4 v[112:113], v[116:119], off
	s_nop 1
	v_pk_mul_f32 v[116:117], v[120:121], v[154:155] op_sel_hi:[1,0]
	v_pk_mul_f32 v[118:119], v[122:123], v[154:155] op_sel_hi:[1,0]
	v_cvt_pk_bf16_f32 v116, v116, v117
	v_pk_mul_f32 v[120:121], v[126:127], v[154:155] op_sel_hi:[1,0]
	v_pk_mul_f32 v[122:123], v[124:125], v[154:155] op_sel_hi:[1,0]
	v_cvt_pk_bf16_f32 v117, v118, v119
	s_nop 0
	v_cvt_pk_bf16_f32 v118, v122, v123
	v_cvt_pk_bf16_f32 v119, v120, v121
	global_store_dwordx4 v[112:113], v[116:119], off offset:256
	s_nop 1
	v_or_b32_e32 v116, 16, v142
	v_ashrrev_i32_e32 v117, 31, v116
	v_lshl_add_u64 v[118:119], v[116:117], 2, s[44:45]
	s_nop 1
	v_mov_b32_e32 v118, v201
	v_fmamk_f32 v118, v118, 0x3c000000, v150
	v_rsq_f32_e32 v119, v118
	s_nop 0
	v_mov_b32_e32 v118, v119
	v_pk_mul_f32 v[98:99], v[98:99], v[118:119] op_sel_hi:[1,0]
	v_pk_mul_f32 v[96:97], v[96:97], v[118:119] op_sel_hi:[1,0]
	v_pk_mul_f32 v[100:101], v[100:101], v[118:119] op_sel_hi:[1,0]
	v_cvt_pk_bf16_f32 v96, v96, v97
	v_cvt_pk_bf16_f32 v97, v98, v99
	v_pk_mul_f32 v[102:103], v[102:103], v[118:119] op_sel_hi:[1,0]
	v_cvt_pk_bf16_f32 v98, v100, v101
	v_lshlrev_b64 v[100:101], 11, v[116:117]
	v_lshl_add_u64 v[100:101], s[12:13], 0, v[100:101]
	v_lshl_add_u64 v[100:101], v[100:101], 0, v[114:115]
	v_cvt_pk_bf16_f32 v99, v102, v103
	global_store_dwordx4 v[100:101], v[96:99], off
	v_pk_mul_f32 v[102:103], v[110:111], v[118:119] op_sel_hi:[1,0]
	s_nop 0
	v_pk_mul_f32 v[96:97], v[104:105], v[118:119] op_sel_hi:[1,0]
	v_pk_mul_f32 v[98:99], v[106:107], v[118:119] op_sel_hi:[1,0]
	v_cvt_pk_bf16_f32 v96, v96, v97
	v_pk_mul_f32 v[104:105], v[108:109], v[118:119] op_sel_hi:[1,0]
	v_cvt_pk_bf16_f32 v97, v98, v99
	s_nop 0
	v_cvt_pk_bf16_f32 v98, v104, v105
	v_cvt_pk_bf16_f32 v99, v102, v103
	global_store_dwordx4 v[100:101], v[96:99], off offset:256
	s_nop 1
	v_or_b32_e32 v96, 32, v142
	v_ashrrev_i32_e32 v97, 31, v96
	v_lshl_add_u64 v[98:99], v[96:97], 2, s[44:45]
	s_nop 1
	v_mov_b32_e32 v98, v202
	v_fmamk_f32 v98, v98, 0x3c000000, v150
	v_rsq_f32_e32 v99, v98
	s_nop 0
	v_mov_b32_e32 v98, v99
	v_pk_mul_f32 v[82:83], v[82:83], v[98:99] op_sel_hi:[1,0]
	v_pk_mul_f32 v[80:81], v[80:81], v[98:99] op_sel_hi:[1,0]
	v_pk_mul_f32 v[84:85], v[84:85], v[98:99] op_sel_hi:[1,0]
	v_cvt_pk_bf16_f32 v80, v80, v81
	v_cvt_pk_bf16_f32 v81, v82, v83
	v_pk_mul_f32 v[86:87], v[86:87], v[98:99] op_sel_hi:[1,0]
	v_cvt_pk_bf16_f32 v82, v84, v85
	v_lshlrev_b64 v[84:85], 11, v[96:97]
	v_lshl_add_u64 v[84:85], s[12:13], 0, v[84:85]
	v_lshl_add_u64 v[84:85], v[84:85], 0, v[114:115]
	v_cvt_pk_bf16_f32 v83, v86, v87
	global_store_dwordx4 v[84:85], v[80:83], off
	v_pk_mul_f32 v[86:87], v[94:95], v[98:99] op_sel_hi:[1,0]
	s_nop 0
	v_pk_mul_f32 v[80:81], v[88:89], v[98:99] op_sel_hi:[1,0]
	v_pk_mul_f32 v[82:83], v[90:91], v[98:99] op_sel_hi:[1,0]
	v_cvt_pk_bf16_f32 v80, v80, v81
	v_pk_mul_f32 v[88:89], v[92:93], v[98:99] op_sel_hi:[1,0]
	v_cvt_pk_bf16_f32 v81, v82, v83
	s_nop 0
	v_cvt_pk_bf16_f32 v82, v88, v89
	v_cvt_pk_bf16_f32 v83, v86, v87
	global_store_dwordx4 v[84:85], v[80:83], off offset:256
	s_nop 1
	v_or_b32_e32 v80, 48, v142
	v_ashrrev_i32_e32 v81, 31, v80
	v_lshl_add_u64 v[82:83], v[80:81], 2, s[44:45]
	s_nop 1
	v_mov_b32_e32 v82, v203
	v_fmamk_f32 v82, v82, 0x3c000000, v150
	v_rsq_f32_e32 v83, v82
	s_nop 0
	v_mov_b32_e32 v82, v83
	v_pk_mul_f32 v[74:75], v[74:75], v[82:83] op_sel_hi:[1,0]
	v_pk_mul_f32 v[72:73], v[72:73], v[82:83] op_sel_hi:[1,0]
	v_pk_mul_f32 v[76:77], v[76:77], v[82:83] op_sel_hi:[1,0]
	v_cvt_pk_bf16_f32 v72, v72, v73
	v_cvt_pk_bf16_f32 v73, v74, v75
	v_pk_mul_f32 v[78:79], v[78:79], v[82:83] op_sel_hi:[1,0]
	v_cvt_pk_bf16_f32 v74, v76, v77
	v_lshlrev_b64 v[76:77], 11, v[80:81]
	v_lshl_add_u64 v[76:77], s[12:13], 0, v[76:77]
	v_lshl_add_u64 v[76:77], v[76:77], 0, v[114:115]
	v_cvt_pk_bf16_f32 v75, v78, v79
	global_store_dwordx4 v[76:77], v[72:75], off
; __device__ __forceinline__ u32x4 pack8(f32x4 a, f32x4 b) { u32x4 o; o.x = cvt_pk(a.x, a.y); o.y = cvt_pk(a.z, a.w); o.z = cvt_pk(b.x, b.y); o.w = cvt_pk(b.z, b.w); return o; }
; __device__ __forceinline__ float rstd_of(const float* SS, int row, float invw) { return 1.0f / sqrtf(SS[row] * invw + EPS); }
;     __device__ __forceinline__ void operator()(const f32x4 (&acc)[2][2][4][2], const pg8::Unit& u, int wr, int wc, int fr, int fq) const {
;         const int row0 = u.pm * 256 + wr * 64 + fr, col0 = u.pn * 256 + wc * 32 + 8 * fq;
; #pragma unroll
;         for (int ai = 0; ai < 2; ++ai)
; #pragma unroll
;             for (int m = 0; m < 4; ++m) {
;                 const int row = row0 + ai * 128 + m * 16; const float r = rstd_of(SS, row, invw);
; #pragma unroll
;                 for (int bj = 0; bj < 2; ++bj)
;                     *(u32x4*)(O + (size_t)row * ldc + col0 + bj * 128) = pack8(acc[ai][bj][m][0] * r, acc[ai][bj][m][1] * r);
;             }
;     }
	v_pk_mul_f32 v[70:71], v[70:71], v[82:83] op_sel_hi:[1,0]
	v_pk_mul_f32 v[68:69], v[68:69], v[82:83] op_sel_hi:[1,0]
	v_pk_mul_f32 v[72:73], v[66:67], v[82:83] op_sel_hi:[1,0]
	v_pk_mul_f32 v[66:67], v[64:65], v[82:83] op_sel_hi:[1,0]
	v_cvt_pk_bf16_f32 v64, v68, v69
	v_cvt_pk_bf16_f32 v65, v70, v71
	s_nop 0
	v_cvt_pk_bf16_f32 v66, v66, v67
	v_cvt_pk_bf16_f32 v67, v72, v73
	global_store_dwordx4 v[76:77], v[64:67], off offset:256
	s_nop 1
	v_mov_b32_e32 v64, v204
	v_fmamk_f32 v64, v64, 0x3c000000, v150
	v_rsq_f32_e32 v65, v64
	s_nop 0
	s_mov_b64 s[0:1], 0x40000
	v_mov_b32_e32 v64, v65
	v_pk_mul_f32 v[56:57], v[56:57], v[64:65] op_sel_hi:[1,0]
	v_pk_mul_f32 v[66:67], v[58:59], v[64:65] op_sel_hi:[1,0]
	v_pk_mul_f32 v[62:63], v[62:63], v[64:65] op_sel_hi:[1,0]
	v_pk_mul_f32 v[60:61], v[60:61], v[64:65] op_sel_hi:[1,0]
	v_cvt_pk_bf16_f32 v58, v56, v57
	v_lshl_add_u64 v[56:57], v[112:113], 0, s[0:1]
	s_mov_b32 s0, 0x40000
	v_cvt_pk_bf16_f32 v59, v66, v67
	v_cvt_pk_bf16_f32 v60, v60, v61
	v_cvt_pk_bf16_f32 v61, v62, v63
	v_add_co_u32_e32 v62, vcc, s0, v112
	v_pk_mul_f32 v[54:55], v[54:55], v[64:65] op_sel_hi:[1,0]
	s_nop 0
	v_addc_co_u32_e32 v63, vcc, 0, v113, vcc
	global_store_dwordx4 v[62:63], v[58:61], off
	v_pk_mul_f32 v[52:53], v[52:53], v[64:65] op_sel_hi:[1,0]
	s_nop 0
	v_pk_mul_f32 v[58:59], v[50:51], v[64:65] op_sel_hi:[1,0]
	v_pk_mul_f32 v[50:51], v[48:49], v[64:65] op_sel_hi:[1,0]
	v_cvt_pk_bf16_f32 v48, v52, v53
	v_cvt_pk_bf16_f32 v49, v54, v55
	s_nop 0
	v_cvt_pk_bf16_f32 v50, v50, v51
	v_cvt_pk_bf16_f32 v51, v58, v59
	global_store_dwordx4 v[56:57], v[48:51], off offset:256
	s_nop 1
	v_mov_b32_e32 v48, v205
	v_fmamk_f32 v48, v48, 0x3c000000, v150
	v_rsq_f32_e32 v49, v48
	s_nop 0
	s_mov_b64 s[0:1], 0x48000
	v_mov_b32_e32 v48, v49
	v_pk_mul_f32 v[40:41], v[40:41], v[48:49] op_sel_hi:[1,0]
	v_pk_mul_f32 v[50:51], v[42:43], v[48:49] op_sel_hi:[1,0]
	v_pk_mul_f32 v[46:47], v[46:47], v[48:49] op_sel_hi:[1,0]
	v_pk_mul_f32 v[44:45], v[44:45], v[48:49] op_sel_hi:[1,0]
	v_cvt_pk_bf16_f32 v42, v40, v41
	v_lshl_add_u64 v[40:41], v[112:113], 0, s[0:1]
	s_mov_b32 s0, 0x48000
	v_cvt_pk_bf16_f32 v43, v50, v51
	v_cvt_pk_bf16_f32 v44, v44, v45
	v_cvt_pk_bf16_f32 v45, v46, v47
	v_add_co_u32_e32 v46, vcc, s0, v112
	v_pk_mul_f32 v[38:39], v[38:39], v[48:49] op_sel_hi:[1,0]
	s_nop 0
	v_addc_co_u32_e32 v47, vcc, 0, v113, vcc
	global_store_dwordx4 v[46:47], v[42:45], off
	v_pk_mul_f32 v[36:37], v[36:37], v[48:49] op_sel_hi:[1,0]
	s_nop 0
	v_pk_mul_f32 v[42:43], v[34:35], v[48:49] op_sel_hi:[1,0]
	v_pk_mul_f32 v[34:35], v[32:33], v[48:49] op_sel_hi:[1,0]
	v_cvt_pk_bf16_f32 v32, v36, v37
	v_cvt_pk_bf16_f32 v33, v38, v39
	s_nop 0
	v_cvt_pk_bf16_f32 v34, v34, v35
	v_cvt_pk_bf16_f32 v35, v42, v43
	global_store_dwordx4 v[40:41], v[32:35], off offset:256
	s_nop 1
	v_mov_b32_e32 v32, v206
	v_fmamk_f32 v32, v32, 0x3c000000, v150
	v_rsq_f32_e32 v33, v32
	s_nop 0
	s_mov_b64 s[0:1], 0x50000
	v_mov_b32_e32 v32, v33
	v_pk_mul_f32 v[24:25], v[24:25], v[32:33] op_sel_hi:[1,0]
	v_pk_mul_f32 v[34:35], v[26:27], v[32:33] op_sel_hi:[1,0]
	v_pk_mul_f32 v[30:31], v[30:31], v[32:33] op_sel_hi:[1,0]
	v_pk_mul_f32 v[28:29], v[28:29], v[32:33] op_sel_hi:[1,0]
	v_cvt_pk_bf16_f32 v26, v24, v25
	v_lshl_add_u64 v[24:25], v[112:113], 0, s[0:1]
	s_mov_b32 s0, 0x50000
	v_cvt_pk_bf16_f32 v27, v34, v35
	v_cvt_pk_bf16_f32 v28, v28, v29
	v_cvt_pk_bf16_f32 v29, v30, v31
	v_add_co_u32_e32 v30, vcc, s0, v112
	v_pk_mul_f32 v[22:23], v[22:23], v[32:33] op_sel_hi:[1,0]
	s_nop 0
	v_addc_co_u32_e32 v31, vcc, 0, v113, vcc
	global_store_dwordx4 v[30:31], v[26:29], off
	v_pk_mul_f32 v[20:21], v[20:21], v[32:33] op_sel_hi:[1,0]
	s_nop 0
	v_pk_mul_f32 v[26:27], v[18:19], v[32:33] op_sel_hi:[1,0]
	v_pk_mul_f32 v[18:19], v[16:17], v[32:33] op_sel_hi:[1,0]
	v_cvt_pk_bf16_f32 v16, v20, v21
	v_cvt_pk_bf16_f32 v17, v22, v23
	s_nop 0
	v_cvt_pk_bf16_f32 v18, v18, v19
	v_cvt_pk_bf16_f32 v19, v26, v27
	global_store_dwordx4 v[24:25], v[16:19], off offset:256
	s_nop 1
	v_mov_b32_e32 v16, v207
	v_fmamk_f32 v16, v16, 0x3c000000, v150
	v_rsq_f32_e32 v17, v16
	s_nop 0
	s_mov_b64 s[0:1], 0x58000
	v_mov_b32_e32 v16, v17
	v_pk_mul_f32 v[10:11], v[10:11], v[16:17] op_sel_hi:[1,0]
	v_pk_mul_f32 v[8:9], v[8:9], v[16:17] op_sel_hi:[1,0]
	v_pk_mul_f32 v[12:13], v[12:13], v[16:17] op_sel_hi:[1,0]
	v_pk_mul_f32 v[14:15], v[14:15], v[16:17] op_sel_hi:[1,0]
	v_cvt_pk_bf16_f32 v8, v8, v9
	v_cvt_pk_bf16_f32 v9, v10, v11
	v_cvt_pk_bf16_f32 v10, v12, v13
	v_lshl_add_u64 v[12:13], v[112:113], 0, s[0:1]
	s_mov_b32 s0, 0x58000
	v_cvt_pk_bf16_f32 v11, v14, v15
	v_add_co_u32_e32 v14, vcc, s0, v112
	v_pk_mul_f32 v[2:3], v[2:3], v[16:17] op_sel_hi:[1,0]
	s_nop 0
	v_addc_co_u32_e32 v15, vcc, 0, v113, vcc
	v_pk_mul_f32 v[0:1], v[0:1], v[16:17] op_sel_hi:[1,0]
	s_mov_b64 s[0:1], -1
	s_andn2_b64 vcc, exec, s[38:39]
	global_store_dwordx4 v[14:15], v[8:11], off
	v_pk_mul_f32 v[6:7], v[6:7], v[16:17] op_sel_hi:[1,0]
	v_pk_mul_f32 v[4:5], v[4:5], v[16:17] op_sel_hi:[1,0]
	v_cvt_pk_bf16_f32 v0, v0, v1
	v_cvt_pk_bf16_f32 v1, v2, v3
	s_nop 0
	v_cvt_pk_bf16_f32 v2, v4, v5
	v_cvt_pk_bf16_f32 v3, v6, v7
	global_store_dwordx4 v[12:13], v[0:3], off offset:256
	s_cbranch_vccnz .LBB0_484
	s_andn2_b64 vcc, exec, s[30:31]
	s_cbranch_vccnz .LBB0_483
	s_barrier
	s_branch .LBB0_483

; __device__ __forceinline__ float sq4(f32x4 a) { return (a.x * a.x + a.y * a.y) + (a.z * a.z + a.w * a.w); }
; __device__ __forceinline__ void finalize_phase(const Params& p, LAS unsigned char* lds, int G) {
;     ...
;     for (int rowb = gw; rowb < M; rowb += 8 * NGW) {
;         u32x4 kn8[8]; f32x2 kx1[8], kx2[8], csv[8], snv[8];
; #pragma unroll
;         for (int k = 0; k < 8; ++k) {
;             const int row = (rowb + k * NGW < M) ? rowb + k * NGW : rowb;
;             const bf16_t* kk = KVRAW + (size_t)row * 1024 + h * 128;
;             kn8[k] = *(const u32x4*)(kk + 8 * sub);
;             kx1[k] = *(const f32x2*)(KR + (size_t)row * 32 + 2 * sub); kx2[k] = *(const f32x2*)(KR + (size_t)row * 32 + 16 + 2 * sub);
;             csv[k] = *(const f32x2*)(COS + (size_t)row * 16 + 2 * sub); snv[k] = *(const f32x2*)(SIN + (size_t)row * 16 + 2 * sub);
;         }
; #pragma unroll
;         for (int k = 0; k < 8; ++k) {
;             const int row = rowb + k * NGW;
;             if (row < M) {
;                 const int b = row >> 12, s = row & 4095;
;                 const f32x2 cs = csv[k], sn = snv[k];
;                 const size_t orow = ((size_t)(b * 8 + h) * SEQ + s) * 96;
;                 {
;                     const u32x4 n8 = kn8[k];
;                     f32x4 a0 = {bflo(n8.x), bfhi(n8.x), bflo(n8.y), bfhi(n8.y)}, a1 = {bflo(n8.z), bfhi(n8.z), bflo(n8.w), bfhi(n8.w)};
;                     f32x2 x1 = kx1[k], x2 = kx2[k];
;                     float ss = sq4(a0) + sq4(a1) + (x1.x * x1.x + x1.y * x1.y) + (x2.x * x2.x + x2.y * x2.y);
;                     ss += __shfl_xor(ss, 1); ss += __shfl_xor(ss, 2); ss += __shfl_xor(ss, 4);
.LBB0_555:
	v_add_u32_e32 v129, s5, v38
	v_cmp_gt_i32_e64 s[50:51], s4, v129
	v_add_u32_e32 v128, s6, v38
	v_cmp_gt_i32_e64 s[48:49], s4, v128
	s_waitcnt vmcnt(0)
	v_cndmask_b32_e64 v8, v38, v129, s[50:51]
	v_ashrrev_i32_e32 v9, 31, v8
	v_lshlrev_b64 v[10:11], 11, v[8:9]
	v_lshl_add_u64 v[10:11], v[46:47], 0, v[10:11]
	v_lshlrev_b64 v[12:13], 7, v[8:9]
	v_lshlrev_b64 v[8:9], 6, v[8:9]
	v_lshl_add_u64 v[12:13], v[52:53], 0, v[12:13]
	global_load_dwordx4 v[32:35], v[10:11], off
	global_load_dwordx2 v[110:111], v[12:13], off
	v_lshl_add_u64 v[10:11], v[48:49], 0, v[8:9]
	v_lshl_add_u64 v[8:9], v[50:51], 0, v[8:9]
	global_load_dwordx2 v[116:117], v[12:13], off offset:64
	global_load_dwordx2 v[112:113], v[10:11], off
	global_load_dwordx2 v[114:115], v[8:9], off
	v_cndmask_b32_e64 v8, v38, v128, s[48:49]
	v_ashrrev_i32_e32 v9, 31, v8
	s_mul_i32 s0, s3, 24
	v_lshlrev_b64 v[10:11], 11, v[8:9]
	v_lshlrev_b64 v[12:13], 7, v[8:9]
	v_add_u32_e32 v127, s0, v38
	v_lshl_add_u64 v[10:11], v[46:47], 0, v[10:11]
	v_lshl_add_u64 v[12:13], v[52:53], 0, v[12:13]
	v_lshlrev_b64 v[8:9], 6, v[8:9]
	v_cmp_gt_i32_e64 s[46:47], s4, v127
	global_load_dwordx4 v[28:31], v[10:11], off
	global_load_dwordx2 v[102:103], v[12:13], off
	v_lshl_add_u64 v[10:11], v[48:49], 0, v[8:9]
	v_lshl_add_u64 v[8:9], v[50:51], 0, v[8:9]
	global_load_dwordx2 v[108:109], v[12:13], off offset:64
	global_load_dwordx2 v[104:105], v[10:11], off
	global_load_dwordx2 v[106:107], v[8:9], off
	v_cndmask_b32_e64 v12, v38, v127, s[46:47]
	v_ashrrev_i32_e32 v13, 31, v12
	v_lshlrev_b64 v[8:9], 11, v[12:13]
	v_lshl_add_u64 v[14:15], v[46:47], 0, v[8:9]
	v_lshl_add_u64 v[8:9], s[92:93], 0, v[54:55]
	global_load_dwordx4 v[8:11], v[8:9], off
	v_lshl_add_u64 v[62:63], s[92:93], 0, v[58:59]
	s_mov_b32 s0, 0x2a00000
	v_add_co_u32_e32 v18, vcc, s0, v62
	v_lshl_add_u64 v[20:21], s[92:93], 0, v[56:57]
	s_nop 0
	v_addc_co_u32_e32 v19, vcc, 0, v63, vcc
	s_mov_b32 s0, 0x1f000000
	v_lshlrev_b64 v[16:17], 7, v[12:13]
	v_add_co_u32_e32 v20, vcc, s0, v20
	v_lshl_add_u64 v[16:17], v[52:53], 0, v[16:17]
	s_nop 0
	v_addc_co_u32_e32 v21, vcc, 0, v21, vcc
	global_load_dwordx2 v[130:131], v[18:19], off
	global_load_dwordx2 v[132:133], v[20:21], off offset:64
	global_load_dwordx2 v[134:135], v[20:21], off
	global_load_dwordx4 v[24:27], v[14:15], off
	global_load_dwordx2 v[96:97], v[16:17], off
	v_lshlrev_b64 v[12:13], 6, v[12:13]
	v_add_u32_e32 v126, s7, v38
	v_lshl_add_u64 v[14:15], v[48:49], 0, v[12:13]
	v_lshl_add_u64 v[12:13], v[50:51], 0, v[12:13]
	v_cmp_gt_i32_e64 s[44:45], s4, v126
	global_load_dwordx2 v[100:101], v[16:17], off offset:64
	global_load_dwordx2 v[94:95], v[14:15], off
	global_load_dwordx2 v[98:99], v[12:13], off
	v_cndmask_b32_e64 v12, v38, v126, s[44:45]
	v_ashrrev_i32_e32 v13, 31, v12
	v_lshlrev_b64 v[14:15], 11, v[12:13]
	s_mul_i32 s0, s3, 40
	v_lshl_add_u64 v[14:15], v[46:47], 0, v[14:15]
	v_lshlrev_b64 v[16:17], 7, v[12:13]
	v_lshlrev_b64 v[12:13], 6, v[12:13]
	v_add_u32_e32 v125, s0, v38
	v_lshl_add_u64 v[16:17], v[52:53], 0, v[16:17]
	global_load_dwordx4 v[20:23], v[14:15], off
	global_load_dwordx2 v[88:89], v[16:17], off
	v_lshl_add_u64 v[14:15], v[48:49], 0, v[12:13]
	v_lshl_add_u64 v[12:13], v[50:51], 0, v[12:13]
	v_cmp_gt_i32_e64 s[42:43], s4, v125
	global_load_dwordx2 v[92:93], v[16:17], off offset:64
	global_load_dwordx2 v[86:87], v[14:15], off
	global_load_dwordx2 v[90:91], v[12:13], off
	v_cndmask_b32_e64 v12, v38, v125, s[42:43]
	s_mul_i32 s0, s3, 48
	v_ashrrev_i32_e32 v13, 31, v12
	v_add_u32_e32 v124, s0, v38
	s_mul_i32 s0, s3, 56
	v_lshlrev_b64 v[14:15], 11, v[12:13]
	v_cmp_gt_i32_e64 s[40:41], s4, v124
	v_add_u32_e32 v123, s0, v38
	v_lshl_add_u64 v[14:15], v[46:47], 0, v[14:15]
	v_lshlrev_b64 v[16:17], 7, v[12:13]
	v_lshlrev_b64 v[12:13], 6, v[12:13]
	v_cndmask_b32_e64 v68, v38, v124, s[40:41]
	v_cmp_gt_i32_e64 s[38:39], s4, v123
	v_lshl_add_u64 v[64:65], v[52:53], 0, v[16:17]
	global_load_dwordx4 v[16:19], v[14:15], off
	global_load_dwordx2 v[80:81], v[64:65], off
	v_lshl_add_u64 v[14:15], v[48:49], 0, v[12:13]
	v_ashrrev_i32_e32 v69, 31, v68
	v_cndmask_b32_e64 v136, v38, v123, s[38:39]
	v_lshl_add_u64 v[12:13], v[50:51], 0, v[12:13]
	global_load_dwordx2 v[84:85], v[64:65], off offset:64
	global_load_dwordx2 v[78:79], v[14:15], off
	global_load_dwordx2 v[82:83], v[12:13], off
	v_lshlrev_b64 v[14:15], 7, v[68:69]
	v_ashrrev_i32_e32 v137, 31, v136
	v_lshl_add_u64 v[72:73], v[52:53], 0, v[14:15]
	v_lshlrev_b64 v[14:15], 7, v[136:137]
	v_lshl_add_u64 v[138:139], v[52:53], 0, v[14:15]
	v_lshlrev_b64 v[14:15], 6, v[136:137]
	s_mov_b32 s0, 0x2e00000
	v_lshl_add_u64 v[64:65], v[48:49], 0, v[14:15]
	v_lshl_add_u64 v[14:15], v[50:51], 0, v[14:15]
	v_add_co_u32_e32 v70, vcc, s0, v62
	v_lshlrev_b64 v[12:13], 11, v[68:69]
	s_nop 0
	v_addc_co_u32_e32 v71, vcc, 0, v63, vcc
	global_load_dwordx2 v[66:67], v[138:139], off offset:64
	global_load_dwordx2 v[62:63], v[64:65], off
	s_nop 0
	global_load_dwordx2 v[64:65], v[14:15], off
	global_load_dwordx2 v[140:141], v[70:71], off
	v_lshl_add_u64 v[12:13], v[46:47], 0, v[12:13]
	s_waitcnt vmcnt(0)
	v_and_b32_e32 v145, 0xffff0000, v10
	v_and_b32_e32 v144, 0xffff0000, v8
	v_and_b32_e32 v149, 0xffff0000, v11
	v_and_b32_e32 v148, 0xffff0000, v9
	v_lshlrev_b32_e32 v143, 16, v10
	v_lshlrev_b32_e32 v142, 16, v8
	v_lshlrev_b32_e32 v147, 16, v11
	v_lshlrev_b32_e32 v146, 16, v9
	v_pk_mul_f32 v[8:9], v[144:145], v[144:145]
	v_pk_mul_f32 v[10:11], v[148:149], v[148:149]
	v_pk_fma_f32 v[8:9], v[142:143], v[142:143], v[8:9]
	v_pk_fma_f32 v[10:11], v[146:147], v[146:147], v[10:11]
	v_mov_b32_e32 v14, v133
	v_mov_b32_e32 v15, v135
	v_pk_add_f32 v[8:9], v[8:9], v[10:11]
	v_mov_b32_e32 v10, v132
	v_mov_b32_e32 v11, v134
	v_pk_mul_f32 v[14:15], v[14:15], v[14:15]
	v_add_f32_e32 v8, v8, v9
	v_pk_fma_f32 v[10:11], v[10:11], v[10:11], v[14:15]
	global_load_dwordx4 v[12:15], v[12:13], off
	s_nop 0
	global_load_dwordx2 v[70:71], v[72:73], off
	v_add_f32_e32 v8, v11, v8
	v_add_f32_e32 v61, v10, v8
	ds_bpermute_b32 v74, v119, v61
	v_lshlrev_b64 v[8:9], 6, v[68:69]
	v_lshl_add_u64 v[10:11], v[48:49], 0, v[8:9]
	v_lshl_add_u64 v[8:9], v[50:51], 0, v[8:9]
	v_pk_mul_f32 v[132:133], v[44:45], v[132:133]
	s_waitcnt lgkmcnt(0)
; __device__ __forceinline__ unsigned cvt_pk(float lo, float hi) { unsigned r; asm volatile("v_cvt_pk_bf16_f32 %0, %1, %2" : "=v"(r) : "v"(lo), "v"(hi)); return r; }
; __device__ __forceinline__ float sq4(f32x4 a) { return (a.x * a.x + a.y * a.y) + (a.z * a.z + a.w * a.w); }
; __device__ __forceinline__ u32x4 pack8(f32x4 a, f32x4 b) { u32x4 o; o.x = cvt_pk(a.x, a.y); o.y = cvt_pk(a.z, a.w); o.z = cvt_pk(b.x, b.y); o.w = cvt_pk(b.z, b.w); return o; }
; __device__ __forceinline__ void finalize_phase(const Params& p, LAS unsigned char* lds, int G) {
;     ...
;         for (int k = 0; k < 8; ++k) {
;             const int row = rowb + k * NGW;
;             if (row < M) {
;                 const int b = row >> 12, s = row & 4095;
;                 const f32x2 cs = csv[k], sn = snv[k];
;                 const size_t orow = ((size_t)(b * 8 + h) * SEQ + s) * 96;
;                 {
;                     const u32x4 n8 = kn8[k];
;                     f32x4 a0 = {bflo(n8.x), bfhi(n8.x), bflo(n8.y), bfhi(n8.y)}, a1 = {bflo(n8.z), bfhi(n8.z), bflo(n8.w), bfhi(n8.w)};
;                     f32x2 x1 = kx1[k], x2 = kx2[k];
;                     float ss = sq4(a0) + sq4(a1) + (x1.x * x1.x + x1.y * x1.y) + (x2.x * x2.x + x2.y * x2.y);
;                     ss += __shfl_xor(ss, 1); ss += __shfl_xor(ss, 2); ss += __shfl_xor(ss, 4);
;                     const float r = 1.0f / sqrtf(ss * (1.f / 96.f) + EPS);
;                     a0 = a0 * gka * r; a1 = a1 * gkb * r; x1 = x1 * gk1 * r; x2 = x2 * gk2 * r;
;                     const f32x2 o1 = x1 * cs - x2 * sn, o2 = x2 * cs + x1 * sn;
;                     *(u32x4*)(KF + orow + 8 * sub) = pack8(a0, a1);
;                     *(unsigned*)(KF + orow + 64 + 2 * sub) = cvt_pk(o1.x, o1.y); *(unsigned*)(KF + orow + 80 + 2 * sub) = cvt_pk(o2.x, o2.y);
;                 }
;             }
	v_add_f32_e32 v61, v61, v74
	ds_bpermute_b32 v68, v120, v61
	global_load_dwordx2 v[76:77], v[72:73], off offset:64
	s_nop 0
	global_load_dwordx2 v[72:73], v[10:11], off
	global_load_dwordx2 v[74:75], v[8:9], off
	v_lshlrev_b64 v[8:9], 11, v[136:137]
	v_lshl_add_u64 v[8:9], v[46:47], 0, v[8:9]
	v_pk_mul_f32 v[134:135], v[42:43], v[134:135]
	s_waitcnt lgkmcnt(0)
	v_add_f32_e32 v61, v61, v68
	global_load_dwordx4 v[8:11], v[8:9], off
	s_nop 0
	global_load_dwordx2 v[68:69], v[138:139], off
	ds_bpermute_b32 v136, v121, v61
	s_waitcnt lgkmcnt(0)
	v_add_f32_e32 v61, v61, v136
	v_fmamk_f32 v61, v61, 0x3c2aaaab, v39
	v_rsq_f32_e32 v138, v61
	s_nop 0
	v_ashrrev_i32_e32 v136, 9, v38
	v_and_or_b32 v136, v136, -8, v37
	v_ashrrev_i32_e32 v137, 31, v136
	v_lshlrev_b64 v[136:137], 12, v[136:137]
	v_and_or_b32 v152, v38, s8, v136
	v_mov_b32_e32 v136, v138
	v_mov_b32_e32 v138, v142
	v_mov_b32_e32 v139, v144
	v_pk_mul_f32 v[132:133], v[132:133], v[136:137] op_sel_hi:[1,0]
	v_pk_mul_f32 v[138:139], v[4:5], v[138:139]
	v_mov_b32_e32 v150, v146
	v_mov_b32_e32 v151, v148
	v_mov_b32_e32 v148, v147
	v_pk_mul_f32 v[134:135], v[134:135], v[136:137] op_sel_hi:[1,0]
	v_pk_mul_f32 v[146:147], v[140:141], v[132:133]
	v_pk_mul_f32 v[138:139], v[138:139], v[136:137] op_sel_hi:[1,0]
	v_pk_fma_f32 v[146:147], v[130:131], v[134:135], v[146:147] neg_lo:[0,0,1] neg_hi:[0,0,1]
	v_pk_mul_f32 v[134:135], v[140:141], v[134:135]
	v_mov_b32_e32 v144, v143
	v_pk_fma_f32 v[134:135], v[130:131], v[132:133], v[134:135]
	v_cvt_pk_bf16_f32 v130, v138, v139
	v_mov_b64_e32 v[138:139], s[36:37]
	v_mad_u64_u32 v[138:139], s[0:1], v152, s10, v[138:139]
	v_pk_mul_f32 v[150:151], v[6:7], v[150:151]
	v_pk_mul_f32 v[142:143], v[0:1], v[144:145]
	v_pk_mul_f32 v[144:145], v[2:3], v[148:149]
	v_mad_i32_i24 v139, v137, s10, v139
	v_pk_mul_f32 v[150:151], v[150:151], v[136:137] op_sel_hi:[1,0]
	v_pk_mul_f32 v[144:145], v[144:145], v[136:137] op_sel_hi:[1,0]
	v_pk_mul_f32 v[142:143], v[142:143], v[136:137] op_sel_hi:[1,0]
	v_cvt_pk_bf16_f32 v131, v150, v151
	v_lshl_add_u64 v[136:137], v[138:139], 0, v[40:41]
	v_cvt_pk_bf16_f32 v132, v142, v143
	v_mov_b32_e32 v61, v41
	v_cvt_pk_bf16_f32 v133, v144, v145
	global_store_dwordx4 v[136:137], v[130:133], off
	s_nop 1
	v_cvt_pk_bf16_f32 v132, v146, v147
	v_lshl_add_u64 v[130:131], v[138:139], 0, v[60:61]
	global_store_dword v[130:131], v132, off offset:128
	v_cvt_pk_bf16_f32 v132, v134, v135
	global_store_dword v[130:131], v132, off offset:160
	s_and_saveexec_b64 s[52:53], s[50:51]
	s_cbranch_execz .LBB0_562
	v_lshlrev_b32_e32 v131, 16, v34
	v_and_b32_e32 v133, 0xffff0000, v34
	v_and_b32_e32 v132, 0xffff0000, v32
	v_lshlrev_b32_e32 v135, 16, v35
	v_and_b32_e32 v35, 0xffff0000, v35
	v_and_b32_e32 v34, 0xffff0000, v33
	v_lshlrev_b32_e32 v130, 16, v32
	v_lshlrev_b32_e32 v134, 16, v33
	v_pk_mul_f32 v[32:33], v[132:133], v[132:133]
	v_pk_mul_f32 v[136:137], v[34:35], v[34:35]
	v_pk_fma_f32 v[32:33], v[130:131], v[130:131], v[32:33]
	v_pk_fma_f32 v[136:137], v[134:135], v[134:135], v[136:137]
	v_mov_b32_e32 v138, v117
	v_mov_b32_e32 v139, v111
	v_pk_add_f32 v[32:33], v[32:33], v[136:137]
	v_mov_b32_e32 v136, v116
	v_mov_b32_e32 v137, v110
	v_pk_mul_f32 v[138:139], v[138:139], v[138:139]
	v_add_f32_e32 v32, v32, v33
	v_pk_fma_f32 v[136:137], v[136:137], v[136:137], v[138:139]
	v_mov_b32_e32 v141, v34
	v_add_f32_e32 v32, v137, v32
	v_add_f32_e32 v32, v136, v32
	ds_bpermute_b32 v33, v119, v32
	v_mov_b32_e32 v34, v135
	v_pk_mul_f32 v[34:35], v[2:3], v[34:35]
	v_pk_mul_f32 v[110:111], v[42:43], v[110:111]
	v_pk_mul_f32 v[116:117], v[44:45], v[116:117]
	s_waitcnt lgkmcnt(0)
	v_add_f32_e32 v32, v32, v33
	ds_bpermute_b32 v33, v120, v32
	s_waitcnt lgkmcnt(0)
	v_add_f32_e32 v32, v32, v33
	ds_bpermute_b32 v33, v121, v32
	s_waitcnt lgkmcnt(0)
	v_add_f32_e32 v32, v32, v33
	v_fmamk_f32 v32, v32, 0x3c2aaaab, v39
	v_rsq_f32_e32 v138, v32
	s_nop 0
	v_ashrrev_i32_e32 v32, 9, v129
	v_and_or_b32 v32, v32, -8, v37
	v_ashrrev_i32_e32 v33, 31, v32
	v_lshlrev_b64 v[136:137], 12, v[32:33]
	v_and_or_b32 v129, v129, s8, v136
	v_mov_b32_e32 v32, v138
	v_mov_b32_e32 v138, v130
	v_mov_b32_e32 v139, v132
	v_mov_b32_e32 v140, v134
	v_mov_b32_e32 v132, v131
	v_pk_mul_f32 v[138:139], v[4:5], v[138:139]
	v_pk_mul_f32 v[140:141], v[6:7], v[140:141]
	v_pk_mul_f32 v[130:131], v[0:1], v[132:133]
	v_pk_mul_f32 v[140:141], v[140:141], v[32:33] op_sel_hi:[1,0]
	v_pk_mul_f32 v[138:139], v[138:139], v[32:33] op_sel_hi:[1,0]
	v_pk_mul_f32 v[132:133], v[34:35], v[32:33] op_sel_hi:[1,0]
	v_pk_mul_f32 v[34:35], v[130:131], v[32:33] op_sel_hi:[1,0]
	v_pk_mul_f32 v[110:111], v[110:111], v[32:33] op_sel_hi:[1,0]
	v_pk_mul_f32 v[32:33], v[116:117], v[32:33] op_sel_hi:[1,0]
	s_nop 0
	v_pk_mul_f32 v[116:117], v[114:115], v[32:33]
	s_nop 0
	v_pk_fma_f32 v[116:117], v[112:113], v[110:111], v[116:117] neg_lo:[0,0,1] neg_hi:[0,0,1]
	v_pk_mul_f32 v[110:111], v[114:115], v[110:111]
	s_nop 0
	v_pk_fma_f32 v[110:111], v[112:113], v[32:33], v[110:111]
	v_mov_b64_e32 v[112:113], s[36:37]
	v_mad_u64_u32 v[112:113], s[0:1], v129, s10, v[112:113]
	v_mad_i32_i24 v113, v137, s10, v113
	v_cvt_pk_bf16_f32 v32, v138, v139
	v_cvt_pk_bf16_f32 v33, v140, v141
	v_cvt_pk_bf16_f32 v34, v34, v35
	v_lshl_add_u64 v[114:115], v[112:113], 0, v[40:41]
	v_cvt_pk_bf16_f32 v35, v132, v133
	global_store_dwordx4 v[114:115], v[32:35], off
	s_nop 1
	v_cvt_pk_bf16_f32 v34, v116, v117
	v_lshl_add_u64 v[32:33], v[112:113], 0, v[60:61]
	global_store_dword v[32:33], v34, off offset:128
	v_cvt_pk_bf16_f32 v34, v110, v111
	global_store_dword v[32:33], v34, off offset:160
	s_or_b64 exec, exec, s[52:53]
	s_and_saveexec_b64 s[50:51], s[48:49]
	s_cbranch_execnz .LBB0_563

; __device__ __forceinline__ unsigned cvt_pk(float lo, float hi) { unsigned r; asm volatile("v_cvt_pk_bf16_f32 %0, %1, %2" : "=v"(r) : "v"(lo), "v"(hi)); return r; }
; __device__ __forceinline__ float sq4(f32x4 a) { return (a.x * a.x + a.y * a.y) + (a.z * a.z + a.w * a.w); }
; __device__ __forceinline__ u32x4 pack8(f32x4 a, f32x4 b) { u32x4 o; o.x = cvt_pk(a.x, a.y); o.y = cvt_pk(a.z, a.w); o.z = cvt_pk(b.x, b.y); o.w = cvt_pk(b.z, b.w); return o; }
; __device__ __forceinline__ void finalize_phase(const Params& p, LAS unsigned char* lds, int G) {
;     ...
;         for (int k = 0; k < 8; ++k) {
;             const int row = rowb + k * NGW;
;             if (row < M) {
;                 const int b = row >> 12, s = row & 4095;
;                 const f32x2 cs = csv[k], sn = snv[k];
;                 const size_t orow = ((size_t)(b * 8 + h) * SEQ + s) * 96;
;                 {
;                     const u32x4 n8 = kn8[k];
;                     f32x4 a0 = {bflo(n8.x), bfhi(n8.x), bflo(n8.y), bfhi(n8.y)}, a1 = {bflo(n8.z), bfhi(n8.z), bflo(n8.w), bfhi(n8.w)};
;                     f32x2 x1 = kx1[k], x2 = kx2[k];
;                     float ss = sq4(a0) + sq4(a1) + (x1.x * x1.x + x1.y * x1.y) + (x2.x * x2.x + x2.y * x2.y);
;                     ss += __shfl_xor(ss, 1); ss += __shfl_xor(ss, 2); ss += __shfl_xor(ss, 4);
;                     const float r = 1.0f / sqrtf(ss * (1.f / 96.f) + EPS);
;                     a0 = a0 * gka * r; a1 = a1 * gkb * r; x1 = x1 * gk1 * r; x2 = x2 * gk2 * r;
;                     const f32x2 o1 = x1 * cs - x2 * sn, o2 = x2 * cs + x1 * sn;
;                     *(u32x4*)(KF + orow + 8 * sub) = pack8(a0, a1);
;                     *(unsigned*)(KF + orow + 64 + 2 * sub) = cvt_pk(o1.x, o1.y); *(unsigned*)(KF + orow + 80 + 2 * sub) = cvt_pk(o2.x, o2.y);
;                 }
;             }
.LBB0_558:
	v_lshlrev_b32_e32 v29, 16, v26
	v_and_b32_e32 v31, 0xffff0000, v26
	v_and_b32_e32 v30, 0xffff0000, v24
	v_lshlrev_b32_e32 v33, 16, v27
	v_and_b32_e32 v27, 0xffff0000, v27
	v_and_b32_e32 v26, 0xffff0000, v25
	v_lshlrev_b32_e32 v28, 16, v24
	v_lshlrev_b32_e32 v32, 16, v25
	v_pk_mul_f32 v[24:25], v[30:31], v[30:31]
	v_pk_mul_f32 v[34:35], v[26:27], v[26:27]
	v_pk_fma_f32 v[24:25], v[28:29], v[28:29], v[24:25]
	v_pk_fma_f32 v[34:35], v[32:33], v[32:33], v[34:35]
	v_mov_b32_e32 v102, v101
	v_mov_b32_e32 v103, v97
	v_pk_add_f32 v[24:25], v[24:25], v[34:35]
	v_mov_b32_e32 v34, v100
	v_mov_b32_e32 v35, v96
	v_pk_mul_f32 v[102:103], v[102:103], v[102:103]
	v_add_f32_e32 v24, v24, v25
	v_pk_fma_f32 v[34:35], v[34:35], v[34:35], v[102:103]
	v_mov_b32_e32 v105, v26
	v_add_f32_e32 v24, v35, v24
	v_add_f32_e32 v24, v34, v24
	ds_bpermute_b32 v25, v119, v24
	v_mov_b32_e32 v26, v33
	v_pk_mul_f32 v[26:27], v[2:3], v[26:27]
	s_waitcnt lgkmcnt(0)
	v_add_f32_e32 v24, v24, v25
	ds_bpermute_b32 v25, v120, v24
	s_waitcnt lgkmcnt(0)
	v_add_f32_e32 v24, v24, v25
	ds_bpermute_b32 v25, v121, v24
	s_waitcnt lgkmcnt(0)
	v_add_f32_e32 v24, v24, v25
	v_fmamk_f32 v24, v24, 0x3c2aaaab, v39
	v_rsq_f32_e32 v61, v24
	s_nop 0
	v_ashrrev_i32_e32 v24, 9, v127
	v_and_or_b32 v24, v24, -8, v37
	v_ashrrev_i32_e32 v25, 31, v24
	v_lshlrev_b64 v[34:35], 12, v[24:25]
	v_and_or_b32 v34, v127, s8, v34
	v_mov_b32_e32 v103, v30
	v_mov_b32_e32 v30, v29
	v_mov_b32_e32 v24, v61
	v_mov_b32_e32 v102, v28
	v_mov_b32_e32 v104, v32
	v_pk_mul_f32 v[28:29], v[0:1], v[30:31]
	v_pk_mul_f32 v[102:103], v[4:5], v[102:103]
	v_pk_mul_f32 v[104:105], v[6:7], v[104:105]
	v_pk_mul_f32 v[30:31], v[26:27], v[24:25] op_sel_hi:[1,0]
	v_pk_mul_f32 v[26:27], v[28:29], v[24:25] op_sel_hi:[1,0]
	v_pk_mul_f32 v[28:29], v[42:43], v[96:97]
	v_pk_mul_f32 v[32:33], v[44:45], v[100:101]
	v_pk_mul_f32 v[104:105], v[104:105], v[24:25] op_sel_hi:[1,0]
	v_pk_mul_f32 v[102:103], v[102:103], v[24:25] op_sel_hi:[1,0]
	v_pk_mul_f32 v[28:29], v[28:29], v[24:25] op_sel_hi:[1,0]
	v_pk_mul_f32 v[24:25], v[32:33], v[24:25] op_sel_hi:[1,0]
	v_mov_b32_e32 v61, v41
	v_pk_mul_f32 v[32:33], v[98:99], v[24:25]
	s_nop 0
	v_pk_fma_f32 v[32:33], v[94:95], v[28:29], v[32:33] neg_lo:[0,0,1] neg_hi:[0,0,1]
	v_pk_mul_f32 v[28:29], v[98:99], v[28:29]
	s_nop 0
	v_pk_fma_f32 v[28:29], v[94:95], v[24:25], v[28:29]
	v_cvt_pk_bf16_f32 v24, v102, v103
	v_cvt_pk_bf16_f32 v25, v104, v105
	v_cvt_pk_bf16_f32 v26, v26, v27
	v_cvt_pk_bf16_f32 v27, v30, v31
	v_mov_b64_e32 v[30:31], s[36:37]
	v_mad_u64_u32 v[30:31], s[0:1], v34, s10, v[30:31]
	v_mad_i32_i24 v31, v35, s10, v31
	v_lshl_add_u64 v[34:35], v[30:31], 0, v[40:41]
	global_store_dwordx4 v[34:35], v[24:27], off
	s_nop 1
	v_cvt_pk_bf16_f32 v26, v32, v33
	v_lshl_add_u64 v[24:25], v[30:31], 0, v[60:61]
	global_store_dword v[24:25], v26, off offset:128
	v_cvt_pk_bf16_f32 v26, v28, v29
	global_store_dword v[24:25], v26, off offset:160
	s_or_b64 exec, exec, s[48:49]
	s_and_saveexec_b64 s[46:47], s[44:45]
	s_cbranch_execnz .LBB0_565

; __device__ __forceinline__ unsigned cvt_pk(float lo, float hi) { unsigned r; asm volatile("v_cvt_pk_bf16_f32 %0, %1, %2" : "=v"(r) : "v"(lo), "v"(hi)); return r; }
; __device__ __forceinline__ float sq4(f32x4 a) { return (a.x * a.x + a.y * a.y) + (a.z * a.z + a.w * a.w); }
; __device__ __forceinline__ u32x4 pack8(f32x4 a, f32x4 b) { u32x4 o; o.x = cvt_pk(a.x, a.y); o.y = cvt_pk(a.z, a.w); o.z = cvt_pk(b.x, b.y); o.w = cvt_pk(b.z, b.w); return o; }
; __device__ __forceinline__ void finalize_phase(const Params& p, LAS unsigned char* lds, int G) {
;     ...
;         for (int k = 0; k < 8; ++k) {
;             const int row = rowb + k * NGW;
;             if (row < M) {
;                 const int b = row >> 12, s = row & 4095;
;                 const f32x2 cs = csv[k], sn = snv[k];
;                 const size_t orow = ((size_t)(b * 8 + h) * SEQ + s) * 96;
;                 {
;                     const u32x4 n8 = kn8[k];
;                     f32x4 a0 = {bflo(n8.x), bfhi(n8.x), bflo(n8.y), bfhi(n8.y)}, a1 = {bflo(n8.z), bfhi(n8.z), bflo(n8.w), bfhi(n8.w)};
;                     f32x2 x1 = kx1[k], x2 = kx2[k];
;                     float ss = sq4(a0) + sq4(a1) + (x1.x * x1.x + x1.y * x1.y) + (x2.x * x2.x + x2.y * x2.y);
;                     ss += __shfl_xor(ss, 1); ss += __shfl_xor(ss, 2); ss += __shfl_xor(ss, 4);
;                     const float r = 1.0f / sqrtf(ss * (1.f / 96.f) + EPS);
;                     a0 = a0 * gka * r; a1 = a1 * gkb * r; x1 = x1 * gk1 * r; x2 = x2 * gk2 * r;
;                     const f32x2 o1 = x1 * cs - x2 * sn, o2 = x2 * cs + x1 * sn;
;                     *(u32x4*)(KF + orow + 8 * sub) = pack8(a0, a1);
;                     *(unsigned*)(KF + orow + 64 + 2 * sub) = cvt_pk(o1.x, o1.y); *(unsigned*)(KF + orow + 80 + 2 * sub) = cvt_pk(o2.x, o2.y);
;                 }
;             }
.LBB0_560:
	v_lshlrev_b32_e32 v21, 16, v18
	v_and_b32_e32 v23, 0xffff0000, v18
	v_and_b32_e32 v22, 0xffff0000, v16
	v_lshlrev_b32_e32 v25, 16, v19
	v_and_b32_e32 v19, 0xffff0000, v19
	v_and_b32_e32 v18, 0xffff0000, v17
	v_lshlrev_b32_e32 v20, 16, v16
	v_lshlrev_b32_e32 v24, 16, v17
	v_pk_mul_f32 v[16:17], v[22:23], v[22:23]
	v_pk_mul_f32 v[26:27], v[18:19], v[18:19]
	v_pk_fma_f32 v[16:17], v[20:21], v[20:21], v[16:17]
	v_pk_fma_f32 v[26:27], v[24:25], v[24:25], v[26:27]
	v_mov_b32_e32 v28, v85
	v_mov_b32_e32 v29, v81
	v_pk_add_f32 v[16:17], v[16:17], v[26:27]
	v_mov_b32_e32 v26, v84
	v_mov_b32_e32 v27, v80
	v_pk_mul_f32 v[28:29], v[28:29], v[28:29]
	v_add_f32_e32 v16, v16, v17
	v_pk_fma_f32 v[26:27], v[26:27], v[26:27], v[28:29]
	v_mov_b32_e32 v61, v41
	v_add_f32_e32 v16, v27, v16
	v_add_f32_e32 v16, v26, v16
	ds_bpermute_b32 v17, v119, v16
	s_waitcnt lgkmcnt(0)
	v_add_f32_e32 v16, v16, v17
	ds_bpermute_b32 v17, v120, v16
	s_waitcnt lgkmcnt(0)
	v_add_f32_e32 v16, v16, v17
	ds_bpermute_b32 v17, v121, v16
	s_waitcnt lgkmcnt(0)
	v_add_f32_e32 v16, v16, v17
	v_fmamk_f32 v16, v16, 0x3c2aaaab, v39
	v_rsq_f32_e32 v28, v16
	s_nop 0
	v_ashrrev_i32_e32 v16, 9, v125
	v_and_or_b32 v16, v16, -8, v37
	v_ashrrev_i32_e32 v17, 31, v16
	v_lshlrev_b64 v[26:27], 12, v[16:17]
	v_and_or_b32 v26, v125, s8, v26
	v_mov_b32_e32 v29, v22
	v_mov_b32_e32 v31, v18
	v_mov_b32_e32 v22, v21
	v_mov_b32_e32 v18, v25
	v_mov_b32_e32 v16, v28
	v_mov_b32_e32 v28, v20
	v_mov_b32_e32 v30, v24
	v_pk_mul_f32 v[20:21], v[0:1], v[22:23]
	v_pk_mul_f32 v[18:19], v[2:3], v[18:19]
	v_pk_mul_f32 v[28:29], v[4:5], v[28:29]
	v_pk_mul_f32 v[30:31], v[6:7], v[30:31]
	v_pk_mul_f32 v[22:23], v[18:19], v[16:17] op_sel_hi:[1,0]
	v_pk_mul_f32 v[18:19], v[20:21], v[16:17] op_sel_hi:[1,0]
	v_pk_mul_f32 v[20:21], v[42:43], v[80:81]
	v_pk_mul_f32 v[24:25], v[44:45], v[84:85]
	v_pk_mul_f32 v[30:31], v[30:31], v[16:17] op_sel_hi:[1,0]
	v_pk_mul_f32 v[28:29], v[28:29], v[16:17] op_sel_hi:[1,0]
	v_pk_mul_f32 v[20:21], v[20:21], v[16:17] op_sel_hi:[1,0]
	v_pk_mul_f32 v[16:17], v[24:25], v[16:17] op_sel_hi:[1,0]
	s_nop 0
	v_pk_mul_f32 v[24:25], v[82:83], v[16:17]
	s_nop 0
	v_pk_fma_f32 v[24:25], v[78:79], v[20:21], v[24:25] neg_lo:[0,0,1] neg_hi:[0,0,1]
	v_pk_mul_f32 v[20:21], v[82:83], v[20:21]
	s_nop 0
	v_pk_fma_f32 v[20:21], v[78:79], v[16:17], v[20:21]
	v_cvt_pk_bf16_f32 v16, v28, v29
	v_cvt_pk_bf16_f32 v17, v30, v31
	v_cvt_pk_bf16_f32 v18, v18, v19
	v_cvt_pk_bf16_f32 v19, v22, v23
	v_mov_b64_e32 v[22:23], s[36:37]
	v_mad_u64_u32 v[22:23], s[0:1], v26, s10, v[22:23]
	v_mad_i32_i24 v23, v27, s10, v23
	v_lshl_add_u64 v[26:27], v[22:23], 0, v[40:41]
	global_store_dwordx4 v[26:27], v[16:19], off
	s_nop 1
	v_cvt_pk_bf16_f32 v18, v24, v25
	v_lshl_add_u64 v[16:17], v[22:23], 0, v[60:61]
	global_store_dword v[16:17], v18, off offset:128
	v_cvt_pk_bf16_f32 v18, v20, v21
	global_store_dword v[16:17], v18, off offset:160
	s_or_b64 exec, exec, s[44:45]
	s_and_saveexec_b64 s[42:43], s[40:41]
	s_cbranch_execnz .LBB0_567

; __device__ __forceinline__ unsigned cvt_pk(float lo, float hi) { unsigned r; asm volatile("v_cvt_pk_bf16_f32 %0, %1, %2" : "=v"(r) : "v"(lo), "v"(hi)); return r; }
; __device__ __forceinline__ float sq4(f32x4 a) { return (a.x * a.x + a.y * a.y) + (a.z * a.z + a.w * a.w); }
; __device__ __forceinline__ u32x4 pack8(f32x4 a, f32x4 b) { u32x4 o; o.x = cvt_pk(a.x, a.y); o.y = cvt_pk(a.z, a.w); o.z = cvt_pk(b.x, b.y); o.w = cvt_pk(b.z, b.w); return o; }
; __device__ __forceinline__ void finalize_phase(const Params& p, LAS unsigned char* lds, int G) {
;     ...
;         for (int k = 0; k < 8; ++k) {
;             const int row = rowb + k * NGW;
;             if (row < M) {
;                 const int b = row >> 12, s = row & 4095;
;                 const f32x2 cs = csv[k], sn = snv[k];
;                 const size_t orow = ((size_t)(b * 8 + h) * SEQ + s) * 96;
;                 {
;                     const u32x4 n8 = kn8[k];
;                     f32x4 a0 = {bflo(n8.x), bfhi(n8.x), bflo(n8.y), bfhi(n8.y)}, a1 = {bflo(n8.z), bfhi(n8.z), bflo(n8.w), bfhi(n8.w)};
;                     f32x2 x1 = kx1[k], x2 = kx2[k];
;                     float ss = sq4(a0) + sq4(a1) + (x1.x * x1.x + x1.y * x1.y) + (x2.x * x2.x + x2.y * x2.y);
;                     ss += __shfl_xor(ss, 1); ss += __shfl_xor(ss, 2); ss += __shfl_xor(ss, 4);
;                     const float r = 1.0f / sqrtf(ss * (1.f / 96.f) + EPS);
;                     a0 = a0 * gka * r; a1 = a1 * gkb * r; x1 = x1 * gk1 * r; x2 = x2 * gk2 * r;
;                     const f32x2 o1 = x1 * cs - x2 * sn, o2 = x2 * cs + x1 * sn;
;                     *(u32x4*)(KF + orow + 8 * sub) = pack8(a0, a1);
;                     *(unsigned*)(KF + orow + 64 + 2 * sub) = cvt_pk(o1.x, o1.y); *(unsigned*)(KF + orow + 80 + 2 * sub) = cvt_pk(o2.x, o2.y);
;                 }
;             }
.LBB0_563:
	v_lshlrev_b32_e32 v33, 16, v30
	v_and_b32_e32 v35, 0xffff0000, v30
	v_and_b32_e32 v34, 0xffff0000, v28
	v_lshlrev_b32_e32 v111, 16, v31
	v_and_b32_e32 v31, 0xffff0000, v31
	v_and_b32_e32 v30, 0xffff0000, v29
	v_lshlrev_b32_e32 v32, 16, v28
	v_lshlrev_b32_e32 v110, 16, v29
	v_pk_mul_f32 v[28:29], v[34:35], v[34:35]
	v_pk_mul_f32 v[112:113], v[30:31], v[30:31]
	v_pk_fma_f32 v[28:29], v[32:33], v[32:33], v[28:29]
	v_pk_fma_f32 v[112:113], v[110:111], v[110:111], v[112:113]
	v_mov_b32_e32 v114, v109
	v_mov_b32_e32 v115, v103
	v_pk_add_f32 v[28:29], v[28:29], v[112:113]
	v_mov_b32_e32 v112, v108
	v_mov_b32_e32 v113, v102
	v_pk_mul_f32 v[114:115], v[114:115], v[114:115]
	v_add_f32_e32 v28, v28, v29
	v_pk_fma_f32 v[112:113], v[112:113], v[112:113], v[114:115]
	v_mov_b32_e32 v117, v30
	v_add_f32_e32 v28, v113, v28
	v_add_f32_e32 v28, v112, v28
	ds_bpermute_b32 v29, v119, v28
	v_mov_b32_e32 v30, v111
	v_pk_mul_f32 v[30:31], v[2:3], v[30:31]
	s_waitcnt lgkmcnt(0)
	v_add_f32_e32 v28, v28, v29
	ds_bpermute_b32 v29, v120, v28
	s_waitcnt lgkmcnt(0)
	v_add_f32_e32 v28, v28, v29
	ds_bpermute_b32 v29, v121, v28
	s_waitcnt lgkmcnt(0)
	v_add_f32_e32 v28, v28, v29
	v_fmamk_f32 v28, v28, 0x3c2aaaab, v39
	v_rsq_f32_e32 v61, v28
	s_nop 0
	v_ashrrev_i32_e32 v28, 9, v128
	v_and_or_b32 v28, v28, -8, v37
	v_ashrrev_i32_e32 v29, 31, v28
	v_lshlrev_b64 v[112:113], 12, v[28:29]
	v_and_or_b32 v112, v128, s8, v112
	v_mov_b32_e32 v115, v34
	v_mov_b32_e32 v34, v33
	v_mov_b32_e32 v28, v61
	v_mov_b32_e32 v114, v32
	v_mov_b32_e32 v116, v110
	v_pk_mul_f32 v[32:33], v[0:1], v[34:35]
	v_pk_mul_f32 v[114:115], v[4:5], v[114:115]
	v_pk_mul_f32 v[116:117], v[6:7], v[116:117]
	v_pk_mul_f32 v[34:35], v[30:31], v[28:29] op_sel_hi:[1,0]
	v_pk_mul_f32 v[30:31], v[32:33], v[28:29] op_sel_hi:[1,0]
	v_pk_mul_f32 v[32:33], v[42:43], v[102:103]
	v_pk_mul_f32 v[102:103], v[44:45], v[108:109]
	v_pk_mul_f32 v[116:117], v[116:117], v[28:29] op_sel_hi:[1,0]
	v_pk_mul_f32 v[114:115], v[114:115], v[28:29] op_sel_hi:[1,0]
	v_pk_mul_f32 v[32:33], v[32:33], v[28:29] op_sel_hi:[1,0]
	v_pk_mul_f32 v[28:29], v[102:103], v[28:29] op_sel_hi:[1,0]
	v_mov_b32_e32 v61, v41
	v_pk_mul_f32 v[102:103], v[106:107], v[28:29]
	s_nop 0
	v_pk_fma_f32 v[102:103], v[104:105], v[32:33], v[102:103] neg_lo:[0,0,1] neg_hi:[0,0,1]
	v_pk_mul_f32 v[32:33], v[106:107], v[32:33]
	s_nop 0
	v_pk_fma_f32 v[32:33], v[104:105], v[28:29], v[32:33]
	v_cvt_pk_bf16_f32 v28, v114, v115
	v_cvt_pk_bf16_f32 v29, v116, v117
	v_cvt_pk_bf16_f32 v30, v30, v31
	v_cvt_pk_bf16_f32 v31, v34, v35
	v_mov_b64_e32 v[34:35], s[36:37]
	v_mad_u64_u32 v[34:35], s[0:1], v112, s10, v[34:35]
	v_mad_i32_i24 v35, v113, s10, v35
	v_lshl_add_u64 v[104:105], v[34:35], 0, v[40:41]
	global_store_dwordx4 v[104:105], v[28:31], off
	s_nop 1
	v_cvt_pk_bf16_f32 v30, v102, v103
	v_lshl_add_u64 v[28:29], v[34:35], 0, v[60:61]
	global_store_dword v[28:29], v30, off offset:128
	v_cvt_pk_bf16_f32 v30, v32, v33
	global_store_dword v[28:29], v30, off offset:160
	s_or_b64 exec, exec, s[50:51]
	s_and_saveexec_b64 s[48:49], s[46:47]
	s_cbranch_execnz .LBB0_558

; __device__ __forceinline__ unsigned cvt_pk(float lo, float hi) { unsigned r; asm volatile("v_cvt_pk_bf16_f32 %0, %1, %2" : "=v"(r) : "v"(lo), "v"(hi)); return r; }
; __device__ __forceinline__ float sq4(f32x4 a) { return (a.x * a.x + a.y * a.y) + (a.z * a.z + a.w * a.w); }
; __device__ __forceinline__ u32x4 pack8(f32x4 a, f32x4 b) { u32x4 o; o.x = cvt_pk(a.x, a.y); o.y = cvt_pk(a.z, a.w); o.z = cvt_pk(b.x, b.y); o.w = cvt_pk(b.z, b.w); return o; }
; __device__ __forceinline__ void finalize_phase(const Params& p, LAS unsigned char* lds, int G) {
;     ...
;         for (int k = 0; k < 8; ++k) {
;             const int row = rowb + k * NGW;
;             if (row < M) {
;                 const int b = row >> 12, s = row & 4095;
;                 const f32x2 cs = csv[k], sn = snv[k];
;                 const size_t orow = ((size_t)(b * 8 + h) * SEQ + s) * 96;
;                 {
;                     const u32x4 n8 = kn8[k];
;                     f32x4 a0 = {bflo(n8.x), bfhi(n8.x), bflo(n8.y), bfhi(n8.y)}, a1 = {bflo(n8.z), bfhi(n8.z), bflo(n8.w), bfhi(n8.w)};
;                     f32x2 x1 = kx1[k], x2 = kx2[k];
;                     float ss = sq4(a0) + sq4(a1) + (x1.x * x1.x + x1.y * x1.y) + (x2.x * x2.x + x2.y * x2.y);
;                     ss += __shfl_xor(ss, 1); ss += __shfl_xor(ss, 2); ss += __shfl_xor(ss, 4);
;                     const float r = 1.0f / sqrtf(ss * (1.f / 96.f) + EPS);
;                     a0 = a0 * gka * r; a1 = a1 * gkb * r; x1 = x1 * gk1 * r; x2 = x2 * gk2 * r;
;                     const f32x2 o1 = x1 * cs - x2 * sn, o2 = x2 * cs + x1 * sn;
;                     *(u32x4*)(KF + orow + 8 * sub) = pack8(a0, a1);
;                     *(unsigned*)(KF + orow + 64 + 2 * sub) = cvt_pk(o1.x, o1.y); *(unsigned*)(KF + orow + 80 + 2 * sub) = cvt_pk(o2.x, o2.y);
;                 }
;             }
.LBB0_565:
	v_lshlrev_b32_e32 v25, 16, v22
	v_and_b32_e32 v27, 0xffff0000, v22
	v_and_b32_e32 v26, 0xffff0000, v20
	v_lshlrev_b32_e32 v29, 16, v23
	v_and_b32_e32 v23, 0xffff0000, v23
	v_and_b32_e32 v22, 0xffff0000, v21
	v_lshlrev_b32_e32 v24, 16, v20
	v_lshlrev_b32_e32 v28, 16, v21
	v_pk_mul_f32 v[20:21], v[26:27], v[26:27]
	v_pk_mul_f32 v[30:31], v[22:23], v[22:23]
	v_pk_fma_f32 v[20:21], v[24:25], v[24:25], v[20:21]
	v_pk_fma_f32 v[30:31], v[28:29], v[28:29], v[30:31]
	v_mov_b32_e32 v32, v93
	v_mov_b32_e32 v33, v89
	v_pk_add_f32 v[20:21], v[20:21], v[30:31]
	v_mov_b32_e32 v30, v92
	v_mov_b32_e32 v31, v88
	v_pk_mul_f32 v[32:33], v[32:33], v[32:33]
	v_add_f32_e32 v20, v20, v21
	v_pk_fma_f32 v[30:31], v[30:31], v[30:31], v[32:33]
	v_mov_b32_e32 v61, v41
	v_add_f32_e32 v20, v31, v20
	v_add_f32_e32 v20, v30, v20
	ds_bpermute_b32 v21, v119, v20
	s_waitcnt lgkmcnt(0)
	v_add_f32_e32 v20, v20, v21
	ds_bpermute_b32 v21, v120, v20
	s_waitcnt lgkmcnt(0)
	v_add_f32_e32 v20, v20, v21
	ds_bpermute_b32 v21, v121, v20
	s_waitcnt lgkmcnt(0)
	v_add_f32_e32 v20, v20, v21
	v_fmamk_f32 v20, v20, 0x3c2aaaab, v39
	v_rsq_f32_e32 v32, v20
	s_nop 0
	v_ashrrev_i32_e32 v20, 9, v126
	v_and_or_b32 v20, v20, -8, v37
	v_ashrrev_i32_e32 v21, 31, v20
	v_lshlrev_b64 v[30:31], 12, v[20:21]
	v_and_or_b32 v30, v126, s8, v30
	v_mov_b32_e32 v33, v26
	v_mov_b32_e32 v35, v22
	v_mov_b32_e32 v26, v25
	v_mov_b32_e32 v22, v29
	v_mov_b32_e32 v20, v32
	v_mov_b32_e32 v32, v24
	v_mov_b32_e32 v34, v28
	v_pk_mul_f32 v[24:25], v[0:1], v[26:27]
	v_pk_mul_f32 v[22:23], v[2:3], v[22:23]
	v_pk_mul_f32 v[32:33], v[4:5], v[32:33]
	v_pk_mul_f32 v[34:35], v[6:7], v[34:35]
	v_pk_mul_f32 v[26:27], v[22:23], v[20:21] op_sel_hi:[1,0]
	v_pk_mul_f32 v[22:23], v[24:25], v[20:21] op_sel_hi:[1,0]
	v_pk_mul_f32 v[24:25], v[42:43], v[88:89]
	v_pk_mul_f32 v[28:29], v[44:45], v[92:93]
	v_pk_mul_f32 v[34:35], v[34:35], v[20:21] op_sel_hi:[1,0]
	v_pk_mul_f32 v[32:33], v[32:33], v[20:21] op_sel_hi:[1,0]
	v_pk_mul_f32 v[24:25], v[24:25], v[20:21] op_sel_hi:[1,0]
	v_pk_mul_f32 v[20:21], v[28:29], v[20:21] op_sel_hi:[1,0]
	s_nop 0
	v_pk_mul_f32 v[28:29], v[90:91], v[20:21]
	s_nop 0
	v_pk_fma_f32 v[28:29], v[86:87], v[24:25], v[28:29] neg_lo:[0,0,1] neg_hi:[0,0,1]
	v_pk_mul_f32 v[24:25], v[90:91], v[24:25]
	s_nop 0
	v_pk_fma_f32 v[24:25], v[86:87], v[20:21], v[24:25]
	v_cvt_pk_bf16_f32 v20, v32, v33
	v_cvt_pk_bf16_f32 v21, v34, v35
	v_cvt_pk_bf16_f32 v22, v22, v23
	v_cvt_pk_bf16_f32 v23, v26, v27
	v_mov_b64_e32 v[26:27], s[36:37]
	v_mad_u64_u32 v[26:27], s[0:1], v30, s10, v[26:27]
	v_mad_i32_i24 v27, v31, s10, v27
	v_lshl_add_u64 v[30:31], v[26:27], 0, v[40:41]
	global_store_dwordx4 v[30:31], v[20:23], off
	s_nop 1
	v_cvt_pk_bf16_f32 v22, v28, v29
	v_lshl_add_u64 v[20:21], v[26:27], 0, v[60:61]
	global_store_dword v[20:21], v22, off offset:128
	v_cvt_pk_bf16_f32 v22, v24, v25
	global_store_dword v[20:21], v22, off offset:160
	s_or_b64 exec, exec, s[46:47]
	s_and_saveexec_b64 s[44:45], s[42:43]
	s_cbranch_execnz .LBB0_560

; __device__ __forceinline__ unsigned cvt_pk(float lo, float hi) { unsigned r; asm volatile("v_cvt_pk_bf16_f32 %0, %1, %2" : "=v"(r) : "v"(lo), "v"(hi)); return r; }
; __device__ __forceinline__ float sq4(f32x4 a) { return (a.x * a.x + a.y * a.y) + (a.z * a.z + a.w * a.w); }
; __device__ __forceinline__ u32x4 pack8(f32x4 a, f32x4 b) { u32x4 o; o.x = cvt_pk(a.x, a.y); o.y = cvt_pk(a.z, a.w); o.z = cvt_pk(b.x, b.y); o.w = cvt_pk(b.z, b.w); return o; }
; __device__ __forceinline__ void finalize_phase(const Params& p, LAS unsigned char* lds, int G) {
;     ...
;         for (int k = 0; k < 8; ++k) {
;             const int row = rowb + k * NGW;
;             if (row < M) {
;                 const int b = row >> 12, s = row & 4095;
;                 const f32x2 cs = csv[k], sn = snv[k];
;                 const size_t orow = ((size_t)(b * 8 + h) * SEQ + s) * 96;
;                 {
;                     const u32x4 n8 = kn8[k];
;                     f32x4 a0 = {bflo(n8.x), bfhi(n8.x), bflo(n8.y), bfhi(n8.y)}, a1 = {bflo(n8.z), bfhi(n8.z), bflo(n8.w), bfhi(n8.w)};
;                     f32x2 x1 = kx1[k], x2 = kx2[k];
;                     float ss = sq4(a0) + sq4(a1) + (x1.x * x1.x + x1.y * x1.y) + (x2.x * x2.x + x2.y * x2.y);
;                     ss += __shfl_xor(ss, 1); ss += __shfl_xor(ss, 2); ss += __shfl_xor(ss, 4);
;                     const float r = 1.0f / sqrtf(ss * (1.f / 96.f) + EPS);
;                     a0 = a0 * gka * r; a1 = a1 * gkb * r; x1 = x1 * gk1 * r; x2 = x2 * gk2 * r;
;                     const f32x2 o1 = x1 * cs - x2 * sn, o2 = x2 * cs + x1 * sn;
;                     *(u32x4*)(KF + orow + 8 * sub) = pack8(a0, a1);
;                     *(unsigned*)(KF + orow + 64 + 2 * sub) = cvt_pk(o1.x, o1.y); *(unsigned*)(KF + orow + 80 + 2 * sub) = cvt_pk(o2.x, o2.y);
;                 }
;             }
.LBB0_567:
	s_waitcnt vmcnt(9)
	v_lshlrev_b32_e32 v17, 16, v14
	v_and_b32_e32 v19, 0xffff0000, v14
	v_and_b32_e32 v18, 0xffff0000, v12
	v_lshlrev_b32_e32 v21, 16, v15
	v_and_b32_e32 v15, 0xffff0000, v15
	v_and_b32_e32 v14, 0xffff0000, v13
	v_lshlrev_b32_e32 v16, 16, v12
	v_lshlrev_b32_e32 v20, 16, v13
	v_pk_mul_f32 v[12:13], v[18:19], v[18:19]
	v_pk_mul_f32 v[22:23], v[14:15], v[14:15]
	v_pk_fma_f32 v[12:13], v[16:17], v[16:17], v[12:13]
	v_pk_fma_f32 v[22:23], v[20:21], v[20:21], v[22:23]
	s_waitcnt vmcnt(7)
	v_mov_b32_e32 v24, v77
	v_mov_b32_e32 v25, v71
	v_pk_add_f32 v[12:13], v[12:13], v[22:23]
	v_mov_b32_e32 v22, v76
	v_mov_b32_e32 v23, v70
	v_pk_mul_f32 v[24:25], v[24:25], v[24:25]
	v_add_f32_e32 v12, v12, v13
	v_pk_fma_f32 v[22:23], v[22:23], v[22:23], v[24:25]
	v_mov_b32_e32 v61, v41
	v_add_f32_e32 v12, v23, v12
	v_add_f32_e32 v12, v22, v12
	ds_bpermute_b32 v13, v119, v12
	s_waitcnt lgkmcnt(0)
	v_add_f32_e32 v12, v12, v13
	ds_bpermute_b32 v13, v120, v12
	s_waitcnt lgkmcnt(0)
	v_add_f32_e32 v12, v12, v13
	ds_bpermute_b32 v13, v121, v12
	s_waitcnt lgkmcnt(0)
	v_add_f32_e32 v12, v12, v13
	v_fmamk_f32 v12, v12, 0x3c2aaaab, v39
	v_rsq_f32_e32 v24, v12
	s_nop 0
	v_ashrrev_i32_e32 v12, 9, v124
	v_and_or_b32 v12, v12, -8, v37
	v_ashrrev_i32_e32 v13, 31, v12
	v_lshlrev_b64 v[22:23], 12, v[12:13]
	v_and_or_b32 v22, v124, s8, v22
	v_mov_b32_e32 v25, v18
	v_mov_b32_e32 v27, v14
	v_mov_b32_e32 v18, v17
	v_mov_b32_e32 v14, v21
	v_mov_b32_e32 v12, v24
	v_mov_b32_e32 v24, v16
	v_mov_b32_e32 v26, v20
	v_pk_mul_f32 v[16:17], v[0:1], v[18:19]
	v_pk_mul_f32 v[14:15], v[2:3], v[14:15]
	v_pk_mul_f32 v[24:25], v[4:5], v[24:25]
	v_pk_mul_f32 v[26:27], v[6:7], v[26:27]
	v_pk_mul_f32 v[18:19], v[14:15], v[12:13] op_sel_hi:[1,0]
	v_pk_mul_f32 v[14:15], v[16:17], v[12:13] op_sel_hi:[1,0]
	v_pk_mul_f32 v[16:17], v[42:43], v[70:71]
	v_pk_mul_f32 v[20:21], v[44:45], v[76:77]
	v_pk_mul_f32 v[26:27], v[26:27], v[12:13] op_sel_hi:[1,0]
	v_pk_mul_f32 v[24:25], v[24:25], v[12:13] op_sel_hi:[1,0]
	v_pk_mul_f32 v[16:17], v[16:17], v[12:13] op_sel_hi:[1,0]
	v_pk_mul_f32 v[12:13], v[20:21], v[12:13] op_sel_hi:[1,0]
	s_waitcnt vmcnt(5)
	v_pk_mul_f32 v[20:21], v[74:75], v[12:13]
	s_nop 0
	v_pk_fma_f32 v[20:21], v[72:73], v[16:17], v[20:21] neg_lo:[0,0,1] neg_hi:[0,0,1]
	v_pk_mul_f32 v[16:17], v[74:75], v[16:17]
	s_nop 0
	v_pk_fma_f32 v[16:17], v[72:73], v[12:13], v[16:17]
	v_cvt_pk_bf16_f32 v12, v24, v25
	v_cvt_pk_bf16_f32 v13, v26, v27
	v_cvt_pk_bf16_f32 v14, v14, v15
	v_cvt_pk_bf16_f32 v15, v18, v19
	v_mov_b64_e32 v[18:19], s[36:37]
	v_mad_u64_u32 v[18:19], s[0:1], v22, s10, v[18:19]
	v_mad_i32_i24 v19, v23, s10, v19
	v_lshl_add_u64 v[22:23], v[18:19], 0, v[40:41]
	global_store_dwordx4 v[22:23], v[12:15], off
	s_nop 1
	v_cvt_pk_bf16_f32 v14, v20, v21
	v_lshl_add_u64 v[12:13], v[18:19], 0, v[60:61]
	global_store_dword v[12:13], v14, off offset:128
	v_cvt_pk_bf16_f32 v14, v16, v17
	global_store_dword v[12:13], v14, off offset:160
	s_or_b64 exec, exec, s[42:43]
	s_and_saveexec_b64 s[40:41], s[38:39]
	s_cbranch_execz .LBB0_554
.LBB0_568:
	s_waitcnt vmcnt(4)
	v_lshlrev_b32_e32 v13, 16, v10
	v_and_b32_e32 v15, 0xffff0000, v10
	v_and_b32_e32 v14, 0xffff0000, v8
	v_lshlrev_b32_e32 v17, 16, v11
	v_and_b32_e32 v11, 0xffff0000, v11
	v_and_b32_e32 v10, 0xffff0000, v9
	v_lshlrev_b32_e32 v12, 16, v8
	v_lshlrev_b32_e32 v16, 16, v9
	v_pk_mul_f32 v[8:9], v[14:15], v[14:15]
	v_pk_mul_f32 v[18:19], v[10:11], v[10:11]
	v_pk_fma_f32 v[8:9], v[12:13], v[12:13], v[8:9]
	v_pk_fma_f32 v[18:19], v[16:17], v[16:17], v[18:19]
	v_mov_b32_e32 v20, v67
	s_waitcnt vmcnt(3)
	v_mov_b32_e32 v21, v69
	v_pk_add_f32 v[8:9], v[8:9], v[18:19]
	v_mov_b32_e32 v18, v66
	v_mov_b32_e32 v19, v68
	v_pk_mul_f32 v[20:21], v[20:21], v[20:21]
	v_add_f32_e32 v8, v8, v9
	v_pk_fma_f32 v[18:19], v[18:19], v[18:19], v[20:21]
	v_mov_b32_e32 v61, v41
	v_add_f32_e32 v8, v19, v8
	v_add_f32_e32 v8, v18, v8
	ds_bpermute_b32 v9, v119, v8
	s_waitcnt lgkmcnt(0)
	v_add_f32_e32 v8, v8, v9
	ds_bpermute_b32 v9, v120, v8
	s_waitcnt lgkmcnt(0)
	v_add_f32_e32 v8, v8, v9
	ds_bpermute_b32 v9, v121, v8
	s_waitcnt lgkmcnt(0)
	v_add_f32_e32 v8, v8, v9
	v_fmamk_f32 v8, v8, 0x3c2aaaab, v39
	v_rsq_f32_e32 v20, v8
	s_nop 0
	v_ashrrev_i32_e32 v8, 9, v123
	v_and_or_b32 v8, v8, -8, v37
	v_ashrrev_i32_e32 v9, 31, v8
	v_lshlrev_b64 v[18:19], 12, v[8:9]
	v_and_or_b32 v18, v123, s8, v18
	v_mov_b32_e32 v21, v14
	v_mov_b32_e32 v23, v10
	v_mov_b32_e32 v14, v13
	v_mov_b32_e32 v10, v17
	v_mov_b32_e32 v8, v20
	v_mov_b32_e32 v20, v12
	v_mov_b32_e32 v22, v16
	v_pk_mul_f32 v[12:13], v[0:1], v[14:15]
	v_pk_mul_f32 v[10:11], v[2:3], v[10:11]
	v_pk_mul_f32 v[20:21], v[4:5], v[20:21]
	v_pk_mul_f32 v[22:23], v[6:7], v[22:23]
	v_pk_mul_f32 v[14:15], v[10:11], v[8:9] op_sel_hi:[1,0]
	v_pk_mul_f32 v[10:11], v[12:13], v[8:9] op_sel_hi:[1,0]
	v_pk_mul_f32 v[12:13], v[42:43], v[68:69]
	v_pk_mul_f32 v[16:17], v[44:45], v[66:67]
	v_pk_mul_f32 v[22:23], v[22:23], v[8:9] op_sel_hi:[1,0]
	v_pk_mul_f32 v[20:21], v[20:21], v[8:9] op_sel_hi:[1,0]
	v_pk_mul_f32 v[12:13], v[12:13], v[8:9] op_sel_hi:[1,0]
	v_pk_mul_f32 v[8:9], v[16:17], v[8:9] op_sel_hi:[1,0]
	s_nop 0
	v_pk_mul_f32 v[16:17], v[64:65], v[8:9]
	s_nop 0
	v_pk_fma_f32 v[16:17], v[62:63], v[12:13], v[16:17] neg_lo:[0,0,1] neg_hi:[0,0,1]
	v_pk_mul_f32 v[12:13], v[64:65], v[12:13]
	s_nop 0
	v_pk_fma_f32 v[12:13], v[62:63], v[8:9], v[12:13]
	v_cvt_pk_bf16_f32 v8, v20, v21
	v_cvt_pk_bf16_f32 v9, v22, v23
	v_cvt_pk_bf16_f32 v10, v10, v11
	v_cvt_pk_bf16_f32 v11, v14, v15
	v_mov_b64_e32 v[14:15], s[36:37]
	v_mad_u64_u32 v[14:15], s[0:1], v18, s10, v[14:15]
	v_mad_i32_i24 v15, v19, s10, v15
	v_lshl_add_u64 v[18:19], v[14:15], 0, v[40:41]
	global_store_dwordx4 v[18:19], v[8:11], off
	s_nop 1
	v_cvt_pk_bf16_f32 v10, v16, v17
	v_lshl_add_u64 v[8:9], v[14:15], 0, v[60:61]
	global_store_dword v[8:9], v10, off offset:128
	v_cvt_pk_bf16_f32 v10, v12, v13
	global_store_dword v[8:9], v10, off offset:160
	s_branch .LBB0_554

; __device__ __forceinline__ float sq4(f32x4 a) { return (a.x * a.x + a.y * a.y) + (a.z * a.z + a.w * a.w); }
; __device__ __forceinline__ u32x4 pack8(f32x4 a, f32x4 b) { u32x4 o; o.x = cvt_pk(a.x, a.y); o.y = cvt_pk(a.z, a.w); o.z = cvt_pk(b.x, b.y); o.w = cvt_pk(b.z, b.w); return o; }
; __device__ __forceinline__ float rstd_of(const float* SS, int row, float invw) { return 1.0f / sqrtf(SS[row] * invw + EPS); }
;     __device__ __forceinline__ void operator()(const f32x4 (&acc)[2][2][4][2], const pg8::Unit& u, int wr, int wc, int fr, int fq) const {
;         const int row0 = u.pm * 256 + wr * 64 + fr, col0 = u.pn * 256 + wc * 32 + 8 * fq;
; #pragma unroll
;         for (int ai = 0; ai < 2; ++ai)
; #pragma unroll
;             for (int m = 0; m < 4; ++m) {
;                 const int row = row0 + ai * 128 + m * 16; float ssq = 0.f;
;                 const float rb = rstd_of(SSB, row, 1.f / 512.f);
; #pragma unroll
;                 for (int bj = 0; bj < 2; ++bj) {
;                     const size_t idx = (size_t)row * D + col0 + bj * 128;
;                     const u32x4 w = *(const u32x4*)(X + idx);
;                     const f32x4 r0 = {bflo(w.x), bfhi(w.x), bflo(w.y), bfhi(w.y)}, r1 = {bflo(w.z), bfhi(w.z), bflo(w.w), bfhi(w.w)};
;                     const f32x4 v0 = r0 + acc[ai][bj][m][0] * rb, v1 = r1 + acc[ai][bj][m][1] * rb;
;                     ssq += sq4(v0) + sq4(v1);
;                     *(u32x4*)(X + idx) = pack8(v0, v1);
;                 }
;                 row_stat_add(SS, row, ssq, fq);
;             }
;     }
.LBB0_740:
	v_lshl_add_u32 v150, s70, 8, v149
	v_ashrrev_i32_e32 v151, 31, v150
	v_lshl_add_u64 v[152:153], v[150:151], 2, s[34:35]
	global_load_dword v1, v[152:153], off
	v_lshl_or_b32 v2, s60, 8, v161
	v_lshlrev_b64 v[154:155], 11, v[150:151]
	v_ashrrev_i32_e32 v3, 31, v2
	v_lshl_add_u64 v[154:155], s[96:97], 0, v[154:155]
	v_lshl_add_u64 v[168:169], v[2:3], 1, v[154:155]
	global_load_dwordx4 v[154:157], v[168:169], off
	s_waitcnt vmcnt(0)
	v_fmamk_f32 v1, v1, 0x3b000000, v148
	v_rsq_f32_e32 v165, v1
	s_nop 0
	v_lshlrev_b32_e32 v170, 16, v154
	s_nop 0
	v_and_b32_e32 v171, 0xffff0000, v154
	v_lshlrev_b32_e32 v154, 16, v155
	v_and_b32_e32 v155, 0xffff0000, v155
	v_lshlrev_b32_e32 v172, 16, v156
	v_and_b32_e32 v173, 0xffff0000, v156
	v_lshlrev_b32_e32 v156, 16, v157
	v_and_b32_e32 v157, 0xffff0000, v157
	v_mov_b32_e32 v174, v165
	v_pk_fma_f32 v[154:155], v[130:131], v[174:175], v[154:155] op_sel_hi:[1,0,1]
	v_pk_fma_f32 v[170:171], v[128:129], v[174:175], v[170:171] op_sel_hi:[1,0,1]
	v_pk_fma_f32 v[156:157], v[126:127], v[174:175], v[156:157] op_sel_hi:[1,0,1]
	v_pk_fma_f32 v[172:173], v[124:125], v[174:175], v[172:173] op_sel_hi:[1,0,1]
	v_cvt_pk_bf16_f32 v124, v170, v171
	v_cvt_pk_bf16_f32 v125, v154, v155
	v_mul_f32_e32 v171, v171, v171
	v_cvt_pk_bf16_f32 v126, v172, v173
	v_cvt_pk_bf16_f32 v127, v156, v157
	global_load_dwordx4 v[128:131], v[168:169], off offset:256
	v_mul_f32_e32 v155, v155, v155
	v_mul_f32_e32 v173, v173, v173
	v_mul_f32_e32 v157, v157, v157
	v_fmac_f32_e32 v171, v170, v170
	v_fmac_f32_e32 v155, v154, v154
	v_fmac_f32_e32 v173, v172, v172
	v_fmac_f32_e32 v157, v156, v156
	v_add_f32_e32 v154, v171, v155
	v_add_f32_e32 v155, v173, v157
	v_add_f32_e32 v170, v154, v155
	v_and_b32_e32 v165, 64, v164
	v_xor_b32_e32 v1, 16, v164
	v_add_u32_e32 v165, 64, v165
	v_cmp_lt_i32_e32 vcc, v1, v165
	v_xor_b32_e32 v167, 32, v164
	global_store_dwordx4 v[168:169], v[124:127], off
	v_cndmask_b32_e32 v1, v164, v1, vcc
	v_lshlrev_b32_e32 v1, 2, v1
	v_cmp_lt_i32_e32 vcc, v167, v165
	s_waitcnt vmcnt(1)
	v_lshlrev_b32_e32 v154, 16, v128
	v_and_b32_e32 v155, 0xffff0000, v128
	v_lshlrev_b32_e32 v128, 16, v129
	v_and_b32_e32 v129, 0xffff0000, v129
	v_lshlrev_b32_e32 v156, 16, v130
	v_and_b32_e32 v157, 0xffff0000, v130
	v_lshlrev_b32_e32 v130, 16, v131
	v_and_b32_e32 v131, 0xffff0000, v131
	v_pk_fma_f32 v[122:123], v[122:123], v[174:175], v[128:129] op_sel_hi:[1,0,1]
	v_pk_fma_f32 v[120:121], v[120:121], v[174:175], v[154:155] op_sel_hi:[1,0,1]
	v_pk_fma_f32 v[128:129], v[118:119], v[174:175], v[130:131] op_sel_hi:[1,0,1]
	v_pk_fma_f32 v[130:131], v[116:117], v[174:175], v[156:157] op_sel_hi:[1,0,1]
	v_mul_f32_e32 v116, v121, v121
	v_mul_f32_e32 v117, v123, v123
	v_mul_f32_e32 v118, v131, v131
	v_mul_f32_e32 v119, v129, v129
	v_fmac_f32_e32 v116, v120, v120
	v_fmac_f32_e32 v117, v122, v122
	v_fmac_f32_e32 v118, v130, v130
	v_fmac_f32_e32 v119, v128, v128
	v_add_f32_e32 v116, v116, v117
	v_add_f32_e32 v117, v118, v119
	v_add_f32_e32 v116, v116, v117
	v_add_f32_e32 v116, v170, v116
	ds_bpermute_b32 v117, v1, v116
	v_cndmask_b32_e32 v118, v164, v167, vcc
	v_lshlrev_b32_e32 v118, 2, v118
	v_cvt_pk_bf16_f32 v120, v120, v121
	v_cvt_pk_bf16_f32 v121, v122, v123
	s_waitcnt lgkmcnt(0)
	v_add_f32_e32 v116, v116, v117
	ds_bpermute_b32 v117, v118, v116
	v_cvt_pk_bf16_f32 v122, v130, v131
	v_cvt_pk_bf16_f32 v123, v128, v129
	global_store_dwordx4 v[168:169], v[120:123], off offset:256
	s_and_saveexec_b64 s[0:1], s[40:41]
	s_cbranch_execz .LBB0_742
	v_lshl_add_u64 v[120:121], v[150:151], 2, s[44:45]
	s_waitcnt lgkmcnt(0)
	v_add_f32_e32 v116, v116, v117
	global_atomic_add_f32 v[120:121], v116, off
.LBB0_742:
	s_or_b64 exec, exec, s[0:1]
	v_or_b32_e32 v116, 16, v150
	s_waitcnt lgkmcnt(0)
	v_ashrrev_i32_e32 v117, 31, v116
	v_lshl_add_u64 v[120:121], v[116:117], 2, s[34:35]
	global_load_dword v119, v[120:121], off
	v_lshlrev_b64 v[120:121], 11, v[116:117]
	v_lshl_add_u64 v[120:121], s[96:97], 0, v[120:121]
	v_lshl_add_u64 v[124:125], v[2:3], 1, v[120:121]
	global_load_dwordx4 v[120:123], v[124:125], off
	s_waitcnt vmcnt(1)
	v_fmamk_f32 v119, v119, 0x3b000000, v148
	v_rsq_f32_e32 v131, v119
	s_nop 0
	s_waitcnt vmcnt(0)
	v_and_b32_e32 v127, 0xffff0000, v120
	v_lshlrev_b32_e32 v126, 16, v120
	v_lshlrev_b32_e32 v120, 16, v121
	v_and_b32_e32 v121, 0xffff0000, v121
	v_lshlrev_b32_e32 v128, 16, v122
	v_and_b32_e32 v129, 0xffff0000, v122
	v_lshlrev_b32_e32 v122, 16, v123
	v_and_b32_e32 v123, 0xffff0000, v123
	v_mov_b32_e32 v130, v131
	v_pk_fma_f32 v[120:121], v[114:115], v[130:131], v[120:121] op_sel_hi:[1,0,1]
	v_pk_fma_f32 v[126:127], v[112:113], v[130:131], v[126:127] op_sel_hi:[1,0,1]
	v_pk_fma_f32 v[122:123], v[110:111], v[130:131], v[122:123] op_sel_hi:[1,0,1]
	v_pk_fma_f32 v[128:129], v[108:109], v[130:131], v[128:129] op_sel_hi:[1,0,1]
	v_cvt_pk_bf16_f32 v108, v126, v127
	v_cvt_pk_bf16_f32 v109, v120, v121
	v_mul_f32_e32 v119, v127, v127
	v_cvt_pk_bf16_f32 v110, v128, v129
	v_cvt_pk_bf16_f32 v111, v122, v123
	global_load_dwordx4 v[112:115], v[124:125], off offset:256
	v_mul_f32_e32 v121, v121, v121
	v_mul_f32_e32 v127, v129, v129
	v_mul_f32_e32 v123, v123, v123
	v_fmac_f32_e32 v119, v126, v126
	v_fmac_f32_e32 v121, v120, v120
	v_fmac_f32_e32 v127, v128, v128
	v_fmac_f32_e32 v123, v122, v122
	v_add_f32_e32 v119, v119, v121
	v_add_f32_e32 v120, v127, v123
	v_add_f32_e32 v119, v119, v120
	global_store_dwordx4 v[124:125], v[108:111], off
	s_waitcnt vmcnt(1)
	v_lshlrev_b32_e32 v120, 16, v112
	v_and_b32_e32 v121, 0xffff0000, v112
	v_lshlrev_b32_e32 v112, 16, v113
	v_and_b32_e32 v113, 0xffff0000, v113
	v_lshlrev_b32_e32 v122, 16, v114
	v_and_b32_e32 v123, 0xffff0000, v114
	v_lshlrev_b32_e32 v114, 16, v115
	v_and_b32_e32 v115, 0xffff0000, v115
	v_pk_fma_f32 v[106:107], v[106:107], v[130:131], v[112:113] op_sel_hi:[1,0,1]
	v_pk_fma_f32 v[104:105], v[104:105], v[130:131], v[120:121] op_sel_hi:[1,0,1]
	v_pk_fma_f32 v[112:113], v[102:103], v[130:131], v[114:115] op_sel_hi:[1,0,1]
	v_pk_fma_f32 v[114:115], v[100:101], v[130:131], v[122:123] op_sel_hi:[1,0,1]
	v_mul_f32_e32 v100, v105, v105
	v_mul_f32_e32 v101, v107, v107
	v_mul_f32_e32 v102, v115, v115
	v_mul_f32_e32 v103, v113, v113
	v_fmac_f32_e32 v100, v104, v104
	v_fmac_f32_e32 v101, v106, v106
	v_fmac_f32_e32 v102, v114, v114
	v_fmac_f32_e32 v103, v112, v112
	v_add_f32_e32 v100, v100, v101
	v_add_f32_e32 v101, v102, v103
	v_add_f32_e32 v100, v100, v101
	v_add_f32_e32 v100, v119, v100
	ds_bpermute_b32 v101, v1, v100
	v_cvt_pk_bf16_f32 v102, v104, v105
	v_cvt_pk_bf16_f32 v103, v106, v107
	v_cvt_pk_bf16_f32 v104, v114, v115
	v_cvt_pk_bf16_f32 v105, v112, v113
	s_waitcnt lgkmcnt(0)
	v_add_f32_e32 v100, v100, v101
	ds_bpermute_b32 v101, v118, v100
	global_store_dwordx4 v[124:125], v[102:105], off offset:256
	s_and_saveexec_b64 s[0:1], s[40:41]
	s_cbranch_execz .LBB0_744
	v_lshl_add_u64 v[102:103], v[116:117], 2, s[44:45]
	s_waitcnt lgkmcnt(0)
	v_add_f32_e32 v100, v100, v101
	global_atomic_add_f32 v[102:103], v100, off
; __device__ __forceinline__ float sq4(f32x4 a) { return (a.x * a.x + a.y * a.y) + (a.z * a.z + a.w * a.w); }
; __device__ __forceinline__ u32x4 pack8(f32x4 a, f32x4 b) { u32x4 o; o.x = cvt_pk(a.x, a.y); o.y = cvt_pk(a.z, a.w); o.z = cvt_pk(b.x, b.y); o.w = cvt_pk(b.z, b.w); return o; }
; __device__ __forceinline__ float rstd_of(const float* SS, int row, float invw) { return 1.0f / sqrtf(SS[row] * invw + EPS); }
;     __device__ __forceinline__ void operator()(const f32x4 (&acc)[2][2][4][2], const pg8::Unit& u, int wr, int wc, int fr, int fq) const {
;         const int row0 = u.pm * 256 + wr * 64 + fr, col0 = u.pn * 256 + wc * 32 + 8 * fq;
; #pragma unroll
;         for (int ai = 0; ai < 2; ++ai)
; #pragma unroll
;             for (int m = 0; m < 4; ++m) {
;                 const int row = row0 + ai * 128 + m * 16; float ssq = 0.f;
;                 const float rb = rstd_of(SSB, row, 1.f / 512.f);
; #pragma unroll
;                 for (int bj = 0; bj < 2; ++bj) {
;                     const size_t idx = (size_t)row * D + col0 + bj * 128;
;                     const u32x4 w = *(const u32x4*)(X + idx);
;                     const f32x4 r0 = {bflo(w.x), bfhi(w.x), bflo(w.y), bfhi(w.y)}, r1 = {bflo(w.z), bfhi(w.z), bflo(w.w), bfhi(w.w)};
;                     const f32x4 v0 = r0 + acc[ai][bj][m][0] * rb, v1 = r1 + acc[ai][bj][m][1] * rb;
;                     ssq += sq4(v0) + sq4(v1);
;                     *(u32x4*)(X + idx) = pack8(v0, v1);
;                 }
;                 row_stat_add(SS, row, ssq, fq);
;             }
;     }
.LBB0_744:
	s_or_b64 exec, exec, s[0:1]
	v_or_b32_e32 v100, 32, v150
	s_waitcnt lgkmcnt(0)
	v_ashrrev_i32_e32 v101, 31, v100
	v_lshl_add_u64 v[102:103], v[100:101], 2, s[34:35]
	global_load_dword v108, v[102:103], off
	v_lshlrev_b64 v[102:103], 11, v[100:101]
	v_lshl_add_u64 v[102:103], s[96:97], 0, v[102:103]
	v_lshl_add_u64 v[106:107], v[2:3], 1, v[102:103]
	global_load_dwordx4 v[102:105], v[106:107], off
	s_waitcnt vmcnt(1)
	v_fmamk_f32 v108, v108, 0x3b000000, v148
	v_rsq_f32_e32 v113, v108
	s_nop 0
	s_waitcnt vmcnt(0)
	v_lshlrev_b32_e32 v110, 16, v104
	v_lshlrev_b32_e32 v108, 16, v102
	v_and_b32_e32 v109, 0xffff0000, v102
	v_lshlrev_b32_e32 v102, 16, v103
	v_and_b32_e32 v103, 0xffff0000, v103
	v_and_b32_e32 v111, 0xffff0000, v104
	v_lshlrev_b32_e32 v104, 16, v105
	v_and_b32_e32 v105, 0xffff0000, v105
	v_mov_b32_e32 v112, v113
	v_pk_fma_f32 v[102:103], v[98:99], v[112:113], v[102:103] op_sel_hi:[1,0,1]
	v_pk_fma_f32 v[108:109], v[96:97], v[112:113], v[108:109] op_sel_hi:[1,0,1]
	v_pk_fma_f32 v[104:105], v[94:95], v[112:113], v[104:105] op_sel_hi:[1,0,1]
	v_pk_fma_f32 v[110:111], v[92:93], v[112:113], v[110:111] op_sel_hi:[1,0,1]
	v_cvt_pk_bf16_f32 v92, v108, v109
	v_cvt_pk_bf16_f32 v93, v102, v103
	v_mul_f32_e32 v109, v109, v109
	v_cvt_pk_bf16_f32 v94, v110, v111
	v_cvt_pk_bf16_f32 v95, v104, v105
	global_load_dwordx4 v[96:99], v[106:107], off offset:256
	v_mul_f32_e32 v103, v103, v103
	v_mul_f32_e32 v111, v111, v111
	v_mul_f32_e32 v105, v105, v105
	v_fmac_f32_e32 v109, v108, v108
	v_fmac_f32_e32 v103, v102, v102
	v_fmac_f32_e32 v111, v110, v110
	v_fmac_f32_e32 v105, v104, v104
	v_add_f32_e32 v102, v109, v103
	v_add_f32_e32 v103, v111, v105
	v_add_f32_e32 v108, v102, v103
	global_store_dwordx4 v[106:107], v[92:95], off
	s_waitcnt vmcnt(1)
	v_lshlrev_b32_e32 v102, 16, v96
	v_and_b32_e32 v103, 0xffff0000, v96
	v_lshlrev_b32_e32 v96, 16, v97
	v_and_b32_e32 v97, 0xffff0000, v97
	v_lshlrev_b32_e32 v104, 16, v98
	v_and_b32_e32 v105, 0xffff0000, v98
	v_lshlrev_b32_e32 v98, 16, v99
	v_and_b32_e32 v99, 0xffff0000, v99
	v_pk_fma_f32 v[90:91], v[90:91], v[112:113], v[96:97] op_sel_hi:[1,0,1]
	v_pk_fma_f32 v[88:89], v[88:89], v[112:113], v[102:103] op_sel_hi:[1,0,1]
	v_pk_fma_f32 v[96:97], v[86:87], v[112:113], v[98:99] op_sel_hi:[1,0,1]
	v_pk_fma_f32 v[98:99], v[84:85], v[112:113], v[104:105] op_sel_hi:[1,0,1]
	v_mul_f32_e32 v84, v89, v89
	v_mul_f32_e32 v85, v91, v91
	v_mul_f32_e32 v86, v99, v99
	v_mul_f32_e32 v87, v97, v97
	v_fmac_f32_e32 v84, v88, v88
	v_fmac_f32_e32 v85, v90, v90
	v_fmac_f32_e32 v86, v98, v98
	v_fmac_f32_e32 v87, v96, v96
	v_add_f32_e32 v84, v84, v85
	v_add_f32_e32 v85, v86, v87
	v_add_f32_e32 v84, v84, v85
	v_add_f32_e32 v84, v108, v84
	ds_bpermute_b32 v85, v1, v84
	v_cvt_pk_bf16_f32 v86, v88, v89
	v_cvt_pk_bf16_f32 v87, v90, v91
	v_cvt_pk_bf16_f32 v88, v98, v99
	v_cvt_pk_bf16_f32 v89, v96, v97
	s_waitcnt lgkmcnt(0)
	v_add_f32_e32 v84, v84, v85
	ds_bpermute_b32 v85, v118, v84
	global_store_dwordx4 v[106:107], v[86:89], off offset:256
	s_and_saveexec_b64 s[0:1], s[40:41]
	s_cbranch_execz .LBB0_746
	v_lshl_add_u64 v[86:87], v[100:101], 2, s[44:45]
	s_waitcnt lgkmcnt(0)
	v_add_f32_e32 v84, v84, v85
	global_atomic_add_f32 v[86:87], v84, off
.LBB0_746:
	s_or_b64 exec, exec, s[0:1]
	v_or_b32_e32 v84, 48, v150
	s_waitcnt lgkmcnt(0)
	v_ashrrev_i32_e32 v85, 31, v84
	v_lshl_add_u64 v[86:87], v[84:85], 2, s[34:35]
	global_load_dword v92, v[86:87], off
	v_lshlrev_b64 v[86:87], 11, v[84:85]
	v_lshl_add_u64 v[86:87], s[96:97], 0, v[86:87]
	v_lshl_add_u64 v[90:91], v[2:3], 1, v[86:87]
	global_load_dwordx4 v[86:89], v[90:91], off
	s_waitcnt vmcnt(1)
	v_fmamk_f32 v92, v92, 0x3b000000, v148
	v_rsq_f32_e32 v97, v92
	s_nop 0
	s_waitcnt vmcnt(0)
	v_lshlrev_b32_e32 v94, 16, v88
	v_lshlrev_b32_e32 v92, 16, v86
	v_and_b32_e32 v93, 0xffff0000, v86
	v_lshlrev_b32_e32 v86, 16, v87
	v_and_b32_e32 v87, 0xffff0000, v87
	v_and_b32_e32 v95, 0xffff0000, v88
	v_lshlrev_b32_e32 v88, 16, v89
	v_and_b32_e32 v89, 0xffff0000, v89
	v_mov_b32_e32 v96, v97
	v_pk_fma_f32 v[86:87], v[82:83], v[96:97], v[86:87] op_sel_hi:[1,0,1]
	v_pk_fma_f32 v[92:93], v[80:81], v[96:97], v[92:93] op_sel_hi:[1,0,1]
	v_pk_fma_f32 v[88:89], v[78:79], v[96:97], v[88:89] op_sel_hi:[1,0,1]
	v_pk_fma_f32 v[94:95], v[76:77], v[96:97], v[94:95] op_sel_hi:[1,0,1]
	v_cvt_pk_bf16_f32 v76, v92, v93
	v_cvt_pk_bf16_f32 v77, v86, v87
	v_mul_f32_e32 v93, v93, v93
	v_cvt_pk_bf16_f32 v78, v94, v95
	v_cvt_pk_bf16_f32 v79, v88, v89
	global_load_dwordx4 v[80:83], v[90:91], off offset:256
	v_mul_f32_e32 v87, v87, v87
	v_mul_f32_e32 v95, v95, v95
	v_mul_f32_e32 v89, v89, v89
	v_fmac_f32_e32 v93, v92, v92
	v_fmac_f32_e32 v87, v86, v86
	v_fmac_f32_e32 v95, v94, v94
	v_fmac_f32_e32 v89, v88, v88
	v_add_f32_e32 v86, v93, v87
	v_add_f32_e32 v87, v95, v89
	v_add_f32_e32 v92, v86, v87
	global_store_dwordx4 v[90:91], v[76:79], off
	s_waitcnt vmcnt(1)
	v_lshlrev_b32_e32 v86, 16, v80
	v_and_b32_e32 v87, 0xffff0000, v80
	v_lshlrev_b32_e32 v80, 16, v81
	v_and_b32_e32 v81, 0xffff0000, v81
	v_lshlrev_b32_e32 v88, 16, v82
	v_and_b32_e32 v89, 0xffff0000, v82
	v_lshlrev_b32_e32 v82, 16, v83
	v_and_b32_e32 v83, 0xffff0000, v83
	v_pk_fma_f32 v[74:75], v[74:75], v[96:97], v[80:81] op_sel_hi:[1,0,1]
	v_pk_fma_f32 v[72:73], v[72:73], v[96:97], v[86:87] op_sel_hi:[1,0,1]
	v_pk_fma_f32 v[80:81], v[70:71], v[96:97], v[82:83] op_sel_hi:[1,0,1]
	v_pk_fma_f32 v[82:83], v[68:69], v[96:97], v[88:89] op_sel_hi:[1,0,1]
	v_mul_f32_e32 v68, v73, v73
	v_mul_f32_e32 v69, v75, v75
	v_mul_f32_e32 v70, v83, v83
	v_mul_f32_e32 v71, v81, v81
	v_fmac_f32_e32 v68, v72, v72
	v_fmac_f32_e32 v69, v74, v74
	v_fmac_f32_e32 v70, v82, v82
	v_fmac_f32_e32 v71, v80, v80
	v_add_f32_e32 v68, v68, v69
	v_add_f32_e32 v69, v70, v71
	v_add_f32_e32 v68, v68, v69
	v_add_f32_e32 v68, v92, v68
	ds_bpermute_b32 v69, v1, v68
	v_cvt_pk_bf16_f32 v70, v72, v73
	v_cvt_pk_bf16_f32 v71, v74, v75
	v_cvt_pk_bf16_f32 v72, v82, v83
	v_cvt_pk_bf16_f32 v73, v80, v81
	s_waitcnt lgkmcnt(0)
	v_add_f32_e32 v68, v68, v69
	ds_bpermute_b32 v69, v118, v68
	global_store_dwordx4 v[90:91], v[70:73], off offset:256
	s_and_saveexec_b64 s[0:1], s[40:41]
	s_cbranch_execz .LBB0_748
	v_lshl_add_u64 v[70:71], v[84:85], 2, s[44:45]
	s_waitcnt lgkmcnt(0)
	v_add_f32_e32 v68, v68, v69
	global_atomic_add_f32 v[70:71], v68, off
; __device__ __forceinline__ float sq4(f32x4 a) { return (a.x * a.x + a.y * a.y) + (a.z * a.z + a.w * a.w); }
; __device__ __forceinline__ u32x4 pack8(f32x4 a, f32x4 b) { u32x4 o; o.x = cvt_pk(a.x, a.y); o.y = cvt_pk(a.z, a.w); o.z = cvt_pk(b.x, b.y); o.w = cvt_pk(b.z, b.w); return o; }
; __device__ __forceinline__ float rstd_of(const float* SS, int row, float invw) { return 1.0f / sqrtf(SS[row] * invw + EPS); }
;     __device__ __forceinline__ void operator()(const f32x4 (&acc)[2][2][4][2], const pg8::Unit& u, int wr, int wc, int fr, int fq) const {
;         const int row0 = u.pm * 256 + wr * 64 + fr, col0 = u.pn * 256 + wc * 32 + 8 * fq;
; #pragma unroll
;         for (int ai = 0; ai < 2; ++ai)
; #pragma unroll
;             for (int m = 0; m < 4; ++m) {
;                 const int row = row0 + ai * 128 + m * 16; float ssq = 0.f;
;                 const float rb = rstd_of(SSB, row, 1.f / 512.f);
; #pragma unroll
;                 for (int bj = 0; bj < 2; ++bj) {
;                     const size_t idx = (size_t)row * D + col0 + bj * 128;
;                     const u32x4 w = *(const u32x4*)(X + idx);
;                     const f32x4 r0 = {bflo(w.x), bfhi(w.x), bflo(w.y), bfhi(w.y)}, r1 = {bflo(w.z), bfhi(w.z), bflo(w.w), bfhi(w.w)};
;                     const f32x4 v0 = r0 + acc[ai][bj][m][0] * rb, v1 = r1 + acc[ai][bj][m][1] * rb;
;                     ssq += sq4(v0) + sq4(v1);
;                     *(u32x4*)(X + idx) = pack8(v0, v1);
;                 }
;                 row_stat_add(SS, row, ssq, fq);
;             }
;     }
.LBB0_748:
	s_or_b64 exec, exec, s[0:1]
	global_load_dword v76, v[152:153], off offset:512
	v_add_u32_e32 v68, 0x80, v150
	s_waitcnt lgkmcnt(0)
	v_ashrrev_i32_e32 v69, 31, v68
	v_lshlrev_b64 v[70:71], 11, v[68:69]
	v_lshl_add_u64 v[70:71], s[96:97], 0, v[70:71]
	v_lshl_add_u64 v[74:75], v[2:3], 1, v[70:71]
	global_load_dwordx4 v[70:73], v[74:75], off
	s_waitcnt vmcnt(1)
	v_fmamk_f32 v76, v76, 0x3b000000, v148
	v_rsq_f32_e32 v81, v76
	s_nop 0
	s_waitcnt vmcnt(0)
	v_lshlrev_b32_e32 v78, 16, v72
	v_lshlrev_b32_e32 v76, 16, v70
	v_and_b32_e32 v77, 0xffff0000, v70
	v_lshlrev_b32_e32 v70, 16, v71
	v_and_b32_e32 v71, 0xffff0000, v71
	v_and_b32_e32 v79, 0xffff0000, v72
	v_lshlrev_b32_e32 v72, 16, v73
	v_and_b32_e32 v73, 0xffff0000, v73
	v_mov_b32_e32 v80, v81
	v_pk_fma_f32 v[70:71], v[66:67], v[80:81], v[70:71] op_sel_hi:[1,0,1]
	v_pk_fma_f32 v[76:77], v[64:65], v[80:81], v[76:77] op_sel_hi:[1,0,1]
	v_pk_fma_f32 v[72:73], v[62:63], v[80:81], v[72:73] op_sel_hi:[1,0,1]
	v_pk_fma_f32 v[78:79], v[60:61], v[80:81], v[78:79] op_sel_hi:[1,0,1]
	v_cvt_pk_bf16_f32 v60, v76, v77
	v_cvt_pk_bf16_f32 v61, v70, v71
	v_mul_f32_e32 v77, v77, v77
	v_cvt_pk_bf16_f32 v62, v78, v79
	v_cvt_pk_bf16_f32 v63, v72, v73
	global_load_dwordx4 v[64:67], v[74:75], off offset:256
	v_mul_f32_e32 v71, v71, v71
	v_mul_f32_e32 v79, v79, v79
	v_mul_f32_e32 v73, v73, v73
	v_fmac_f32_e32 v77, v76, v76
	v_fmac_f32_e32 v71, v70, v70
	v_fmac_f32_e32 v79, v78, v78
	v_fmac_f32_e32 v73, v72, v72
	v_add_f32_e32 v70, v77, v71
	v_add_f32_e32 v71, v79, v73
	v_add_f32_e32 v76, v70, v71
	global_store_dwordx4 v[74:75], v[60:63], off
	s_waitcnt vmcnt(1)
	v_lshlrev_b32_e32 v70, 16, v64
	v_and_b32_e32 v71, 0xffff0000, v64
	v_lshlrev_b32_e32 v64, 16, v65
	v_and_b32_e32 v65, 0xffff0000, v65
	v_lshlrev_b32_e32 v72, 16, v66
	v_and_b32_e32 v73, 0xffff0000, v66
	v_lshlrev_b32_e32 v66, 16, v67
	v_and_b32_e32 v67, 0xffff0000, v67
	v_pk_fma_f32 v[58:59], v[58:59], v[80:81], v[64:65] op_sel_hi:[1,0,1]
	v_pk_fma_f32 v[56:57], v[56:57], v[80:81], v[70:71] op_sel_hi:[1,0,1]
	v_pk_fma_f32 v[64:65], v[54:55], v[80:81], v[66:67] op_sel_hi:[1,0,1]
	v_pk_fma_f32 v[66:67], v[52:53], v[80:81], v[72:73] op_sel_hi:[1,0,1]
	v_mul_f32_e32 v52, v57, v57
	v_mul_f32_e32 v53, v59, v59
	v_mul_f32_e32 v54, v67, v67
	v_mul_f32_e32 v55, v65, v65
	v_fmac_f32_e32 v52, v56, v56
	v_fmac_f32_e32 v53, v58, v58
	v_fmac_f32_e32 v54, v66, v66
	v_fmac_f32_e32 v55, v64, v64
	v_add_f32_e32 v52, v52, v53
	v_add_f32_e32 v53, v54, v55
	v_add_f32_e32 v52, v52, v53
	v_add_f32_e32 v52, v76, v52
	ds_bpermute_b32 v53, v1, v52
	v_cvt_pk_bf16_f32 v54, v56, v57
	v_cvt_pk_bf16_f32 v55, v58, v59
	v_cvt_pk_bf16_f32 v56, v66, v67
	v_cvt_pk_bf16_f32 v57, v64, v65
	s_waitcnt lgkmcnt(0)
	v_add_f32_e32 v52, v52, v53
	ds_bpermute_b32 v53, v118, v52
	global_store_dwordx4 v[74:75], v[54:57], off offset:256
	s_and_saveexec_b64 s[0:1], s[40:41]
	s_cbranch_execz .LBB0_750
	v_lshl_add_u64 v[54:55], v[68:69], 2, s[44:45]
	s_waitcnt lgkmcnt(0)
	v_add_f32_e32 v52, v52, v53
	global_atomic_add_f32 v[54:55], v52, off
; __device__ __forceinline__ float sq4(f32x4 a) { return (a.x * a.x + a.y * a.y) + (a.z * a.z + a.w * a.w); }
; __device__ __forceinline__ u32x4 pack8(f32x4 a, f32x4 b) { u32x4 o; o.x = cvt_pk(a.x, a.y); o.y = cvt_pk(a.z, a.w); o.z = cvt_pk(b.x, b.y); o.w = cvt_pk(b.z, b.w); return o; }
; __device__ __forceinline__ float rstd_of(const float* SS, int row, float invw) { return 1.0f / sqrtf(SS[row] * invw + EPS); }
;     __device__ __forceinline__ void operator()(const f32x4 (&acc)[2][2][4][2], const pg8::Unit& u, int wr, int wc, int fr, int fq) const {
;         const int row0 = u.pm * 256 + wr * 64 + fr, col0 = u.pn * 256 + wc * 32 + 8 * fq;
; #pragma unroll
;         for (int ai = 0; ai < 2; ++ai)
; #pragma unroll
;             for (int m = 0; m < 4; ++m) {
;                 const int row = row0 + ai * 128 + m * 16; float ssq = 0.f;
;                 const float rb = rstd_of(SSB, row, 1.f / 512.f);
; #pragma unroll
;                 for (int bj = 0; bj < 2; ++bj) {
;                     const size_t idx = (size_t)row * D + col0 + bj * 128;
;                     const u32x4 w = *(const u32x4*)(X + idx);
;                     const f32x4 r0 = {bflo(w.x), bfhi(w.x), bflo(w.y), bfhi(w.y)}, r1 = {bflo(w.z), bfhi(w.z), bflo(w.w), bfhi(w.w)};
;                     const f32x4 v0 = r0 + acc[ai][bj][m][0] * rb, v1 = r1 + acc[ai][bj][m][1] * rb;
;                     ssq += sq4(v0) + sq4(v1);
;                     *(u32x4*)(X + idx) = pack8(v0, v1);
;                 }
;                 row_stat_add(SS, row, ssq, fq);
;             }
;     }
.LBB0_750:
	s_or_b64 exec, exec, s[0:1]
	global_load_dword v60, v[152:153], off offset:576
	v_add_u32_e32 v52, 0x90, v150
	s_waitcnt lgkmcnt(0)
	v_ashrrev_i32_e32 v53, 31, v52
	v_lshlrev_b64 v[54:55], 11, v[52:53]
	v_lshl_add_u64 v[54:55], s[96:97], 0, v[54:55]
	v_lshl_add_u64 v[58:59], v[2:3], 1, v[54:55]
	global_load_dwordx4 v[54:57], v[58:59], off
	s_waitcnt vmcnt(1)
	v_fmamk_f32 v60, v60, 0x3b000000, v148
	v_rsq_f32_e32 v65, v60
	s_nop 0
	s_waitcnt vmcnt(0)
	v_lshlrev_b32_e32 v62, 16, v56
	v_lshlrev_b32_e32 v60, 16, v54
	v_and_b32_e32 v61, 0xffff0000, v54
	v_lshlrev_b32_e32 v54, 16, v55
	v_and_b32_e32 v55, 0xffff0000, v55
	v_and_b32_e32 v63, 0xffff0000, v56
	v_lshlrev_b32_e32 v56, 16, v57
	v_and_b32_e32 v57, 0xffff0000, v57
	v_mov_b32_e32 v64, v65
	v_pk_fma_f32 v[54:55], v[50:51], v[64:65], v[54:55] op_sel_hi:[1,0,1]
	v_pk_fma_f32 v[60:61], v[48:49], v[64:65], v[60:61] op_sel_hi:[1,0,1]
	v_pk_fma_f32 v[56:57], v[46:47], v[64:65], v[56:57] op_sel_hi:[1,0,1]
	v_pk_fma_f32 v[62:63], v[44:45], v[64:65], v[62:63] op_sel_hi:[1,0,1]
	v_cvt_pk_bf16_f32 v44, v60, v61
	v_cvt_pk_bf16_f32 v45, v54, v55
	v_mul_f32_e32 v61, v61, v61
	v_cvt_pk_bf16_f32 v46, v62, v63
	v_cvt_pk_bf16_f32 v47, v56, v57
	global_load_dwordx4 v[48:51], v[58:59], off offset:256
	v_mul_f32_e32 v55, v55, v55
	v_mul_f32_e32 v63, v63, v63
	v_mul_f32_e32 v57, v57, v57
	v_fmac_f32_e32 v61, v60, v60
	v_fmac_f32_e32 v55, v54, v54
	v_fmac_f32_e32 v63, v62, v62
	v_fmac_f32_e32 v57, v56, v56
	v_add_f32_e32 v54, v61, v55
	v_add_f32_e32 v55, v63, v57
	v_add_f32_e32 v60, v54, v55
	global_store_dwordx4 v[58:59], v[44:47], off
	s_waitcnt vmcnt(1)
	v_lshlrev_b32_e32 v54, 16, v48
	v_and_b32_e32 v55, 0xffff0000, v48
	v_lshlrev_b32_e32 v48, 16, v49
	v_and_b32_e32 v49, 0xffff0000, v49
	v_lshlrev_b32_e32 v56, 16, v50
	v_and_b32_e32 v57, 0xffff0000, v50
	v_lshlrev_b32_e32 v50, 16, v51
	v_and_b32_e32 v51, 0xffff0000, v51
	v_pk_fma_f32 v[42:43], v[42:43], v[64:65], v[48:49] op_sel_hi:[1,0,1]
	v_pk_fma_f32 v[40:41], v[40:41], v[64:65], v[54:55] op_sel_hi:[1,0,1]
	v_pk_fma_f32 v[48:49], v[38:39], v[64:65], v[50:51] op_sel_hi:[1,0,1]
	v_pk_fma_f32 v[50:51], v[36:37], v[64:65], v[56:57] op_sel_hi:[1,0,1]
	v_mul_f32_e32 v36, v41, v41
	v_mul_f32_e32 v37, v43, v43
	v_mul_f32_e32 v38, v51, v51
	v_mul_f32_e32 v39, v49, v49
	v_fmac_f32_e32 v36, v40, v40
	v_fmac_f32_e32 v37, v42, v42
	v_fmac_f32_e32 v38, v50, v50
	v_fmac_f32_e32 v39, v48, v48
	v_add_f32_e32 v36, v36, v37
	v_add_f32_e32 v37, v38, v39
	v_add_f32_e32 v36, v36, v37
	v_add_f32_e32 v36, v60, v36
	ds_bpermute_b32 v37, v1, v36
	v_cvt_pk_bf16_f32 v38, v40, v41
	v_cvt_pk_bf16_f32 v39, v42, v43
	v_cvt_pk_bf16_f32 v40, v50, v51
	v_cvt_pk_bf16_f32 v41, v48, v49
	s_waitcnt lgkmcnt(0)
	v_add_f32_e32 v36, v36, v37
	ds_bpermute_b32 v37, v118, v36
	global_store_dwordx4 v[58:59], v[38:41], off offset:256
	s_and_saveexec_b64 s[0:1], s[40:41]
	s_cbranch_execz .LBB0_752
	v_lshl_add_u64 v[38:39], v[52:53], 2, s[44:45]
	s_waitcnt lgkmcnt(0)
	v_add_f32_e32 v36, v36, v37
	global_atomic_add_f32 v[38:39], v36, off
.LBB0_752:
	s_or_b64 exec, exec, s[0:1]
	global_load_dword v44, v[152:153], off offset:640
	v_add_u32_e32 v36, 0xa0, v150
	s_waitcnt lgkmcnt(0)
	v_ashrrev_i32_e32 v37, 31, v36
	v_lshlrev_b64 v[38:39], 11, v[36:37]
	v_lshl_add_u64 v[38:39], s[96:97], 0, v[38:39]
	v_lshl_add_u64 v[42:43], v[2:3], 1, v[38:39]
	global_load_dwordx4 v[38:41], v[42:43], off
	s_waitcnt vmcnt(1)
	v_fmamk_f32 v44, v44, 0x3b000000, v148
	v_rsq_f32_e32 v49, v44
	s_nop 0
	s_waitcnt vmcnt(0)
	v_lshlrev_b32_e32 v46, 16, v40
	v_lshlrev_b32_e32 v44, 16, v38
	v_and_b32_e32 v45, 0xffff0000, v38
	v_lshlrev_b32_e32 v38, 16, v39
	v_and_b32_e32 v39, 0xffff0000, v39
	v_and_b32_e32 v47, 0xffff0000, v40
	v_lshlrev_b32_e32 v40, 16, v41
	v_and_b32_e32 v41, 0xffff0000, v41
	v_mov_b32_e32 v48, v49
	v_pk_fma_f32 v[38:39], v[34:35], v[48:49], v[38:39] op_sel_hi:[1,0,1]
	v_pk_fma_f32 v[44:45], v[32:33], v[48:49], v[44:45] op_sel_hi:[1,0,1]
	v_pk_fma_f32 v[40:41], v[30:31], v[48:49], v[40:41] op_sel_hi:[1,0,1]
	v_pk_fma_f32 v[46:47], v[28:29], v[48:49], v[46:47] op_sel_hi:[1,0,1]
	v_cvt_pk_bf16_f32 v28, v44, v45
	v_cvt_pk_bf16_f32 v29, v38, v39
	v_mul_f32_e32 v45, v45, v45
	v_cvt_pk_bf16_f32 v30, v46, v47
	v_cvt_pk_bf16_f32 v31, v40, v41
	global_load_dwordx4 v[32:35], v[42:43], off offset:256
	v_mul_f32_e32 v39, v39, v39
	v_mul_f32_e32 v47, v47, v47
	v_mul_f32_e32 v41, v41, v41
	v_fmac_f32_e32 v45, v44, v44
	v_fmac_f32_e32 v39, v38, v38
	v_fmac_f32_e32 v47, v46, v46
	v_fmac_f32_e32 v41, v40, v40
	v_add_f32_e32 v38, v45, v39
	v_add_f32_e32 v39, v47, v41
	v_add_f32_e32 v44, v38, v39
	global_store_dwordx4 v[42:43], v[28:31], off
	s_waitcnt vmcnt(1)
	v_lshlrev_b32_e32 v38, 16, v32
	v_and_b32_e32 v39, 0xffff0000, v32
	v_lshlrev_b32_e32 v32, 16, v33
	v_and_b32_e32 v33, 0xffff0000, v33
	v_lshlrev_b32_e32 v40, 16, v34
	v_and_b32_e32 v41, 0xffff0000, v34
	v_lshlrev_b32_e32 v34, 16, v35
	v_and_b32_e32 v35, 0xffff0000, v35
	v_pk_fma_f32 v[26:27], v[26:27], v[48:49], v[32:33] op_sel_hi:[1,0,1]
	v_pk_fma_f32 v[24:25], v[24:25], v[48:49], v[38:39] op_sel_hi:[1,0,1]
	v_pk_fma_f32 v[32:33], v[22:23], v[48:49], v[34:35] op_sel_hi:[1,0,1]
	v_pk_fma_f32 v[34:35], v[20:21], v[48:49], v[40:41] op_sel_hi:[1,0,1]
	v_mul_f32_e32 v20, v25, v25
	v_mul_f32_e32 v21, v27, v27
	v_mul_f32_e32 v22, v35, v35
	v_mul_f32_e32 v23, v33, v33
	v_fmac_f32_e32 v20, v24, v24
	v_fmac_f32_e32 v21, v26, v26
	v_fmac_f32_e32 v22, v34, v34
	v_fmac_f32_e32 v23, v32, v32
	v_add_f32_e32 v20, v20, v21
	v_add_f32_e32 v21, v22, v23
	v_add_f32_e32 v20, v20, v21
	v_add_f32_e32 v20, v44, v20
	ds_bpermute_b32 v21, v1, v20
	v_cvt_pk_bf16_f32 v22, v24, v25
	v_cvt_pk_bf16_f32 v23, v26, v27
	v_cvt_pk_bf16_f32 v24, v34, v35
	v_cvt_pk_bf16_f32 v25, v32, v33
	s_waitcnt lgkmcnt(0)
	v_add_f32_e32 v20, v20, v21
	ds_bpermute_b32 v21, v118, v20
	global_store_dwordx4 v[42:43], v[22:25], off offset:256
	s_and_saveexec_b64 s[0:1], s[40:41]
	s_cbranch_execz .LBB0_754
	v_lshl_add_u64 v[22:23], v[36:37], 2, s[44:45]
	s_waitcnt lgkmcnt(0)
	v_add_f32_e32 v20, v20, v21
	global_atomic_add_f32 v[22:23], v20, off

; __device__ __forceinline__ int opaque_tid() { int t = threadIdx.x; asm volatile("" : "+v"(t)); return t; }
; __device__ __forceinline__ void final_phase(const bf16_t* X, const float* SS, const float* gain, float* out, int G) {
;     const int tid_ = opaque_tid(), lane = tid_ & 63, gw = blockIdx.x * 8 + (tid_ >> 6), NGW = G * 8;
;     const f32x4* g4 = (const f32x4*)gain;
;     const f32x4 ga0 = g4[2 * lane], ga1 = g4[2 * lane + 1], gb0 = g4[128 + 2 * lane], gb1 = g4[129 + 2 * lane];
;     for (int m = gw; m < M; m += 4 * NGW) {
;         u32x4 a[4], b[4]; float sv[4];
; #pragma unroll
;         for (int k = 0; k < 4; ++k) { const int mm = (m + k * NGW < M) ? m + k * NGW : m; const bf16_t* x = X + (size_t)mm * D;
;             a[k] = *(const u32x4*)(x + 8 * lane); b[k] = *(const u32x4*)(x + 512 + 8 * lane); sv[k] = SS[mm]; }
; #pragma unroll
;         for (int k = 0; k < 4; ++k) { const int mm = m + k * NGW; if (mm < M) {
;             f32x4* o4 = (f32x4*)(out + (size_t)mm * D);
;             const float r = 1.0f / sqrtf(sv[k] * (1.f / 1024.f) + EPS);
;             const f32x4 a0 = {bflo(a[k].x), bfhi(a[k].x), bflo(a[k].y), bfhi(a[k].y)}, a1 = {bflo(a[k].z), bfhi(a[k].z), bflo(a[k].w), bfhi(a[k].w)};
;             const f32x4 b0 = {bflo(b[k].x), bfhi(b[k].x), bflo(b[k].y), bfhi(b[k].y)}, b1 = {bflo(b[k].z), bfhi(b[k].z), bflo(b[k].w), bfhi(b[k].w)};
;             o4[2 * lane] = a0 * r * ga0; o4[2 * lane + 1] = a1 * r * ga1; o4[128 + 2 * lane] = b0 * r * gb0; o4[129 + 2 * lane] = b1 * r * gb1; } }
;     }
.LBB0_986:
	global_load_dword v82, v[48:49], off
	global_load_dwordx4 v[62:65], v[52:53], off offset:-1024
	global_load_dwordx4 v[66:69], v[52:53], off
	s_waitcnt vmcnt(7)
	v_add_u32_e32 v16, s21, v40
	v_add_u32_e32 v58, s9, v40
	v_add_u32_e32 v56, s22, v40
	v_cmp_gt_i32_e64 s[4:5], s20, v16
	v_cmp_gt_i32_e64 s[2:3], s20, v58
	v_cmp_gt_i32_e64 s[0:1], s20, v56
	v_cndmask_b32_e64 v16, v40, v16, s[4:5]
	v_cndmask_b32_e64 v18, v40, v58, s[2:3]
	v_cndmask_b32_e64 v20, v40, v56, s[0:1]
	v_ashrrev_i32_e32 v17, 31, v16
	v_ashrrev_i32_e32 v19, 31, v18
	v_ashrrev_i32_e32 v21, 31, v20
	v_lshlrev_b64 v[22:23], 11, v[16:17]
	v_lshl_add_u64 v[70:71], v[16:17], 2, s[12:13]
	v_lshlrev_b64 v[16:17], 11, v[18:19]
	v_lshl_add_u64 v[72:73], v[18:19], 2, s[12:13]
	v_lshlrev_b64 v[18:19], 11, v[20:21]
	v_lshl_add_u64 v[74:75], v[20:21], 2, s[12:13]
	v_lshl_add_u64 v[76:77], v[44:45], 0, v[22:23]
	v_lshl_add_u64 v[78:79], v[44:45], 0, v[16:17]
	v_lshl_add_u64 v[80:81], v[44:45], 0, v[18:19]
	global_load_dword v57, v[74:75], off
	global_load_dwordx4 v[36:39], v[76:77], off
	global_load_dwordx4 v[32:35], v[76:77], off offset:1024
	global_load_dword v61, v[70:71], off
	global_load_dwordx4 v[28:31], v[78:79], off
	global_load_dwordx4 v[24:27], v[78:79], off offset:1024
	global_load_dword v59, v[72:73], off
	global_load_dwordx4 v[20:23], v[80:81], off
	global_load_dwordx4 v[16:19], v[80:81], off offset:1024
	v_lshl_add_u64 v[78:79], v[50:51], 0, v[42:43]
	s_waitcnt vmcnt(11)
	v_fmamk_f32 v76, v82, 0x3a800000, v41
	v_mul_f32_e32 v77, 0x4f800000, v76
	v_cmp_gt_f32_e32 vcc, s23, v76
	s_waitcnt vmcnt(10)
	v_lshlrev_b32_e32 v70, 16, v62
	v_and_b32_e32 v71, 0xffff0000, v62
	v_cndmask_b32_e32 v80, v76, v77, vcc
	v_sqrt_f32_e32 v81, v80
	v_lshlrev_b32_e32 v62, 16, v63
	v_and_b32_e32 v63, 0xffff0000, v63
	v_lshlrev_b32_e32 v72, 16, v64
	v_add_u32_e32 v82, -1, v81
	v_add_u32_e32 v83, 1, v81
	v_fma_f32 v84, -v82, v81, v80
	v_fma_f32 v85, -v83, v81, v80
	v_cmp_ge_f32_e64 s[6:7], 0, v84
	v_and_b32_e32 v73, 0xffff0000, v64
	v_lshlrev_b32_e32 v64, 16, v65
	v_cndmask_b32_e64 v81, v81, v82, s[6:7]
	v_cmp_lt_f32_e64 s[6:7], 0, v85
	v_and_b32_e32 v65, 0xffff0000, v65
	s_waitcnt vmcnt(9)
	v_lshlrev_b32_e32 v74, 16, v66
	v_cndmask_b32_e64 v81, v81, v83, s[6:7]
	v_mul_f32_e32 v82, 0x37800000, v81
	v_cndmask_b32_e32 v81, v81, v82, vcc
	v_cmp_class_f32_e32 vcc, v80, v60
	v_and_b32_e32 v75, 0xffff0000, v66
	v_lshlrev_b32_e32 v66, 16, v67
	v_cndmask_b32_e32 v80, v81, v80, vcc
	v_div_scale_f32 v81, s[6:7], v80, v80, 1.0
	v_rcp_f32_e32 v82, v81
	v_div_scale_f32 v83, vcc, 1.0, v80, 1.0
	v_and_b32_e32 v67, 0xffff0000, v67
	v_fma_f32 v84, -v81, v82, 1.0
	v_fmac_f32_e32 v82, v84, v82
	v_mul_f32_e32 v84, v83, v82
	v_fma_f32 v85, -v81, v84, v83
	v_fmac_f32_e32 v84, v85, v82
	v_fma_f32 v81, -v81, v84, v83
	v_div_fmas_f32 v81, v81, v82, v84
	v_div_fixup_f32 v80, v81, v80, 1.0
	v_lshlrev_b32_e32 v76, 16, v68
	v_and_b32_e32 v77, 0xffff0000, v68
	v_lshlrev_b32_e32 v68, 16, v69
	v_and_b32_e32 v69, 0xffff0000, v69
	v_pk_mul_f32 v[70:71], v[80:81], v[70:71] op_sel_hi:[0,1]
	v_pk_mul_f32 v[62:63], v[80:81], v[62:63] op_sel_hi:[0,1]
	v_pk_mul_f32 v[72:73], v[80:81], v[72:73] op_sel_hi:[0,1]
	v_pk_mul_f32 v[82:83], v[80:81], v[64:65] op_sel_hi:[0,1]
	v_pk_mul_f32 v[74:75], v[80:81], v[74:75] op_sel_hi:[0,1]
	v_pk_mul_f32 v[84:85], v[80:81], v[66:67] op_sel_hi:[0,1]
	v_pk_mul_f32 v[86:87], v[80:81], v[76:77] op_sel_hi:[0,1]
	v_pk_mul_f32 v[76:77], v[80:81], v[68:69] op_sel_hi:[0,1]
	v_pk_mul_f32 v[64:65], v[6:7], v[62:63]
	v_pk_mul_f32 v[62:63], v[4:5], v[70:71]
	v_pk_mul_f32 v[68:69], v[2:3], v[82:83]
	v_pk_mul_f32 v[66:67], v[0:1], v[72:73]
	v_pk_mul_f32 v[72:73], v[14:15], v[84:85]
	v_pk_mul_f32 v[70:71], v[12:13], v[74:75]
	v_pk_mul_f32 v[76:77], v[10:11], v[76:77]
	v_pk_mul_f32 v[74:75], v[8:9], v[86:87]
	global_store_dwordx4 v[78:79], v[62:65], off
	global_store_dwordx4 v[78:79], v[66:69], off offset:16
	global_store_dwordx4 v[78:79], v[70:73], off offset:2048
	global_store_dwordx4 v[78:79], v[74:77], off offset:2064
	s_and_saveexec_b64 s[6:7], s[4:5]
	s_cbranch_execz .LBB0_989
	s_waitcnt vmcnt(9)
	v_fmamk_f32 v61, v61, 0x3a800000, v41
	v_rsq_f32_e32 v63, v61
	s_nop 0
	v_lshlrev_b32_e32 v68, 16, v32
	v_and_b32_e32 v69, 0xffff0000, v32
	v_lshlrev_b32_e32 v70, 16, v33
	v_and_b32_e32 v71, 0xffff0000, v33
	v_lshlrev_b32_e32 v72, 16, v34
	v_and_b32_e32 v73, 0xffff0000, v34
	v_lshlrev_b32_e32 v74, 16, v35
	v_and_b32_e32 v75, 0xffff0000, v35
	v_and_b32_e32 v67, 0xffff0000, v38
	v_mov_b32_e32 v62, v63
	v_lshlrev_b32_e32 v64, 16, v36
	v_and_b32_e32 v65, 0xffff0000, v36
	v_lshlrev_b32_e32 v36, 16, v37
	v_and_b32_e32 v37, 0xffff0000, v37
	v_pk_mul_f32 v[32:33], v[62:63], v[64:65] op_sel_hi:[0,1]
	v_pk_mul_f32 v[34:35], v[62:63], v[36:37] op_sel_hi:[0,1]
	v_lshlrev_b32_e32 v66, 16, v38
	v_lshlrev_b32_e32 v38, 16, v39
	v_and_b32_e32 v39, 0xffff0000, v39
	v_pk_mul_f32 v[34:35], v[6:7], v[34:35]
	v_pk_mul_f32 v[32:33], v[4:5], v[32:33]
	v_lshl_add_u64 v[36:37], v[54:55], 0, v[42:43]
	global_store_dwordx4 v[36:37], v[32:35], off
	s_nop 1
	v_pk_mul_f32 v[32:33], v[62:63], v[66:67] op_sel_hi:[0,1]
	v_pk_mul_f32 v[34:35], v[62:63], v[38:39] op_sel_hi:[0,1]
	v_pk_mul_f32 v[34:35], v[2:3], v[34:35]
	v_pk_mul_f32 v[32:33], v[0:1], v[32:33]
	global_store_dwordx4 v[36:37], v[32:35], off offset:16
	s_nop 1
	v_pk_mul_f32 v[32:33], v[62:63], v[68:69] op_sel_hi:[0,1]
	v_pk_mul_f32 v[34:35], v[62:63], v[70:71] op_sel_hi:[0,1]
	v_pk_mul_f32 v[34:35], v[14:15], v[34:35]
	v_pk_mul_f32 v[32:33], v[12:13], v[32:33]
	global_store_dwordx4 v[36:37], v[32:35], off offset:2048
	s_nop 1
	v_pk_mul_f32 v[32:33], v[62:63], v[72:73] op_sel_hi:[0,1]
	v_pk_mul_f32 v[34:35], v[62:63], v[74:75] op_sel_hi:[0,1]
	v_pk_mul_f32 v[34:35], v[10:11], v[34:35]
	v_pk_mul_f32 v[32:33], v[8:9], v[32:33]
	global_store_dwordx4 v[36:37], v[32:35], off offset:2064
	s_or_b64 exec, exec, s[6:7]
	s_and_saveexec_b64 s[4:5], s[2:3]
	s_cbranch_execnz .LBB0_990
